# v48 with the residual epilogues prefetching one row group ahead (two register sets, counted waits)
# speedup vs baseline: 1.0294x; 1.0001x over previous
; template <class Epi>
; __device__ __forceinline__ void gemm_phase(LAS unsigned char* lds, const Gemm g, const StaticOrder& S, const Epi& E) {
;     ...
;         for (int t = 0; t < nt; t += 2) {
;             const bool last = (t == nt - 2);
;             const char* a1 = cA + (size_t)(t + 1) * kstep;
;             const char* a2 = last ? nA : cA + (size_t)(t + 2) * kstep; const char* b2 = last ? nB : cB + (size_t)(t + 2) * kstep;
;             const char* a3 = a2 + kstep; const char* b3 = b2 + kstep;
;             PG8_LDB(B0, 0, 0); PG8_SCHED; PG8_LDA(At, 0, 0); PG8_STAGE(PG8_SA(1, 1), a1 + hstep, voffA);
;             PG8_WAIT_L(8); PG8_BAR; PG8_WAIT_L(0); PG8_MMA(0, 0, At, B0); PG8_BAR; PG8_SCHED;
;             PG8_LDB(B1, 0, 1); PG8_STAGE(PG8_SB(0, 0), b2, voffB);
;             PG8_BAR; PG8_WAIT_L(0); PG8_MMA(0, 1, At, B1); PG8_BAR;
;             PG8_LDA(At, 0, 1); PG8_STAGE(PG8_SA(0, 0), a2, voffA);
;             PG8_BAR; PG8_WAIT_L(0); PG8_MMA(1, 0, At, B0); PG8_BAR; PG8_SCHED;
;             PG8_STAGE(PG8_SB(0, 1), b2 + hstep, voffB);
;             PG8_WAIT_V(6); PG8_BAR; PG8_MMA(1, 1, At, B1); PG8_BAR;
;             PG8_LDB(B0, 1, 0); PG8_SCHED; PG8_LDA(At, 1, 0); PG8_STAGE(PG8_SA(0, 1), a2 + hstep, voffA);
;             PG8_WAIT_L(8); PG8_BAR; PG8_WAIT_L(0); PG8_MMA(0, 0, At, B0); PG8_BAR; PG8_SCHED;
;             PG8_LDB(B1, 1, 1); PG8_STAGE(PG8_SB(1, 0), b3, voffB);
;             PG8_BAR; PG8_WAIT_L(0); PG8_MMA(0, 1, At, B1); PG8_BAR;
;             PG8_LDA(At, 1, 1); PG8_STAGE(PG8_SA(1, 0), a3, voffA);
;             PG8_BAR; PG8_WAIT_L(0); PG8_MMA(1, 0, At, B0); PG8_BAR; PG8_SCHED;
;             PG8_STAGE(PG8_SB(1, 1), b3 + hstep, voffB);
;             PG8_WAIT_V(6); PG8_BAR; PG8_MMA(1, 1, At, B1); PG8_BAR;
;     DI void operator()(const f32x4 (&acc)[2][2][4][2], const Unit& u, int wr, int wc, int fr, int fq) const {
;         const int row0 = u.pm * 256 + wr * 64 + fr, col0 = u.pn * 256 + wc * 32 + 4 * fq;
; #pragma unroll
;         for (int ai = 0; ai < 2; ++ai)
; #pragma unroll
;             for (int m = 0; m < 4; ++m) {
;                 const int r = row0 + ai * 128 + m * 16;
;                 const float* rp;
;                 if (MODE == 0) rp = x + (size_t)r * 1024;
;                 else rp = h + (size_t)r * 1024;
;                 float sq = 0.f;
; #pragma unroll
;                 for (int bj = 0; bj < 2; ++bj)
; #pragma unroll
.LBB0_770:
	ds_read_b128 v[128:131], v161
	ds_read_b128 v[132:135], v161 offset:1024
	ds_read_b128 v[148:151], v161 offset:2048
	ds_read_b128 v[152:155], v161 offset:3072
	s_add_u32 s26, s24, 0xfff80080
	s_addc_u32 s27, s25, -1
	s_cmp_eq_u32 s47, 28
	s_cselect_b32 s29, s9, s27
	s_cselect_b32 s28, s15, s26
	s_cselect_b32 s27, s13, s46
	s_cselect_b32 s26, s23, s45
	v_lshl_add_u64 v[156:157], s[24:25], 0, v[140:141]
	s_add_i32 m0, s33, 0xc000
	ds_read_b128 v[164:167], v162
	ds_read_b128 v[168:171], v162 offset:1024
	ds_read_b128 v[180:183], v162 offset:2048
	ds_read_b128 v[184:187], v162 offset:3072
	ds_read_b128 v[188:191], v162 offset:4096
	ds_read_b128 v[192:195], v162 offset:5120
	ds_read_b128 v[196:199], v162 offset:6144
	ds_read_b128 v[200:203], v162 offset:7168
	global_load_lds_dwordx4 v[156:157], off
	v_lshl_add_u64 v[156:157], s[24:25], 0, v[142:143]
	s_add_i32 m0, s33, 0xe000
	s_nop 0
	global_load_lds_dwordx4 v[156:157], off
	s_waitcnt lgkmcnt(8)
	s_barrier
	s_waitcnt lgkmcnt(0)
	s_setprio 1
	s_waitcnt lgkmcnt(0)
	v_mfma_f32_16x16x32_bf16 v[124:127], v[128:131], v[164:167], v[124:127]
	v_mfma_f32_16x16x32_bf16 v[120:123], v[148:151], v[164:167], v[120:123]
	v_mfma_f32_16x16x32_bf16 v[108:111], v[128:131], v[180:183], v[108:111]
	v_mfma_f32_16x16x32_bf16 v[104:107], v[148:151], v[180:183], v[104:107]
	v_mfma_f32_16x16x32_bf16 v[92:95], v[128:131], v[188:191], v[92:95]
	v_mfma_f32_16x16x32_bf16 v[88:91], v[148:151], v[188:191], v[88:91]
	v_mfma_f32_16x16x32_bf16 v[76:79], v[128:131], v[196:199], v[76:79]
	v_mfma_f32_16x16x32_bf16 v[72:75], v[148:151], v[196:199], v[72:75]
	v_mfma_f32_16x16x32_bf16 v[124:127], v[132:135], v[168:171], v[124:127]
	v_mfma_f32_16x16x32_bf16 v[120:123], v[152:155], v[168:171], v[120:123]
	v_mfma_f32_16x16x32_bf16 v[108:111], v[132:135], v[184:187], v[108:111]
	v_mfma_f32_16x16x32_bf16 v[104:107], v[152:155], v[184:187], v[104:107]
	v_mfma_f32_16x16x32_bf16 v[92:95], v[132:135], v[192:195], v[92:95]
	v_mfma_f32_16x16x32_bf16 v[88:91], v[152:155], v[192:195], v[88:91]
	v_mfma_f32_16x16x32_bf16 v[76:79], v[132:135], v[200:203], v[76:79]
	v_mfma_f32_16x16x32_bf16 v[72:75], v[152:155], v[200:203], v[72:75]
	s_setprio 0
	s_barrier
	s_add_i32 s48, s43, s3
	v_lshl_add_u64 v[156:157], s[26:27], 0, v[136:137]
	s_mov_b32 m0, s48
	ds_read_b128 v[204:207], v163
	ds_read_b128 v[208:211], v163 offset:1024
	ds_read_b128 v[212:215], v163 offset:2048
	ds_read_b128 v[216:219], v163 offset:3072
	global_load_lds_dwordx4 v[156:157], off
	v_lshl_add_u64 v[172:173], s[26:27], 0, v[138:139]
	s_add_i32 m0, s48, 0x2000
	s_nop 0
	global_load_lds_dwordx4 v[172:173], off
	s_barrier
	s_waitcnt lgkmcnt(0)
	s_setprio 1
	s_waitcnt lgkmcnt(0)
	v_mfma_f32_16x16x32_bf16 v[116:119], v[204:207], v[164:167], v[116:119]
	v_mfma_f32_16x16x32_bf16 v[112:115], v[212:215], v[164:167], v[112:115]
	v_mfma_f32_16x16x32_bf16 v[100:103], v[204:207], v[180:183], v[100:103]
	v_mfma_f32_16x16x32_bf16 v[96:99], v[212:215], v[180:183], v[96:99]
	v_mfma_f32_16x16x32_bf16 v[84:87], v[204:207], v[188:191], v[84:87]
	v_mfma_f32_16x16x32_bf16 v[80:83], v[212:215], v[188:191], v[80:83]
	v_mfma_f32_16x16x32_bf16 v[68:71], v[204:207], v[196:199], v[68:71]
	v_mfma_f32_16x16x32_bf16 v[64:67], v[212:215], v[196:199], v[64:67]
	v_mfma_f32_16x16x32_bf16 v[116:119], v[208:211], v[168:171], v[116:119]
	v_mfma_f32_16x16x32_bf16 v[112:115], v[216:219], v[168:171], v[112:115]
	v_mfma_f32_16x16x32_bf16 v[100:103], v[208:211], v[184:187], v[100:103]
	v_mfma_f32_16x16x32_bf16 v[96:99], v[216:219], v[184:187], v[96:99]
	v_mfma_f32_16x16x32_bf16 v[84:87], v[208:211], v[192:195], v[84:87]
	v_mfma_f32_16x16x32_bf16 v[80:83], v[216:219], v[192:195], v[80:83]
	v_mfma_f32_16x16x32_bf16 v[68:71], v[208:211], v[200:203], v[68:71]
	v_mfma_f32_16x16x32_bf16 v[64:67], v[216:219], v[200:203], v[64:67]
	s_setprio 0
	s_mov_b32 m0, s33
	v_lshl_add_u64 v[176:177], s[28:29], 0, v[136:137]
	s_barrier
	ds_read_b128 v[164:167], v162 offset:16384
	ds_read_b128 v[168:171], v162 offset:17408
	ds_read_b128 v[180:183], v162 offset:18432
	ds_read_b128 v[184:187], v162 offset:19456
	ds_read_b128 v[188:191], v162 offset:20480
	ds_read_b128 v[192:195], v162 offset:21504
	ds_read_b128 v[196:199], v162 offset:22528
	ds_read_b128 v[200:203], v162 offset:23552
	global_load_lds_dwordx4 v[176:177], off
	v_lshl_add_u64 v[220:221], s[28:29], 0, v[138:139]
	s_mov_b32 m0, s34
	s_nop 0
	global_load_lds_dwordx4 v[220:221], off
	s_barrier
	s_waitcnt lgkmcnt(0)
	s_setprio 1
	s_waitcnt lgkmcnt(0)
	v_mfma_f32_16x16x32_bf16 v[60:63], v[128:131], v[164:167], v[60:63]
	v_mfma_f32_16x16x32_bf16 v[56:59], v[148:151], v[164:167], v[56:59]
	v_mfma_f32_16x16x32_bf16 v[44:47], v[128:131], v[180:183], v[44:47]
	v_mfma_f32_16x16x32_bf16 v[40:43], v[148:151], v[180:183], v[40:43]
	v_mfma_f32_16x16x32_bf16 v[28:31], v[128:131], v[188:191], v[28:31]
	v_mfma_f32_16x16x32_bf16 v[24:27], v[148:151], v[188:191], v[24:27]
	v_mfma_f32_16x16x32_bf16 v[12:15], v[128:131], v[196:199], v[12:15]
	v_mfma_f32_16x16x32_bf16 v[8:11], v[148:151], v[196:199], v[8:11]
	v_mfma_f32_16x16x32_bf16 v[60:63], v[132:135], v[168:171], v[60:63]
	v_mfma_f32_16x16x32_bf16 v[56:59], v[152:155], v[168:171], v[56:59]
	v_mfma_f32_16x16x32_bf16 v[44:47], v[132:135], v[184:187], v[44:47]
	v_mfma_f32_16x16x32_bf16 v[40:43], v[152:155], v[184:187], v[40:43]
	v_mfma_f32_16x16x32_bf16 v[28:31], v[132:135], v[192:195], v[28:31]
	v_mfma_f32_16x16x32_bf16 v[24:27], v[152:155], v[192:195], v[24:27]
	v_mfma_f32_16x16x32_bf16 v[12:15], v[132:135], v[200:203], v[12:15]
	v_mfma_f32_16x16x32_bf16 v[8:11], v[152:155], v[200:203], v[8:11]
	s_setprio 0
	s_barrier
; #define PG8_STAGE(bufoff, gbase, voff) do { _Pragma("unroll") for (int _i = 0; _i < 2; ++_i) \
;         __builtin_amdgcn_global_load_lds((const unsigned*)((const char*)(gbase) + (voff)[_i]), (LAS unsigned*)(lds + (bufoff) + ldsw + _i * 8192), 16, 0, 0); } while (0)
; #define PG8_LDA(dst, b, h) do { _Pragma("unroll") for (int m = 0; m < 4; ++m) _Pragma("unroll") for (int k = 0; k < 2; ++k) dst[m][k] = *(const LAS bf16x8*)(lds + PG8_SA(b, h) + aoff + m * 2048 + k * 1024); } while (0)
; #define PG8_WAIT_V(n) asm volatile("s_waitcnt vmcnt(" #n ")" ::: "memory")
; #define PG8_WAIT_L(n) asm volatile("s_waitcnt lgkmcnt(" #n ")" ::: "memory")
; template <class Epi>
; __device__ __forceinline__ void gemm_phase(LAS unsigned char* lds, const Gemm g, const StaticOrder& S, const Epi& E) {
;     ...
;         for (int t = 0; t < nt; t += 2) {
;             const bool last = (t == nt - 2);
;             const char* a1 = cA + (size_t)(t + 1) * kstep;
;             const char* a2 = last ? nA : cA + (size_t)(t + 2) * kstep; const char* b2 = last ? nB : cB + (size_t)(t + 2) * kstep;
;             const char* a3 = a2 + kstep; const char* b3 = b2 + kstep;
;             PG8_LDB(B0, 0, 0); PG8_SCHED; PG8_LDA(At, 0, 0); PG8_STAGE(PG8_SA(1, 1), a1 + hstep, voffA);
;             PG8_WAIT_L(8); PG8_BAR; PG8_WAIT_L(0); PG8_MMA(0, 0, At, B0); PG8_BAR; PG8_SCHED;
;             PG8_LDB(B1, 0, 1); PG8_STAGE(PG8_SB(0, 0), b2, voffB);
;             PG8_BAR; PG8_WAIT_L(0); PG8_MMA(0, 1, At, B1); PG8_BAR;
;             PG8_LDA(At, 0, 1); PG8_STAGE(PG8_SA(0, 0), a2, voffA);
;             PG8_BAR; PG8_WAIT_L(0); PG8_MMA(1, 0, At, B0); PG8_BAR; PG8_SCHED;
;             PG8_STAGE(PG8_SB(0, 1), b2 + hstep, voffB);
;             PG8_WAIT_V(6); PG8_BAR; PG8_MMA(1, 1, At, B1); PG8_BAR;
;             PG8_LDB(B0, 1, 0); PG8_SCHED; PG8_LDA(At, 1, 0); PG8_STAGE(PG8_SA(0, 1), a2 + hstep, voffA);
;             PG8_WAIT_L(8); PG8_BAR; PG8_WAIT_L(0); PG8_MMA(0, 0, At, B0); PG8_BAR; PG8_SCHED;
;             PG8_LDB(B1, 1, 1); PG8_STAGE(PG8_SB(1, 0), b3, voffB);
;             PG8_BAR; PG8_WAIT_L(0); PG8_MMA(0, 1, At, B1); PG8_BAR;
;             PG8_LDA(At, 1, 1); PG8_STAGE(PG8_SA(1, 0), a3, voffA);
;             PG8_BAR; PG8_WAIT_L(0); PG8_MMA(1, 0, At, B0); PG8_BAR; PG8_SCHED;
;             PG8_STAGE(PG8_SB(1, 1), b3 + hstep, voffB);
;             PG8_WAIT_V(6); PG8_BAR; PG8_MMA(1, 1, At, B1); PG8_BAR;
	s_add_u32 s48, s26, 0x80000
	s_addc_u32 s49, s27, 0
	s_add_i32 s50, s44, s3
	v_lshl_add_u64 v[128:129], s[48:49], 0, v[136:137]
	s_mov_b32 m0, s50
	s_nop 0
	global_load_lds_dwordx4 v[128:129], off
	v_lshl_add_u64 v[128:129], s[48:49], 0, v[138:139]
	s_add_i32 m0, s50, 0x2000
	s_nop 0
	global_load_lds_dwordx4 v[128:129], off
	s_waitcnt vmcnt(6)
	s_barrier
	s_setprio 1
	v_mfma_f32_16x16x32_bf16 v[52:55], v[204:207], v[164:167], v[52:55]
	v_mfma_f32_16x16x32_bf16 v[48:51], v[212:215], v[164:167], v[48:51]
	v_mfma_f32_16x16x32_bf16 v[36:39], v[204:207], v[180:183], v[36:39]
	v_mfma_f32_16x16x32_bf16 v[32:35], v[212:215], v[180:183], v[32:35]
	v_mfma_f32_16x16x32_bf16 v[20:23], v[204:207], v[188:191], v[20:23]
	v_mfma_f32_16x16x32_bf16 v[16:19], v[212:215], v[188:191], v[16:19]
	v_mfma_f32_16x16x32_bf16 v[4:7], v[204:207], v[196:199], v[4:7]
	v_mfma_f32_16x16x32_bf16 v[0:3], v[212:215], v[196:199], v[0:3]
	v_mfma_f32_16x16x32_bf16 v[52:55], v[208:211], v[168:171], v[52:55]
	v_mfma_f32_16x16x32_bf16 v[48:51], v[216:219], v[168:171], v[48:51]
	v_mfma_f32_16x16x32_bf16 v[36:39], v[208:211], v[184:187], v[36:39]
	v_mfma_f32_16x16x32_bf16 v[32:35], v[216:219], v[184:187], v[32:35]
	v_mfma_f32_16x16x32_bf16 v[20:23], v[208:211], v[192:195], v[20:23]
	v_mfma_f32_16x16x32_bf16 v[16:19], v[216:219], v[192:195], v[16:19]
	v_mfma_f32_16x16x32_bf16 v[4:7], v[208:211], v[200:203], v[4:7]
	v_mfma_f32_16x16x32_bf16 v[0:3], v[216:219], v[200:203], v[0:3]
	s_setprio 0
	s_add_i32 s48, 0, 0x18000
	v_add_u32_e32 v152, s48, v159
	s_barrier
	ds_read_b128 v[128:131], v152
	ds_read_b128 v[132:135], v152 offset:1024
	ds_read_b128 v[148:151], v152 offset:2048
	ds_read_b128 v[152:155], v152 offset:3072
	s_add_u32 s28, s28, 0x80000
	s_addc_u32 s29, s29, 0
	s_mov_b32 m0, s35
	v_lshl_add_u64 v[204:205], s[28:29], 0, v[136:137]
	ds_read_b128 v[164:167], v162 offset:32768
	ds_read_b128 v[168:171], v162 offset:33792
	ds_read_b128 v[180:183], v162 offset:34816
	ds_read_b128 v[184:187], v162 offset:35840
	ds_read_b128 v[188:191], v162 offset:36864
	ds_read_b128 v[192:195], v162 offset:37888
	ds_read_b128 v[196:199], v162 offset:38912
	ds_read_b128 v[200:203], v162 offset:39936
	global_load_lds_dwordx4 v[204:205], off
	v_lshl_add_u64 v[204:205], s[28:29], 0, v[138:139]
	s_mov_b32 m0, s36
	s_nop 0
	global_load_lds_dwordx4 v[204:205], off
	s_waitcnt lgkmcnt(8)
	s_barrier
	s_waitcnt lgkmcnt(0)
	s_setprio 1
	s_waitcnt lgkmcnt(0)
	v_mfma_f32_16x16x32_bf16 v[124:127], v[128:131], v[164:167], v[124:127]
	v_mfma_f32_16x16x32_bf16 v[120:123], v[148:151], v[164:167], v[120:123]
	v_mfma_f32_16x16x32_bf16 v[108:111], v[128:131], v[180:183], v[108:111]
	v_mfma_f32_16x16x32_bf16 v[104:107], v[148:151], v[180:183], v[104:107]
	v_mfma_f32_16x16x32_bf16 v[92:95], v[128:131], v[188:191], v[92:95]
	v_mfma_f32_16x16x32_bf16 v[88:91], v[148:151], v[188:191], v[88:91]
	v_mfma_f32_16x16x32_bf16 v[76:79], v[128:131], v[196:199], v[76:79]
	v_mfma_f32_16x16x32_bf16 v[72:75], v[148:151], v[196:199], v[72:75]
	v_mfma_f32_16x16x32_bf16 v[124:127], v[132:135], v[168:171], v[124:127]
	v_mfma_f32_16x16x32_bf16 v[120:123], v[152:155], v[168:171], v[120:123]
	v_mfma_f32_16x16x32_bf16 v[108:111], v[132:135], v[184:187], v[108:111]
	v_mfma_f32_16x16x32_bf16 v[104:107], v[152:155], v[184:187], v[104:107]
	v_mfma_f32_16x16x32_bf16 v[92:95], v[132:135], v[192:195], v[92:95]
	v_mfma_f32_16x16x32_bf16 v[88:91], v[152:155], v[192:195], v[88:91]
	v_mfma_f32_16x16x32_bf16 v[76:79], v[132:135], v[200:203], v[76:79]
	v_mfma_f32_16x16x32_bf16 v[72:75], v[152:155], v[200:203], v[72:75]
	s_setprio 0
	s_barrier
	s_add_i32 s28, 0, 0x1c000
	s_add_i32 s29, s48, s3
	v_add_u32_e32 v174, s28, v159
	v_lshl_add_u64 v[156:157], v[156:157], 0, s[0:1]
	s_mov_b32 m0, s29
	ds_read_b128 v[204:207], v174
	ds_read_b128 v[208:211], v174 offset:1024
	ds_read_b128 v[212:215], v174 offset:2048
	ds_read_b128 v[216:219], v174 offset:3072
	global_load_lds_dwordx4 v[156:157], off
	v_lshl_add_u64 v[156:157], v[172:173], 0, s[0:1]
	s_add_i32 m0, s29, 0x2000
	s_nop 0
	global_load_lds_dwordx4 v[156:157], off
	s_barrier
	s_waitcnt lgkmcnt(0)
	s_setprio 1
	s_waitcnt lgkmcnt(0)
	v_mfma_f32_16x16x32_bf16 v[116:119], v[204:207], v[164:167], v[116:119]
	v_mfma_f32_16x16x32_bf16 v[112:115], v[212:215], v[164:167], v[112:115]
	v_mfma_f32_16x16x32_bf16 v[100:103], v[204:207], v[180:183], v[100:103]
	v_mfma_f32_16x16x32_bf16 v[96:99], v[212:215], v[180:183], v[96:99]
	v_mfma_f32_16x16x32_bf16 v[84:87], v[204:207], v[188:191], v[84:87]
	v_mfma_f32_16x16x32_bf16 v[80:83], v[212:215], v[188:191], v[80:83]
	v_mfma_f32_16x16x32_bf16 v[68:71], v[204:207], v[196:199], v[68:71]
	v_mfma_f32_16x16x32_bf16 v[64:67], v[212:215], v[196:199], v[64:67]
	v_mfma_f32_16x16x32_bf16 v[116:119], v[208:211], v[168:171], v[116:119]
	v_mfma_f32_16x16x32_bf16 v[112:115], v[216:219], v[168:171], v[112:115]
	v_mfma_f32_16x16x32_bf16 v[100:103], v[208:211], v[184:187], v[100:103]
	v_mfma_f32_16x16x32_bf16 v[96:99], v[216:219], v[184:187], v[96:99]
	v_mfma_f32_16x16x32_bf16 v[84:87], v[208:211], v[192:195], v[84:87]
	v_mfma_f32_16x16x32_bf16 v[80:83], v[216:219], v[192:195], v[80:83]
	v_mfma_f32_16x16x32_bf16 v[68:71], v[208:211], v[200:203], v[68:71]
	v_mfma_f32_16x16x32_bf16 v[64:67], v[216:219], v[200:203], v[64:67]
	s_setprio 0
	s_mov_b32 m0, s38
	v_lshl_add_u64 v[156:157], v[176:177], 0, s[0:1]
	s_barrier
	ds_read_b128 v[164:167], v162 offset:49152
	ds_read_b128 v[168:171], v162 offset:50176
	ds_read_b128 v[180:183], v162 offset:51200
	ds_read_b128 v[184:187], v162 offset:52224
	ds_read_b128 v[188:191], v162 offset:53248
	ds_read_b128 v[192:195], v162 offset:54272
	ds_read_b128 v[196:199], v162 offset:55296
	ds_read_b128 v[200:203], v162 offset:56320
	global_load_lds_dwordx4 v[156:157], off
	v_lshl_add_u64 v[156:157], v[220:221], 0, s[0:1]
	s_mov_b32 m0, s39
	s_nop 0
	global_load_lds_dwordx4 v[156:157], off
	s_barrier
; DI unsigned pk2(float a, float b) { f32x2 v = {a, b}; hbf2 r = __builtin_convertvector(v, hbf2); return __builtin_bit_cast(unsigned, r); }
; #define PG8_LDA(dst, b, h) do { _Pragma("unroll") for (int m = 0; m < 4; ++m) _Pragma("unroll") for (int k = 0; k < 2; ++k) dst[m][k] = *(const LAS bf16x8*)(lds + PG8_SA(b, h) + aoff + m * 2048 + k * 1024); } while (0)
; template <class Epi>
; __device__ __forceinline__ void gemm_phase(LAS unsigned char* lds, const Gemm g, const StaticOrder& S, const Epi& E) {
;     ...
;             PG8_WAIT_V(6); PG8_BAR; PG8_MMA(1, 1, At, B1); PG8_BAR;
;             PG8_LDB(B0, 1, 0); PG8_SCHED; PG8_LDA(At, 1, 0); PG8_STAGE(PG8_SA(0, 1), a2 + hstep, voffA);
;             PG8_WAIT_L(8); PG8_BAR; PG8_WAIT_L(0); PG8_MMA(0, 0, At, B0); PG8_BAR; PG8_SCHED;
;             PG8_LDB(B1, 1, 1); PG8_STAGE(PG8_SB(1, 0), b3, voffB);
;             PG8_BAR; PG8_WAIT_L(0); PG8_MMA(0, 1, At, B1); PG8_BAR;
;             PG8_LDA(At, 1, 1); PG8_STAGE(PG8_SA(1, 0), a3, voffA);
;             PG8_BAR; PG8_WAIT_L(0); PG8_MMA(1, 0, At, B0); PG8_BAR; PG8_SCHED;
;             PG8_STAGE(PG8_SB(1, 1), b3 + hstep, voffB);
;             PG8_WAIT_V(6); PG8_BAR; PG8_MMA(1, 1, At, B1); PG8_BAR;
;     DI void operator()(const f32x4 (&acc)[2][2][4][2], const Unit& u, int wr, int wc, int fr, int fq) const {
;         const int row0 = u.pm * 256 + wr * 64 + fr, col0 = u.pn * 256 + wc * 32 + 4 * fq;
; #pragma unroll
;         for (int ai = 0; ai < 2; ++ai)
; #pragma unroll
;             for (int m = 0; m < 4; ++m) {
;                 const int r = row0 + ai * 128 + m * 16;
;                 const float* rp;
;                 if (MODE == 0) rp = x + (size_t)r * 1024;
;                 else rp = h + (size_t)r * 1024;
;                 float sq = 0.f;
; #pragma unroll
;                 for (int bj = 0; bj < 2; ++bj)
; #pragma unroll
;                     for (int n = 0; n < 2; ++n) {
;                         const int c = col0 + bj * 128 + n * 16;
;                         f32x4 rv = rp ? *(const f32x4*)(rp + c) : (f32x4){0.f, 0.f, 0.f, 0.f};
;                         f32x4 v = acc[ai][bj][m][n] + rv;
;                         *(f32x4*)(h + (size_t)r * 1024 + c) = v;
;                         if (WRITE_HB) {
;                             u32x2 w; w.x = pk2(v[0], v[1]); w.y = pk2(v[2], v[3]);
;                             *(u32x2*)(hb + (size_t)r * 1024 + c) = w;
	s_waitcnt lgkmcnt(0)
	s_setprio 1
	s_waitcnt lgkmcnt(0)
	v_mfma_f32_16x16x32_bf16 v[60:63], v[128:131], v[164:167], v[60:63]
	v_mfma_f32_16x16x32_bf16 v[56:59], v[148:151], v[164:167], v[56:59]
	v_mfma_f32_16x16x32_bf16 v[44:47], v[128:131], v[180:183], v[44:47]
	v_mfma_f32_16x16x32_bf16 v[40:43], v[148:151], v[180:183], v[40:43]
	v_mfma_f32_16x16x32_bf16 v[28:31], v[128:131], v[188:191], v[28:31]
	v_mfma_f32_16x16x32_bf16 v[24:27], v[148:151], v[188:191], v[24:27]
	v_mfma_f32_16x16x32_bf16 v[12:15], v[128:131], v[196:199], v[12:15]
	v_mfma_f32_16x16x32_bf16 v[8:11], v[148:151], v[196:199], v[8:11]
	v_mfma_f32_16x16x32_bf16 v[60:63], v[132:135], v[168:171], v[60:63]
	v_mfma_f32_16x16x32_bf16 v[56:59], v[152:155], v[168:171], v[56:59]
	v_mfma_f32_16x16x32_bf16 v[44:47], v[132:135], v[184:187], v[44:47]
	v_mfma_f32_16x16x32_bf16 v[40:43], v[152:155], v[184:187], v[40:43]
	v_mfma_f32_16x16x32_bf16 v[28:31], v[132:135], v[192:195], v[28:31]
	v_mfma_f32_16x16x32_bf16 v[24:27], v[152:155], v[192:195], v[24:27]
	v_mfma_f32_16x16x32_bf16 v[12:15], v[132:135], v[200:203], v[12:15]
	v_mfma_f32_16x16x32_bf16 v[8:11], v[152:155], v[200:203], v[8:11]
	s_setprio 0
	s_barrier
	s_add_u32 s26, s26, 0x80080
	s_addc_u32 s27, s27, 0
	s_add_i32 s28, s28, s3
	v_lshl_add_u64 v[128:129], s[26:27], 0, v[136:137]
	s_mov_b32 m0, s28
	s_nop 0
	global_load_lds_dwordx4 v[128:129], off
	v_lshl_add_u64 v[128:129], s[26:27], 0, v[138:139]
	s_add_i32 m0, s28, 0x2000
	s_nop 0
	global_load_lds_dwordx4 v[128:129], off
	s_waitcnt vmcnt(6)
	s_barrier
	s_setprio 1
	v_mfma_f32_16x16x32_bf16 v[52:55], v[204:207], v[164:167], v[52:55]
	v_mfma_f32_16x16x32_bf16 v[48:51], v[212:215], v[164:167], v[48:51]
	v_mfma_f32_16x16x32_bf16 v[36:39], v[204:207], v[180:183], v[36:39]
	v_mfma_f32_16x16x32_bf16 v[32:35], v[212:215], v[180:183], v[32:35]
	v_mfma_f32_16x16x32_bf16 v[20:23], v[204:207], v[188:191], v[20:23]
	v_mfma_f32_16x16x32_bf16 v[16:19], v[212:215], v[188:191], v[16:19]
	v_mfma_f32_16x16x32_bf16 v[4:7], v[204:207], v[196:199], v[4:7]
	v_mfma_f32_16x16x32_bf16 v[0:3], v[212:215], v[196:199], v[0:3]
	v_mfma_f32_16x16x32_bf16 v[52:55], v[208:211], v[168:171], v[52:55]
	v_mfma_f32_16x16x32_bf16 v[48:51], v[216:219], v[168:171], v[48:51]
	v_mfma_f32_16x16x32_bf16 v[36:39], v[208:211], v[184:187], v[36:39]
	v_mfma_f32_16x16x32_bf16 v[32:35], v[216:219], v[184:187], v[32:35]
	v_mfma_f32_16x16x32_bf16 v[20:23], v[208:211], v[192:195], v[20:23]
	v_mfma_f32_16x16x32_bf16 v[16:19], v[216:219], v[192:195], v[16:19]
	v_mfma_f32_16x16x32_bf16 v[4:7], v[208:211], v[200:203], v[4:7]
	v_mfma_f32_16x16x32_bf16 v[0:3], v[216:219], v[200:203], v[0:3]
	s_setprio 0
	s_add_i32 s47, s47, 2
	s_add_u32 s24, s24, 0x100
	s_addc_u32 s25, s25, 0
	s_add_u32 s45, s45, 0x100
	s_addc_u32 s46, s46, 0
	s_cmp_gt_u32 s47, 29
	s_barrier
	s_cbranch_scc0 .LBB0_770
	v_lshl_add_u32 v150, s8, 8, v158
	v_ashrrev_i32_e32 v151, 31, v150
	v_lshl_or_b32 v148, s22, 8, v160
	v_lshlrev_b64 v[128:129], 12, v[150:151]
	v_lshl_add_u64 v[130:131], s[56:57], 0, v[128:129]
	v_ashrrev_i32_e32 v149, 31, v148
	v_cndmask_b32_e64 v129, 0, 1, s[10:11]
	v_mov_b32_e32 v128, 0
	v_cmp_ne_u32_e64 s[8:9], 1, v129
	s_andn2_b64 vcc, exec, s[10:11]
	v_lshl_add_u64 v[156:157], v[148:149], 2, v[130:131]
	v_mov_b32_e32 v130, 0
	v_mov_b32_e32 v131, 0
	v_mov_b32_e32 v132, 0
	v_mov_b32_e32 v133, 0
	s_cbranch_vccnz .LBB0_773
	s_mov_b64 s[98:99], 0x10000
	s_mov_b64 s[100:101], 0x80000
	v_mov_b64_e32 v[196:197], v[156:157]
	v_lshl_add_u64 v[200:201], v[156:157], 0, s[100:101]
	v_lshl_add_u64 v[198:199], v[156:157], 0, s[98:99]
	global_load_dwordx4 v[180:183], v[156:157], off
	global_load_dwordx4 v[184:187], v[156:157], off offset:64
	global_load_dwordx4 v[188:191], v[156:157], off offset:512
	global_load_dwordx4 v[192:195], v[156:157], off offset:576
	global_load_dwordx4 v[212:215], v[198:199], off
	global_load_dwordx4 v[216:219], v[198:199], off offset:64
	global_load_dwordx4 v[220:223], v[198:199], off offset:512
	global_load_dwordx4 v[224:227], v[198:199], off offset:576
.LBB0_773:
	v_lshlrev_b64 v[134:135], 10, v[150:151]
	s_waitcnt vmcnt(7)
	v_pk_add_f32 v[126:127], v[126:127], v[182:183]
	v_pk_add_f32 v[124:125], v[124:125], v[180:181]
	v_lshl_add_u64 v[130:131], v[134:135], 2, s[66:67]
	v_lshl_add_u64 v[132:133], v[134:135], 1, s[68:69]
	v_lshl_add_u64 v[152:153], v[148:149], 2, v[130:131]
	v_cvt_pk_bf16_f32 v130, v124, v125
	v_cvt_pk_bf16_f32 v131, v126, v127
	v_lshl_add_u64 v[154:155], v[148:149], 1, v[132:133]
	global_store_dwordx4 v[152:153], v[124:127], off
	global_store_dwordx2 v[154:155], v[130:131], off
	s_and_b64 vcc, exec, s[8:9]
	v_mov_b32_e32 v129, 0
	v_mov_b32_e32 v130, 0
	v_mov_b32_e32 v131, 0
	s_cbranch_vccnz .LBB0_775
	s_nop 0
.LBB0_775:
	s_waitcnt vmcnt(8)
	v_pk_add_f32 v[130:131], v[122:123], v[186:187]
	v_pk_add_f32 v[128:129], v[120:121], v[184:185]
	v_cvt_pk_bf16_f32 v121, v130, v131
	v_cvt_pk_bf16_f32 v120, v128, v129
	global_store_dwordx4 v[152:153], v[128:131], off offset:64
	global_store_dwordx2 v[154:155], v[120:121], off offset:32
	v_mov_b32_e32 v120, 0
	s_and_b64 vcc, exec, s[8:9]
	v_mov_b32_e32 v132, 0
	v_mov_b32_e32 v133, 0
	v_mov_b32_e32 v134, 0
	v_mov_b32_e32 v135, 0
	s_cbranch_vccnz .LBB0_777
	s_nop 0
.LBB0_777:
	s_waitcnt vmcnt(9)
	v_pk_add_f32 v[118:119], v[118:119], v[190:191]
	v_pk_add_f32 v[116:117], v[116:117], v[188:189]
	v_cvt_pk_bf16_f32 v123, v118, v119
	v_cvt_pk_bf16_f32 v122, v116, v117
	global_store_dwordx4 v[152:153], v[116:119], off offset:512
	global_store_dwordx2 v[154:155], v[122:123], off offset:256
	s_and_b64 vcc, exec, s[8:9]
	v_mov_b32_e32 v121, 0
	v_mov_b32_e32 v122, 0
	v_mov_b32_e32 v123, 0
	s_cbranch_vccnz .LBB0_779
	s_nop 0
; DI unsigned pk2(float a, float b) { f32x2 v = {a, b}; hbf2 r = __builtin_convertvector(v, hbf2); return __builtin_bit_cast(unsigned, r); }
; DI float sum_x16_x32(float x) { return sum_x32(sum_x16(x)); }
;     DI void operator()(const f32x4 (&acc)[2][2][4][2], const Unit& u, int wr, int wc, int fr, int fq) const {
;         const int row0 = u.pm * 256 + wr * 64 + fr, col0 = u.pn * 256 + wc * 32 + 4 * fq;
; #pragma unroll
;         for (int ai = 0; ai < 2; ++ai)
; #pragma unroll
;             for (int m = 0; m < 4; ++m) {
;                 const int r = row0 + ai * 128 + m * 16;
;                 const float* rp;
;                 if (MODE == 0) rp = x + (size_t)r * 1024;
;                 else rp = h + (size_t)r * 1024;
;                 float sq = 0.f;
; #pragma unroll
;                 for (int bj = 0; bj < 2; ++bj)
; #pragma unroll
;                     for (int n = 0; n < 2; ++n) {
;                         const int c = col0 + bj * 128 + n * 16;
;                         f32x4 rv = rp ? *(const f32x4*)(rp + c) : (f32x4){0.f, 0.f, 0.f, 0.f};
;                         f32x4 v = acc[ai][bj][m][n] + rv;
;                         *(f32x4*)(h + (size_t)r * 1024 + c) = v;
;                         if (WRITE_HB) {
;                             u32x2 w; w.x = pk2(v[0], v[1]); w.y = pk2(v[2], v[3]);
;                             *(u32x2*)(hb + (size_t)r * 1024 + c) = w;
;                         }
;                         sq += v[0] * v[0] + v[1] * v[1] + v[2] * v[2] + v[3] * v[3];
;                     }
;                 sq = sum_x16_x32(sq);
;                 if (fq == 0) atomicAdd(ss + r, sq);
.LBB0_779:
	v_mul_f32_e32 v125, v125, v125
	v_fmac_f32_e32 v125, v124, v124
	v_mul_f32_e32 v124, v129, v129
	v_fmac_f32_e32 v124, v128, v128
	v_mul_f32_e32 v117, v117, v117
	s_waitcnt vmcnt(10)
	v_pk_add_f32 v[114:115], v[114:115], v[194:195]
	v_pk_add_f32 v[112:113], v[112:113], v[192:193]
	v_fmac_f32_e32 v125, v126, v126
	v_fmac_f32_e32 v124, v130, v130
	v_fmac_f32_e32 v117, v116, v116
	global_store_dwordx4 v[152:153], v[112:115], off offset:576
	v_cvt_pk_bf16_f32 v116, v112, v113
	v_fmac_f32_e32 v125, v127, v127
	v_mul_f32_e32 v113, v113, v113
	v_fmac_f32_e32 v124, v131, v131
	v_fmac_f32_e32 v117, v118, v118
	v_fmac_f32_e32 v113, v112, v112
	v_add_f32_e32 v124, v125, v124
	v_fmac_f32_e32 v117, v119, v119
	v_fmac_f32_e32 v113, v114, v114
	v_add_f32_e32 v118, v124, v117
	v_fmac_f32_e32 v113, v115, v115
	v_add_f32_e32 v112, v118, v113
	v_mov_b32_e32 v113, v112
	s_nop 1
	v_permlane16_swap_b32_e32 v112, v113
	v_add_f32_e32 v112, v112, v113
	v_mov_b32_e32 v113, v112
	v_cvt_pk_bf16_f32 v117, v114, v115
	s_nop 0
	v_permlane32_swap_b32_e32 v112, v113
	global_store_dwordx2 v[154:155], v[116:117], off offset:288
	s_and_saveexec_b64 s[22:23], s[4:5]
	s_cbranch_execz .LBB0_781
	v_lshl_add_u64 v[114:115], v[150:151], 2, s[94:95]
	v_add_f32_e32 v112, v112, v113
	global_atomic_add_f32 v[114:115], v112, off
.LBB0_781:
	s_or_b64 exec, exec, s[22:23]
	v_or_b32_e32 v120, 16, v150
	v_ashrrev_i32_e32 v121, 31, v120
	v_lshlrev_b64 v[112:113], 12, v[120:121]
	v_lshl_add_u64 v[114:115], s[56:57], 0, v[112:113]
	v_mov_b32_e32 v112, 0
	s_and_b64 vcc, exec, s[8:9]
	v_lshl_add_u64 v[126:127], v[148:149], 2, v[114:115]
	v_mov_b32_e32 v114, 0
	v_mov_b32_e32 v115, 0
	v_mov_b32_e32 v116, 0
	v_mov_b32_e32 v117, 0
	s_cbranch_vccnz .LBB0_783
	v_lshl_add_u64 v[198:199], v[198:199], 0, s[98:99]
	global_load_dwordx4 v[180:183], v[198:199], off
	global_load_dwordx4 v[184:187], v[198:199], off offset:64
	global_load_dwordx4 v[188:191], v[198:199], off offset:512
	global_load_dwordx4 v[192:195], v[198:199], off offset:576
.LBB0_783:
	v_lshlrev_b64 v[118:119], 10, v[120:121]
	s_waitcnt vmcnt(15)
	v_pk_add_f32 v[110:111], v[110:111], v[214:215]
	v_pk_add_f32 v[108:109], v[108:109], v[212:213]
	v_lshl_add_u64 v[114:115], v[118:119], 2, s[66:67]
	v_lshl_add_u64 v[116:117], v[118:119], 1, s[68:69]
	v_lshl_add_u64 v[122:123], v[148:149], 2, v[114:115]
	v_cvt_pk_bf16_f32 v114, v108, v109
	v_cvt_pk_bf16_f32 v115, v110, v111
	v_lshl_add_u64 v[124:125], v[148:149], 1, v[116:117]
	global_store_dwordx4 v[122:123], v[108:111], off
	global_store_dwordx2 v[124:125], v[114:115], off
	s_and_b64 vcc, exec, s[8:9]
	v_mov_b32_e32 v113, 0
	v_mov_b32_e32 v114, 0
	v_mov_b32_e32 v115, 0
	s_cbranch_vccnz .LBB0_785
	s_nop 0
.LBB0_785:
	s_waitcnt vmcnt(16)
	v_pk_add_f32 v[114:115], v[106:107], v[218:219]
	v_pk_add_f32 v[112:113], v[104:105], v[216:217]
	v_cvt_pk_bf16_f32 v105, v114, v115
	v_cvt_pk_bf16_f32 v104, v112, v113
	global_store_dwordx4 v[122:123], v[112:115], off offset:64
	global_store_dwordx2 v[124:125], v[104:105], off offset:32
	v_mov_b32_e32 v104, 0
	s_and_b64 vcc, exec, s[8:9]
	v_mov_b32_e32 v116, 0
	v_mov_b32_e32 v117, 0
	v_mov_b32_e32 v118, 0
	v_mov_b32_e32 v119, 0
	s_cbranch_vccnz .LBB0_787
	s_nop 0
.LBB0_787:
	s_waitcnt vmcnt(17)
	v_pk_add_f32 v[102:103], v[102:103], v[222:223]
	v_pk_add_f32 v[100:101], v[100:101], v[220:221]
	v_cvt_pk_bf16_f32 v107, v102, v103
	v_cvt_pk_bf16_f32 v106, v100, v101
	global_store_dwordx4 v[122:123], v[100:103], off offset:512
	global_store_dwordx2 v[124:125], v[106:107], off offset:256
	s_and_b64 vcc, exec, s[8:9]
	v_mov_b32_e32 v105, 0
	v_mov_b32_e32 v106, 0
	v_mov_b32_e32 v107, 0
	s_cbranch_vccnz .LBB0_789
	s_nop 0
.LBB0_789:
	v_mul_f32_e32 v109, v109, v109
	v_fmac_f32_e32 v109, v108, v108
	v_mul_f32_e32 v108, v113, v113
	v_fmac_f32_e32 v108, v112, v112
	v_mul_f32_e32 v101, v101, v101
	s_waitcnt vmcnt(18)
	v_pk_add_f32 v[98:99], v[98:99], v[226:227]
	v_pk_add_f32 v[96:97], v[96:97], v[224:225]
	v_fmac_f32_e32 v109, v110, v110
	v_fmac_f32_e32 v108, v114, v114
	v_fmac_f32_e32 v101, v100, v100
	global_store_dwordx4 v[122:123], v[96:99], off offset:576
	v_cvt_pk_bf16_f32 v100, v96, v97
	v_fmac_f32_e32 v109, v111, v111
	v_mul_f32_e32 v97, v97, v97
	v_fmac_f32_e32 v108, v115, v115
	v_fmac_f32_e32 v101, v102, v102
	v_fmac_f32_e32 v97, v96, v96
	v_add_f32_e32 v108, v109, v108
	v_fmac_f32_e32 v101, v103, v103
	v_fmac_f32_e32 v97, v98, v98
	v_add_f32_e32 v102, v108, v101
	v_fmac_f32_e32 v97, v99, v99
	v_add_f32_e32 v96, v102, v97
	v_mov_b32_e32 v97, v96
	s_nop 1
	v_permlane16_swap_b32_e32 v96, v97
	v_add_f32_e32 v96, v96, v97
	v_mov_b32_e32 v97, v96
	v_cvt_pk_bf16_f32 v101, v98, v99
	s_nop 0
	v_permlane32_swap_b32_e32 v96, v97
	global_store_dwordx2 v[124:125], v[100:101], off offset:288
	s_and_saveexec_b64 s[22:23], s[4:5]
	s_cbranch_execz .LBB0_791
	v_lshl_add_u64 v[98:99], v[120:121], 2, s[94:95]
	v_add_f32_e32 v96, v96, v97
	global_atomic_add_f32 v[98:99], v96, off
.LBB0_791:
	s_or_b64 exec, exec, s[22:23]
	v_or_b32_e32 v104, 32, v150
	v_ashrrev_i32_e32 v105, 31, v104
	v_lshlrev_b64 v[96:97], 12, v[104:105]
	v_lshl_add_u64 v[98:99], s[56:57], 0, v[96:97]
	v_mov_b32_e32 v96, 0
	s_and_b64 vcc, exec, s[8:9]
	v_lshl_add_u64 v[110:111], v[148:149], 2, v[98:99]
	v_mov_b32_e32 v98, 0
	v_mov_b32_e32 v99, 0
	v_mov_b32_e32 v100, 0
	v_mov_b32_e32 v101, 0
	s_cbranch_vccnz .LBB0_793
	v_lshl_add_u64 v[198:199], v[198:199], 0, s[98:99]
	global_load_dwordx4 v[212:215], v[198:199], off
	global_load_dwordx4 v[216:219], v[198:199], off offset:64
	global_load_dwordx4 v[220:223], v[198:199], off offset:512
	global_load_dwordx4 v[224:227], v[198:199], off offset:576
; DI unsigned pk2(float a, float b) { f32x2 v = {a, b}; hbf2 r = __builtin_convertvector(v, hbf2); return __builtin_bit_cast(unsigned, r); }
; DI float sum_x16_x32(float x) { return sum_x32(sum_x16(x)); }
;     DI void operator()(const f32x4 (&acc)[2][2][4][2], const Unit& u, int wr, int wc, int fr, int fq) const {
;         const int row0 = u.pm * 256 + wr * 64 + fr, col0 = u.pn * 256 + wc * 32 + 4 * fq;
; #pragma unroll
;         for (int ai = 0; ai < 2; ++ai)
; #pragma unroll
;             for (int m = 0; m < 4; ++m) {
;                 const int r = row0 + ai * 128 + m * 16;
;                 const float* rp;
;                 if (MODE == 0) rp = x + (size_t)r * 1024;
;                 else rp = h + (size_t)r * 1024;
;                 float sq = 0.f;
; #pragma unroll
;                 for (int bj = 0; bj < 2; ++bj)
; #pragma unroll
;                     for (int n = 0; n < 2; ++n) {
;                         const int c = col0 + bj * 128 + n * 16;
;                         f32x4 rv = rp ? *(const f32x4*)(rp + c) : (f32x4){0.f, 0.f, 0.f, 0.f};
;                         f32x4 v = acc[ai][bj][m][n] + rv;
;                         *(f32x4*)(h + (size_t)r * 1024 + c) = v;
;                         if (WRITE_HB) {
;                             u32x2 w; w.x = pk2(v[0], v[1]); w.y = pk2(v[2], v[3]);
;                             *(u32x2*)(hb + (size_t)r * 1024 + c) = w;
;                         }
;                         sq += v[0] * v[0] + v[1] * v[1] + v[2] * v[2] + v[3] * v[3];
;                     }
;                 sq = sum_x16_x32(sq);
;                 if (fq == 0) atomicAdd(ss + r, sq);
.LBB0_793:
	v_lshlrev_b64 v[102:103], 10, v[104:105]
	s_waitcnt vmcnt(15)
	v_pk_add_f32 v[94:95], v[94:95], v[182:183]
	v_pk_add_f32 v[92:93], v[92:93], v[180:181]
	v_lshl_add_u64 v[98:99], v[102:103], 2, s[66:67]
	v_lshl_add_u64 v[100:101], v[102:103], 1, s[68:69]
	v_lshl_add_u64 v[106:107], v[148:149], 2, v[98:99]
	v_cvt_pk_bf16_f32 v98, v92, v93
	v_cvt_pk_bf16_f32 v99, v94, v95
	v_lshl_add_u64 v[108:109], v[148:149], 1, v[100:101]
	global_store_dwordx4 v[106:107], v[92:95], off
	global_store_dwordx2 v[108:109], v[98:99], off
	s_and_b64 vcc, exec, s[8:9]
	v_mov_b32_e32 v97, 0
	v_mov_b32_e32 v98, 0
	v_mov_b32_e32 v99, 0
	s_cbranch_vccnz .LBB0_795
	s_nop 0
.LBB0_795:
	s_waitcnt vmcnt(16)
	v_pk_add_f32 v[98:99], v[90:91], v[186:187]
	v_pk_add_f32 v[96:97], v[88:89], v[184:185]
	v_cvt_pk_bf16_f32 v89, v98, v99
	v_cvt_pk_bf16_f32 v88, v96, v97
	global_store_dwordx4 v[106:107], v[96:99], off offset:64
	global_store_dwordx2 v[108:109], v[88:89], off offset:32
	v_mov_b32_e32 v88, 0
	s_and_b64 vcc, exec, s[8:9]
	v_mov_b32_e32 v100, 0
	v_mov_b32_e32 v101, 0
	v_mov_b32_e32 v102, 0
	v_mov_b32_e32 v103, 0
	s_cbranch_vccnz .LBB0_797
	s_nop 0
.LBB0_797:
	s_waitcnt vmcnt(17)
	v_pk_add_f32 v[86:87], v[86:87], v[190:191]
	v_pk_add_f32 v[84:85], v[84:85], v[188:189]
	v_cvt_pk_bf16_f32 v91, v86, v87
	v_cvt_pk_bf16_f32 v90, v84, v85
	global_store_dwordx4 v[106:107], v[84:87], off offset:512
	global_store_dwordx2 v[108:109], v[90:91], off offset:256
	s_and_b64 vcc, exec, s[8:9]
	v_mov_b32_e32 v89, 0
	v_mov_b32_e32 v90, 0
	v_mov_b32_e32 v91, 0
	s_cbranch_vccnz .LBB0_799
	s_nop 0
.LBB0_799:
	v_mul_f32_e32 v93, v93, v93
	v_fmac_f32_e32 v93, v92, v92
	v_mul_f32_e32 v92, v97, v97
	v_fmac_f32_e32 v92, v96, v96
	v_mul_f32_e32 v85, v85, v85
	s_waitcnt vmcnt(18)
	v_pk_add_f32 v[82:83], v[82:83], v[194:195]
	v_pk_add_f32 v[80:81], v[80:81], v[192:193]
	v_fmac_f32_e32 v93, v94, v94
	v_fmac_f32_e32 v92, v98, v98
	v_fmac_f32_e32 v85, v84, v84
	global_store_dwordx4 v[106:107], v[80:83], off offset:576
	v_cvt_pk_bf16_f32 v84, v80, v81
	v_fmac_f32_e32 v93, v95, v95
	v_mul_f32_e32 v81, v81, v81
	v_fmac_f32_e32 v92, v99, v99
	v_fmac_f32_e32 v85, v86, v86
	v_fmac_f32_e32 v81, v80, v80
	v_add_f32_e32 v92, v93, v92
	v_fmac_f32_e32 v85, v87, v87
	v_fmac_f32_e32 v81, v82, v82
	v_add_f32_e32 v86, v92, v85
	v_fmac_f32_e32 v81, v83, v83
	v_add_f32_e32 v80, v86, v81
	v_mov_b32_e32 v81, v80
	s_nop 1
	v_permlane16_swap_b32_e32 v80, v81
	v_add_f32_e32 v80, v80, v81
	v_mov_b32_e32 v81, v80
	v_cvt_pk_bf16_f32 v85, v82, v83
	s_nop 0
	v_permlane32_swap_b32_e32 v80, v81
	global_store_dwordx2 v[108:109], v[84:85], off offset:288
	s_and_saveexec_b64 s[22:23], s[4:5]
	s_cbranch_execz .LBB0_801
	v_lshl_add_u64 v[82:83], v[104:105], 2, s[94:95]
	v_add_f32_e32 v80, v80, v81
	global_atomic_add_f32 v[82:83], v80, off
.LBB0_801:
	s_or_b64 exec, exec, s[22:23]
	v_or_b32_e32 v88, 48, v150
	v_ashrrev_i32_e32 v89, 31, v88
	v_lshlrev_b64 v[80:81], 12, v[88:89]
	v_lshl_add_u64 v[82:83], s[56:57], 0, v[80:81]
	v_mov_b32_e32 v80, 0
	s_and_b64 vcc, exec, s[8:9]
	v_lshl_add_u64 v[94:95], v[148:149], 2, v[82:83]
	v_mov_b32_e32 v82, 0
	v_mov_b32_e32 v83, 0
	v_mov_b32_e32 v84, 0
	v_mov_b32_e32 v85, 0
	s_cbranch_vccnz .LBB0_803
	v_mov_b64_e32 v[198:199], v[200:201]
	global_load_dwordx4 v[180:183], v[198:199], off
	global_load_dwordx4 v[184:187], v[198:199], off offset:64
	global_load_dwordx4 v[188:191], v[198:199], off offset:512
	global_load_dwordx4 v[192:195], v[198:199], off offset:576
.LBB0_803:
	v_lshlrev_b64 v[86:87], 10, v[88:89]
	s_waitcnt vmcnt(15)
	v_pk_add_f32 v[78:79], v[78:79], v[214:215]
	v_pk_add_f32 v[76:77], v[76:77], v[212:213]
	v_lshl_add_u64 v[82:83], v[86:87], 2, s[66:67]
	v_lshl_add_u64 v[84:85], v[86:87], 1, s[68:69]
	v_lshl_add_u64 v[90:91], v[148:149], 2, v[82:83]
	v_cvt_pk_bf16_f32 v82, v76, v77
	v_cvt_pk_bf16_f32 v83, v78, v79
	v_lshl_add_u64 v[92:93], v[148:149], 1, v[84:85]
	global_store_dwordx4 v[90:91], v[76:79], off
	global_store_dwordx2 v[92:93], v[82:83], off
	s_and_b64 vcc, exec, s[8:9]
	v_mov_b32_e32 v81, 0
	v_mov_b32_e32 v82, 0
	v_mov_b32_e32 v83, 0
	s_cbranch_vccnz .LBB0_805
	s_nop 0
.LBB0_805:
	s_waitcnt vmcnt(16)
	v_pk_add_f32 v[82:83], v[74:75], v[218:219]
	v_pk_add_f32 v[80:81], v[72:73], v[216:217]
	v_cvt_pk_bf16_f32 v73, v82, v83
	v_cvt_pk_bf16_f32 v72, v80, v81
	global_store_dwordx4 v[90:91], v[80:83], off offset:64
	global_store_dwordx2 v[92:93], v[72:73], off offset:32
	v_mov_b32_e32 v72, 0
	s_and_b64 vcc, exec, s[8:9]
	v_mov_b32_e32 v84, 0
	v_mov_b32_e32 v85, 0
	v_mov_b32_e32 v86, 0
	v_mov_b32_e32 v87, 0
	s_cbranch_vccnz .LBB0_807
	s_nop 0
.LBB0_807:
	s_waitcnt vmcnt(17)
	v_pk_add_f32 v[70:71], v[70:71], v[222:223]
	v_pk_add_f32 v[68:69], v[68:69], v[220:221]
	v_cvt_pk_bf16_f32 v75, v70, v71
	v_cvt_pk_bf16_f32 v74, v68, v69
	global_store_dwordx4 v[90:91], v[68:71], off offset:512
	global_store_dwordx2 v[92:93], v[74:75], off offset:256
	s_and_b64 vcc, exec, s[8:9]
	v_mov_b32_e32 v73, 0
	v_mov_b32_e32 v74, 0
	v_mov_b32_e32 v75, 0
	s_cbranch_vccnz .LBB0_809
	s_nop 0
.LBB0_809:
	v_mul_f32_e32 v77, v77, v77
	v_fmac_f32_e32 v77, v76, v76
	v_mul_f32_e32 v76, v81, v81
	v_fmac_f32_e32 v76, v80, v80
	v_mul_f32_e32 v69, v69, v69
	s_waitcnt vmcnt(18)
	v_pk_add_f32 v[66:67], v[66:67], v[226:227]
	v_pk_add_f32 v[64:65], v[64:65], v[224:225]
	v_fmac_f32_e32 v77, v78, v78
	v_fmac_f32_e32 v76, v82, v82
	v_fmac_f32_e32 v69, v68, v68
	global_store_dwordx4 v[90:91], v[64:67], off offset:576
	v_cvt_pk_bf16_f32 v68, v64, v65
	v_fmac_f32_e32 v77, v79, v79
	v_mul_f32_e32 v65, v65, v65
	v_fmac_f32_e32 v76, v83, v83
	v_fmac_f32_e32 v69, v70, v70
	v_fmac_f32_e32 v65, v64, v64
	v_add_f32_e32 v76, v77, v76
	v_fmac_f32_e32 v69, v71, v71
	v_fmac_f32_e32 v65, v66, v66
	v_add_f32_e32 v70, v76, v69
	v_fmac_f32_e32 v65, v67, v67
	v_add_f32_e32 v64, v70, v65
	v_mov_b32_e32 v65, v64
	s_nop 1
	v_permlane16_swap_b32_e32 v64, v65
	v_add_f32_e32 v64, v64, v65
	v_mov_b32_e32 v65, v64
	v_cvt_pk_bf16_f32 v69, v66, v67
	s_nop 0
	v_permlane32_swap_b32_e32 v64, v65
	global_store_dwordx2 v[92:93], v[68:69], off offset:288
	s_and_saveexec_b64 s[22:23], s[4:5]
	s_cbranch_execz .LBB0_811
	v_lshl_add_u64 v[66:67], v[88:89], 2, s[94:95]
	v_add_f32_e32 v64, v64, v65
	global_atomic_add_f32 v[66:67], v64, off
; DI unsigned pk2(float a, float b) { f32x2 v = {a, b}; hbf2 r = __builtin_convertvector(v, hbf2); return __builtin_bit_cast(unsigned, r); }
; DI float sum_x16_x32(float x) { return sum_x32(sum_x16(x)); }
;     DI void operator()(const f32x4 (&acc)[2][2][4][2], const Unit& u, int wr, int wc, int fr, int fq) const {
;         const int row0 = u.pm * 256 + wr * 64 + fr, col0 = u.pn * 256 + wc * 32 + 4 * fq;
; #pragma unroll
;         for (int ai = 0; ai < 2; ++ai)
; #pragma unroll
;             for (int m = 0; m < 4; ++m) {
;                 const int r = row0 + ai * 128 + m * 16;
;                 const float* rp;
;                 if (MODE == 0) rp = x + (size_t)r * 1024;
;                 else rp = h + (size_t)r * 1024;
;                 float sq = 0.f;
; #pragma unroll
;                 for (int bj = 0; bj < 2; ++bj)
; #pragma unroll
;                     for (int n = 0; n < 2; ++n) {
;                         const int c = col0 + bj * 128 + n * 16;
;                         f32x4 rv = rp ? *(const f32x4*)(rp + c) : (f32x4){0.f, 0.f, 0.f, 0.f};
;                         f32x4 v = acc[ai][bj][m][n] + rv;
;                         *(f32x4*)(h + (size_t)r * 1024 + c) = v;
;                         if (WRITE_HB) {
;                             u32x2 w; w.x = pk2(v[0], v[1]); w.y = pk2(v[2], v[3]);
;                             *(u32x2*)(hb + (size_t)r * 1024 + c) = w;
;                         }
;                         sq += v[0] * v[0] + v[1] * v[1] + v[2] * v[2] + v[3] * v[3];
;                     }
;                 sq = sum_x16_x32(sq);
;                 if (fq == 0) atomicAdd(ss + r, sq);
.LBB0_811:
	s_or_b64 exec, exec, s[22:23]
	v_add_u32_e32 v72, 0x80, v150
	v_ashrrev_i32_e32 v73, 31, v72
	v_lshlrev_b64 v[64:65], 12, v[72:73]
	v_lshl_add_u64 v[66:67], s[56:57], 0, v[64:65]
	v_mov_b32_e32 v64, 0
	s_and_b64 vcc, exec, s[8:9]
	v_lshl_add_u64 v[78:79], v[148:149], 2, v[66:67]
	v_mov_b32_e32 v66, 0
	v_mov_b32_e32 v67, 0
	v_mov_b32_e32 v68, 0
	v_mov_b32_e32 v69, 0
	s_cbranch_vccnz .LBB0_813
	v_lshl_add_u64 v[198:199], v[198:199], 0, s[98:99]
	global_load_dwordx4 v[212:215], v[198:199], off
	global_load_dwordx4 v[216:219], v[198:199], off offset:64
	global_load_dwordx4 v[220:223], v[198:199], off offset:512
	global_load_dwordx4 v[224:227], v[198:199], off offset:576
.LBB0_813:
	v_lshlrev_b64 v[70:71], 10, v[72:73]
	s_waitcnt vmcnt(15)
	v_pk_add_f32 v[62:63], v[62:63], v[182:183]
	v_pk_add_f32 v[60:61], v[60:61], v[180:181]
	v_lshl_add_u64 v[66:67], v[70:71], 2, s[66:67]
	v_lshl_add_u64 v[68:69], v[70:71], 1, s[68:69]
	v_lshl_add_u64 v[74:75], v[148:149], 2, v[66:67]
	v_cvt_pk_bf16_f32 v66, v60, v61
	v_cvt_pk_bf16_f32 v67, v62, v63
	v_lshl_add_u64 v[76:77], v[148:149], 1, v[68:69]
	global_store_dwordx4 v[74:75], v[60:63], off
	global_store_dwordx2 v[76:77], v[66:67], off
	s_and_b64 vcc, exec, s[8:9]
	v_mov_b32_e32 v65, 0
	v_mov_b32_e32 v66, 0
	v_mov_b32_e32 v67, 0
	s_cbranch_vccnz .LBB0_815
	s_nop 0
.LBB0_815:
	s_waitcnt vmcnt(16)
	v_pk_add_f32 v[66:67], v[58:59], v[186:187]
	v_pk_add_f32 v[64:65], v[56:57], v[184:185]
	v_cvt_pk_bf16_f32 v57, v66, v67
	v_cvt_pk_bf16_f32 v56, v64, v65
	global_store_dwordx4 v[74:75], v[64:67], off offset:64
	global_store_dwordx2 v[76:77], v[56:57], off offset:32
	v_mov_b32_e32 v56, 0
	s_and_b64 vcc, exec, s[8:9]
	v_mov_b32_e32 v68, 0
	v_mov_b32_e32 v69, 0
	v_mov_b32_e32 v70, 0
	v_mov_b32_e32 v71, 0
	s_cbranch_vccnz .LBB0_817
	s_nop 0
.LBB0_817:
	s_waitcnt vmcnt(17)
	v_pk_add_f32 v[54:55], v[54:55], v[190:191]
	v_pk_add_f32 v[52:53], v[52:53], v[188:189]
	v_cvt_pk_bf16_f32 v59, v54, v55
	v_cvt_pk_bf16_f32 v58, v52, v53
	global_store_dwordx4 v[74:75], v[52:55], off offset:512
	global_store_dwordx2 v[76:77], v[58:59], off offset:256
	s_and_b64 vcc, exec, s[8:9]
	v_mov_b32_e32 v57, 0
	v_mov_b32_e32 v58, 0
	v_mov_b32_e32 v59, 0
	s_cbranch_vccnz .LBB0_819
	s_nop 0
.LBB0_819:
	v_mul_f32_e32 v61, v61, v61
	v_fmac_f32_e32 v61, v60, v60
	v_mul_f32_e32 v60, v65, v65
	v_fmac_f32_e32 v60, v64, v64
	v_mul_f32_e32 v53, v53, v53
	s_waitcnt vmcnt(18)
	v_pk_add_f32 v[50:51], v[50:51], v[194:195]
	v_pk_add_f32 v[48:49], v[48:49], v[192:193]
	v_fmac_f32_e32 v61, v62, v62
	v_fmac_f32_e32 v60, v66, v66
	v_fmac_f32_e32 v53, v52, v52
	global_store_dwordx4 v[74:75], v[48:51], off offset:576
	v_cvt_pk_bf16_f32 v52, v48, v49
	v_fmac_f32_e32 v61, v63, v63
	v_mul_f32_e32 v49, v49, v49
	v_fmac_f32_e32 v60, v67, v67
	v_fmac_f32_e32 v53, v54, v54
	v_fmac_f32_e32 v49, v48, v48
	v_add_f32_e32 v60, v61, v60
	v_fmac_f32_e32 v53, v55, v55
	v_fmac_f32_e32 v49, v50, v50
	v_add_f32_e32 v54, v60, v53
	v_fmac_f32_e32 v49, v51, v51
	v_add_f32_e32 v48, v54, v49
	v_mov_b32_e32 v49, v48
	s_nop 1
	v_permlane16_swap_b32_e32 v48, v49
	v_add_f32_e32 v48, v48, v49
	v_mov_b32_e32 v49, v48
	v_cvt_pk_bf16_f32 v53, v50, v51
	s_nop 0
	v_permlane32_swap_b32_e32 v48, v49
	global_store_dwordx2 v[76:77], v[52:53], off offset:288
	s_and_saveexec_b64 s[22:23], s[4:5]
	s_cbranch_execz .LBB0_821
	v_lshl_add_u64 v[50:51], v[72:73], 2, s[94:95]
	v_add_f32_e32 v48, v48, v49
	global_atomic_add_f32 v[50:51], v48, off
.LBB0_821:
	s_or_b64 exec, exec, s[22:23]
	v_add_u32_e32 v56, 0x90, v150
	v_ashrrev_i32_e32 v57, 31, v56
	v_lshlrev_b64 v[48:49], 12, v[56:57]
	v_lshl_add_u64 v[50:51], s[56:57], 0, v[48:49]
	v_mov_b32_e32 v48, 0
	s_and_b64 vcc, exec, s[8:9]
	v_lshl_add_u64 v[62:63], v[148:149], 2, v[50:51]
	v_mov_b32_e32 v50, 0
	v_mov_b32_e32 v51, 0
	v_mov_b32_e32 v52, 0
	v_mov_b32_e32 v53, 0
	s_cbranch_vccnz .LBB0_823
	v_lshl_add_u64 v[198:199], v[198:199], 0, s[98:99]
	global_load_dwordx4 v[180:183], v[198:199], off
	global_load_dwordx4 v[184:187], v[198:199], off offset:64
	global_load_dwordx4 v[188:191], v[198:199], off offset:512
	global_load_dwordx4 v[192:195], v[198:199], off offset:576
.LBB0_823:
	v_lshlrev_b64 v[54:55], 10, v[56:57]
	s_waitcnt vmcnt(15)
	v_pk_add_f32 v[46:47], v[46:47], v[214:215]
	v_pk_add_f32 v[44:45], v[44:45], v[212:213]
	v_lshl_add_u64 v[50:51], v[54:55], 2, s[66:67]
	v_lshl_add_u64 v[52:53], v[54:55], 1, s[68:69]
	v_lshl_add_u64 v[58:59], v[148:149], 2, v[50:51]
	v_cvt_pk_bf16_f32 v50, v44, v45
	v_cvt_pk_bf16_f32 v51, v46, v47
	v_lshl_add_u64 v[60:61], v[148:149], 1, v[52:53]
	global_store_dwordx4 v[58:59], v[44:47], off
	global_store_dwordx2 v[60:61], v[50:51], off
	s_and_b64 vcc, exec, s[8:9]
	v_mov_b32_e32 v49, 0
	v_mov_b32_e32 v50, 0
	v_mov_b32_e32 v51, 0
	s_cbranch_vccnz .LBB0_825
	s_nop 0
.LBB0_825:
	s_waitcnt vmcnt(16)
	v_pk_add_f32 v[50:51], v[42:43], v[218:219]
	v_pk_add_f32 v[48:49], v[40:41], v[216:217]
	v_cvt_pk_bf16_f32 v41, v50, v51
	v_cvt_pk_bf16_f32 v40, v48, v49
	global_store_dwordx4 v[58:59], v[48:51], off offset:64
	global_store_dwordx2 v[60:61], v[40:41], off offset:32
	v_mov_b32_e32 v40, 0
	s_and_b64 vcc, exec, s[8:9]
	v_mov_b32_e32 v52, 0
	v_mov_b32_e32 v53, 0
	v_mov_b32_e32 v54, 0
	v_mov_b32_e32 v55, 0
	s_cbranch_vccnz .LBB0_827
	s_nop 0
.LBB0_827:
	s_waitcnt vmcnt(17)
	v_pk_add_f32 v[38:39], v[38:39], v[222:223]
	v_pk_add_f32 v[36:37], v[36:37], v[220:221]
	v_cvt_pk_bf16_f32 v43, v38, v39
	v_cvt_pk_bf16_f32 v42, v36, v37
	global_store_dwordx4 v[58:59], v[36:39], off offset:512
	global_store_dwordx2 v[60:61], v[42:43], off offset:256
	s_and_b64 vcc, exec, s[8:9]
	v_mov_b32_e32 v41, 0
	v_mov_b32_e32 v42, 0
	v_mov_b32_e32 v43, 0
	s_cbranch_vccnz .LBB0_829
	s_nop 0
; DI unsigned pk2(float a, float b) { f32x2 v = {a, b}; hbf2 r = __builtin_convertvector(v, hbf2); return __builtin_bit_cast(unsigned, r); }
; DI float sum_x16_x32(float x) { return sum_x32(sum_x16(x)); }
;     DI void operator()(const f32x4 (&acc)[2][2][4][2], const Unit& u, int wr, int wc, int fr, int fq) const {
;         const int row0 = u.pm * 256 + wr * 64 + fr, col0 = u.pn * 256 + wc * 32 + 4 * fq;
; #pragma unroll
;         for (int ai = 0; ai < 2; ++ai)
; #pragma unroll
;             for (int m = 0; m < 4; ++m) {
;                 const int r = row0 + ai * 128 + m * 16;
;                 const float* rp;
;                 if (MODE == 0) rp = x + (size_t)r * 1024;
;                 else rp = h + (size_t)r * 1024;
;                 float sq = 0.f;
; #pragma unroll
;                 for (int bj = 0; bj < 2; ++bj)
; #pragma unroll
;                     for (int n = 0; n < 2; ++n) {
;                         const int c = col0 + bj * 128 + n * 16;
;                         f32x4 rv = rp ? *(const f32x4*)(rp + c) : (f32x4){0.f, 0.f, 0.f, 0.f};
;                         f32x4 v = acc[ai][bj][m][n] + rv;
;                         *(f32x4*)(h + (size_t)r * 1024 + c) = v;
;                         if (WRITE_HB) {
;                             u32x2 w; w.x = pk2(v[0], v[1]); w.y = pk2(v[2], v[3]);
;                             *(u32x2*)(hb + (size_t)r * 1024 + c) = w;
;                         }
;                         sq += v[0] * v[0] + v[1] * v[1] + v[2] * v[2] + v[3] * v[3];
;                     }
;                 sq = sum_x16_x32(sq);
;                 if (fq == 0) atomicAdd(ss + r, sq);
.LBB0_829:
	v_mul_f32_e32 v45, v45, v45
	v_fmac_f32_e32 v45, v44, v44
	v_mul_f32_e32 v44, v49, v49
	v_fmac_f32_e32 v44, v48, v48
	v_mul_f32_e32 v37, v37, v37
	s_waitcnt vmcnt(18)
	v_pk_add_f32 v[34:35], v[34:35], v[226:227]
	v_pk_add_f32 v[32:33], v[32:33], v[224:225]
	v_fmac_f32_e32 v45, v46, v46
	v_fmac_f32_e32 v44, v50, v50
	v_fmac_f32_e32 v37, v36, v36
	global_store_dwordx4 v[58:59], v[32:35], off offset:576
	v_cvt_pk_bf16_f32 v36, v32, v33
	v_fmac_f32_e32 v45, v47, v47
	v_mul_f32_e32 v33, v33, v33
	v_fmac_f32_e32 v44, v51, v51
	v_fmac_f32_e32 v37, v38, v38
	v_fmac_f32_e32 v33, v32, v32
	v_add_f32_e32 v44, v45, v44
	v_fmac_f32_e32 v37, v39, v39
	v_fmac_f32_e32 v33, v34, v34
	v_add_f32_e32 v38, v44, v37
	v_fmac_f32_e32 v33, v35, v35
	v_add_f32_e32 v32, v38, v33
	v_mov_b32_e32 v33, v32
	s_nop 1
	v_permlane16_swap_b32_e32 v32, v33
	v_add_f32_e32 v32, v32, v33
	v_mov_b32_e32 v33, v32
	v_cvt_pk_bf16_f32 v37, v34, v35
	s_nop 0
	v_permlane32_swap_b32_e32 v32, v33
	global_store_dwordx2 v[60:61], v[36:37], off offset:288
	s_and_saveexec_b64 s[22:23], s[4:5]
	s_cbranch_execz .LBB0_831
	v_lshl_add_u64 v[34:35], v[56:57], 2, s[94:95]
	v_add_f32_e32 v32, v32, v33
	global_atomic_add_f32 v[34:35], v32, off
.LBB0_831:
	s_or_b64 exec, exec, s[22:23]
	v_add_u32_e32 v40, 0xa0, v150
	v_ashrrev_i32_e32 v41, 31, v40
	v_lshlrev_b64 v[32:33], 12, v[40:41]
	v_lshl_add_u64 v[34:35], s[56:57], 0, v[32:33]
	v_mov_b32_e32 v32, 0
	s_and_b64 vcc, exec, s[8:9]
	v_lshl_add_u64 v[46:47], v[148:149], 2, v[34:35]
	v_mov_b32_e32 v34, 0
	v_mov_b32_e32 v35, 0
	v_mov_b32_e32 v36, 0
	v_mov_b32_e32 v37, 0
	s_cbranch_vccnz .LBB0_833
	v_lshl_add_u64 v[198:199], v[198:199], 0, s[98:99]
	global_load_dwordx4 v[212:215], v[198:199], off
	global_load_dwordx4 v[216:219], v[198:199], off offset:64
	global_load_dwordx4 v[220:223], v[198:199], off offset:512
	global_load_dwordx4 v[224:227], v[198:199], off offset:576
.LBB0_833:
	v_lshlrev_b64 v[38:39], 10, v[40:41]
	s_waitcnt vmcnt(15)
	v_pk_add_f32 v[30:31], v[30:31], v[182:183]
	v_pk_add_f32 v[28:29], v[28:29], v[180:181]
	v_lshl_add_u64 v[34:35], v[38:39], 2, s[66:67]
	v_lshl_add_u64 v[36:37], v[38:39], 1, s[68:69]
	v_lshl_add_u64 v[42:43], v[148:149], 2, v[34:35]
	v_cvt_pk_bf16_f32 v34, v28, v29
	v_cvt_pk_bf16_f32 v35, v30, v31
	v_lshl_add_u64 v[44:45], v[148:149], 1, v[36:37]
	global_store_dwordx4 v[42:43], v[28:31], off
	global_store_dwordx2 v[44:45], v[34:35], off
	s_and_b64 vcc, exec, s[8:9]
	v_mov_b32_e32 v33, 0
	v_mov_b32_e32 v34, 0
	v_mov_b32_e32 v35, 0
	s_cbranch_vccnz .LBB0_835
	s_nop 0
.LBB0_835:
	s_waitcnt vmcnt(16)
	v_pk_add_f32 v[34:35], v[26:27], v[186:187]
	v_pk_add_f32 v[32:33], v[24:25], v[184:185]
	v_cvt_pk_bf16_f32 v25, v34, v35
	v_cvt_pk_bf16_f32 v24, v32, v33
	global_store_dwordx4 v[42:43], v[32:35], off offset:64
	global_store_dwordx2 v[44:45], v[24:25], off offset:32
	v_mov_b32_e32 v24, 0
	s_and_b64 vcc, exec, s[8:9]
	v_mov_b32_e32 v36, 0
	v_mov_b32_e32 v37, 0
	v_mov_b32_e32 v38, 0
	v_mov_b32_e32 v39, 0
	s_cbranch_vccnz .LBB0_837
	s_nop 0
.LBB0_837:
	s_waitcnt vmcnt(17)
	v_pk_add_f32 v[22:23], v[22:23], v[190:191]
	v_pk_add_f32 v[20:21], v[20:21], v[188:189]
	v_cvt_pk_bf16_f32 v27, v22, v23
	v_cvt_pk_bf16_f32 v26, v20, v21
	global_store_dwordx4 v[42:43], v[20:23], off offset:512
	global_store_dwordx2 v[44:45], v[26:27], off offset:256
	s_and_b64 vcc, exec, s[8:9]
	v_mov_b32_e32 v25, 0
	v_mov_b32_e32 v26, 0
	v_mov_b32_e32 v27, 0
	s_cbranch_vccnz .LBB0_839
	s_nop 0
; DI unsigned pk2(float a, float b) { f32x2 v = {a, b}; hbf2 r = __builtin_convertvector(v, hbf2); return __builtin_bit_cast(unsigned, r); }
; DI float sum_x16_x32(float x) { return sum_x32(sum_x16(x)); }
;     DI void operator()(const f32x4 (&acc)[2][2][4][2], const Unit& u, int wr, int wc, int fr, int fq) const {
;         const int row0 = u.pm * 256 + wr * 64 + fr, col0 = u.pn * 256 + wc * 32 + 4 * fq;
; #pragma unroll
;         for (int ai = 0; ai < 2; ++ai)
; #pragma unroll
;             for (int m = 0; m < 4; ++m) {
;                 const int r = row0 + ai * 128 + m * 16;
;                 const float* rp;
;                 if (MODE == 0) rp = x + (size_t)r * 1024;
;                 else rp = h + (size_t)r * 1024;
;                 float sq = 0.f;
; #pragma unroll
;                 for (int bj = 0; bj < 2; ++bj)
; #pragma unroll
;                     for (int n = 0; n < 2; ++n) {
;                         const int c = col0 + bj * 128 + n * 16;
;                         f32x4 rv = rp ? *(const f32x4*)(rp + c) : (f32x4){0.f, 0.f, 0.f, 0.f};
;                         f32x4 v = acc[ai][bj][m][n] + rv;
;                         *(f32x4*)(h + (size_t)r * 1024 + c) = v;
;                         if (WRITE_HB) {
;                             u32x2 w; w.x = pk2(v[0], v[1]); w.y = pk2(v[2], v[3]);
;                             *(u32x2*)(hb + (size_t)r * 1024 + c) = w;
;                         }
;                         sq += v[0] * v[0] + v[1] * v[1] + v[2] * v[2] + v[3] * v[3];
;                     }
;                 sq = sum_x16_x32(sq);
;                 if (fq == 0) atomicAdd(ss + r, sq);
.LBB0_839:
	v_mul_f32_e32 v29, v29, v29
	v_fmac_f32_e32 v29, v28, v28
	v_mul_f32_e32 v28, v33, v33
	v_fmac_f32_e32 v28, v32, v32
	v_mul_f32_e32 v21, v21, v21
	s_waitcnt vmcnt(18)
	v_pk_add_f32 v[18:19], v[18:19], v[194:195]
	v_pk_add_f32 v[16:17], v[16:17], v[192:193]
	v_fmac_f32_e32 v29, v30, v30
	v_fmac_f32_e32 v28, v34, v34
	v_fmac_f32_e32 v21, v20, v20
	global_store_dwordx4 v[42:43], v[16:19], off offset:576
	v_cvt_pk_bf16_f32 v20, v16, v17
	v_fmac_f32_e32 v29, v31, v31
	v_mul_f32_e32 v17, v17, v17
	v_fmac_f32_e32 v28, v35, v35
	v_fmac_f32_e32 v21, v22, v22
	v_fmac_f32_e32 v17, v16, v16
	v_add_f32_e32 v28, v29, v28
	v_fmac_f32_e32 v21, v23, v23
	v_fmac_f32_e32 v17, v18, v18
	v_add_f32_e32 v22, v28, v21
	v_fmac_f32_e32 v17, v19, v19
	v_add_f32_e32 v16, v22, v17
	v_mov_b32_e32 v17, v16
	s_nop 1
	v_permlane16_swap_b32_e32 v16, v17
	v_add_f32_e32 v16, v16, v17
	v_mov_b32_e32 v17, v16
	v_cvt_pk_bf16_f32 v21, v18, v19
	s_nop 0
	v_permlane32_swap_b32_e32 v16, v17
	global_store_dwordx2 v[44:45], v[20:21], off offset:288
	s_and_saveexec_b64 s[22:23], s[4:5]
	s_cbranch_execz .LBB0_841
	v_lshl_add_u64 v[18:19], v[40:41], 2, s[94:95]
	v_add_f32_e32 v16, v16, v17
	global_atomic_add_f32 v[18:19], v16, off
.LBB0_841:
	s_or_b64 exec, exec, s[22:23]
	v_add_u32_e32 v24, 0xb0, v150
	v_ashrrev_i32_e32 v25, 31, v24
	v_lshlrev_b64 v[16:17], 12, v[24:25]
	v_lshl_add_u64 v[18:19], s[56:57], 0, v[16:17]
	v_mov_b32_e32 v16, 0
	s_and_b64 vcc, exec, s[8:9]
	v_lshl_add_u64 v[30:31], v[148:149], 2, v[18:19]
	v_mov_b32_e32 v18, 0
	v_mov_b32_e32 v19, 0
	v_mov_b32_e32 v20, 0
	v_mov_b32_e32 v21, 0
	s_cbranch_vccnz .LBB0_843
	s_nop 0
.LBB0_843:
	v_lshlrev_b64 v[22:23], 10, v[24:25]
	s_waitcnt vmcnt(11)
	v_pk_add_f32 v[14:15], v[14:15], v[214:215]
	v_pk_add_f32 v[12:13], v[12:13], v[212:213]
	v_lshl_add_u64 v[18:19], v[22:23], 2, s[66:67]
	v_lshl_add_u64 v[20:21], v[22:23], 1, s[68:69]
	v_lshl_add_u64 v[26:27], v[148:149], 2, v[18:19]
	v_cvt_pk_bf16_f32 v18, v12, v13
	v_cvt_pk_bf16_f32 v19, v14, v15
	v_lshl_add_u64 v[28:29], v[148:149], 1, v[20:21]
	global_store_dwordx4 v[26:27], v[12:15], off
	global_store_dwordx2 v[28:29], v[18:19], off
	s_and_b64 vcc, exec, s[8:9]
	v_mov_b32_e32 v17, 0
	v_mov_b32_e32 v18, 0
	v_mov_b32_e32 v19, 0
	s_cbranch_vccnz .LBB0_845
	s_nop 0
.LBB0_845:
	s_waitcnt vmcnt(12)
	v_pk_add_f32 v[18:19], v[10:11], v[218:219]
	v_pk_add_f32 v[16:17], v[8:9], v[216:217]
	v_cvt_pk_bf16_f32 v9, v18, v19
	v_cvt_pk_bf16_f32 v8, v16, v17
	global_store_dwordx4 v[26:27], v[16:19], off offset:64
	global_store_dwordx2 v[28:29], v[8:9], off offset:32
	v_mov_b32_e32 v8, 0
	s_and_b64 vcc, exec, s[8:9]
	v_mov_b32_e32 v20, 0
	v_mov_b32_e32 v21, 0
	v_mov_b32_e32 v22, 0
	v_mov_b32_e32 v23, 0
	s_cbranch_vccnz .LBB0_847
	s_nop 0
.LBB0_847:
	s_waitcnt vmcnt(13)
	v_pk_add_f32 v[6:7], v[6:7], v[222:223]
	v_pk_add_f32 v[4:5], v[4:5], v[220:221]
	v_cvt_pk_bf16_f32 v11, v6, v7
	v_cvt_pk_bf16_f32 v10, v4, v5
	global_store_dwordx4 v[26:27], v[4:7], off offset:512
	global_store_dwordx2 v[28:29], v[10:11], off offset:256
	s_and_b64 vcc, exec, s[8:9]
	v_mov_b32_e32 v9, 0
	v_mov_b32_e32 v10, 0
	v_mov_b32_e32 v11, 0
	s_cbranch_vccnz .LBB0_849
	s_nop 0
.LBB0_849:
	v_mul_f32_e32 v13, v13, v13
	v_fmac_f32_e32 v13, v12, v12
	v_mul_f32_e32 v12, v17, v17
	v_fmac_f32_e32 v12, v16, v16
	v_mul_f32_e32 v5, v5, v5
	s_waitcnt vmcnt(14)
	v_pk_add_f32 v[2:3], v[2:3], v[226:227]
	v_pk_add_f32 v[0:1], v[0:1], v[224:225]
	v_fmac_f32_e32 v13, v14, v14
	v_fmac_f32_e32 v12, v18, v18
	v_fmac_f32_e32 v5, v4, v4
	global_store_dwordx4 v[26:27], v[0:3], off offset:576
	v_cvt_pk_bf16_f32 v4, v0, v1
	v_fmac_f32_e32 v13, v15, v15
	v_mul_f32_e32 v1, v1, v1
	v_fmac_f32_e32 v12, v19, v19
	v_fmac_f32_e32 v5, v6, v6
	v_fmac_f32_e32 v1, v0, v0
	v_add_f32_e32 v12, v13, v12
	v_fmac_f32_e32 v5, v7, v7
	v_fmac_f32_e32 v1, v2, v2
	v_add_f32_e32 v6, v12, v5
	v_fmac_f32_e32 v1, v3, v3
	v_add_f32_e32 v0, v6, v1
	v_mov_b32_e32 v1, v0
	s_nop 1
	v_permlane16_swap_b32_e32 v0, v1
	v_add_f32_e32 v0, v0, v1
	v_mov_b32_e32 v1, v0
	v_cvt_pk_bf16_f32 v5, v2, v3
	s_nop 0
	v_permlane32_swap_b32_e32 v0, v1
	global_store_dwordx2 v[28:29], v[4:5], off offset:288
	s_and_saveexec_b64 s[8:9], s[4:5]
	s_cbranch_execz .LBB0_762
	v_lshl_add_u64 v[2:3], v[24:25], 2, s[94:95]
	v_add_f32_e32 v0, v0, v1
	global_atomic_add_f32 v[2:3], v0, off
	s_branch .LBB0_762

; #define PG8_STAGE(bufoff, gbase, voff) do { _Pragma("unroll") for (int _i = 0; _i < 2; ++_i) \
;         __builtin_amdgcn_global_load_lds((const unsigned*)((const char*)(gbase) + (voff)[_i]), (LAS unsigned*)(lds + (bufoff) + ldsw + _i * 8192), 16, 0, 0); } while (0)
; #define PG8_LDA(dst, b, h) do { _Pragma("unroll") for (int m = 0; m < 4; ++m) _Pragma("unroll") for (int k = 0; k < 2; ++k) dst[m][k] = *(const LAS bf16x8*)(lds + PG8_SA(b, h) + aoff + m * 2048 + k * 1024); } while (0)
; #define PG8_LDB(dst, b, h) do { _Pragma("unroll") for (int n = 0; n < 2; ++n) _Pragma("unroll") for (int k = 0; k < 2; ++k) dst[n][k] = *(const LAS bf16x8*)(lds + PG8_SB(b, h) + boff + n * 2048 + k * 1024); } while (0)
; #define PG8_MMA(ai, bj, At, Bt) do { __builtin_amdgcn_s_setprio(1); _Pragma("unroll") for (int m = 0; m < 4; ++m) _Pragma("unroll") for (int n = 0; n < 2; ++n) _Pragma("unroll") for (int k = 0; k < 2; ++k) \
;         acc[ai][bj][m][n] = __builtin_amdgcn_mfma_f32_16x16x32_bf16(Bt[n][k], At[m][k], acc[ai][bj][m][n], 0, 0, 0); __builtin_amdgcn_s_setprio(0); } while (0)
; #define PG8_WAIT_L(n) asm volatile("s_waitcnt lgkmcnt(" #n ")" ::: "memory")
; #define PG8_BAR __builtin_amdgcn_s_barrier()
; #define PG8_SCHED __builtin_amdgcn_sched_barrier(0)
; template <class Epi>
; __device__ __forceinline__ void gemm_phase(LAS unsigned char* lds, const Gemm g, const StaticOrder& S, const Epi& E) {
;     ...
;         for (int t = 0; t < nt; t += 2) {
;             const bool last = (t == nt - 2);
;             const char* a1 = cA + (size_t)(t + 1) * kstep;
;             const char* a2 = last ? nA : cA + (size_t)(t + 2) * kstep; const char* b2 = last ? nB : cB + (size_t)(t + 2) * kstep;
;             const char* a3 = a2 + kstep; const char* b3 = b2 + kstep;
;             PG8_LDB(B0, 0, 0); PG8_SCHED; PG8_LDA(At, 0, 0); PG8_STAGE(PG8_SA(1, 1), a1 + hstep, voffA);
;             PG8_WAIT_L(8); PG8_BAR; PG8_WAIT_L(0); PG8_MMA(0, 0, At, B0); PG8_BAR; PG8_SCHED;
;             PG8_LDB(B1, 0, 1); PG8_STAGE(PG8_SB(0, 0), b2, voffB);
;             PG8_BAR; PG8_WAIT_L(0); PG8_MMA(0, 1, At, B1); PG8_BAR;
;             PG8_LDA(At, 0, 1); PG8_STAGE(PG8_SA(0, 0), a2, voffA);
;             PG8_BAR; PG8_WAIT_L(0); PG8_MMA(1, 0, At, B0); PG8_BAR; PG8_SCHED;
.LBB0_1008:
	ds_read_b128 v[140:143], v147
	ds_read_b128 v[150:153], v147 offset:1024
	ds_read_b128 v[154:157], v147 offset:2048
	ds_read_b128 v[158:161], v147 offset:3072
	s_add_u32 s24, s22, 0x100
	s_addc_u32 s25, s23, 0
	s_cmp_eq_u32 s57, 60
	s_cselect_b32 s29, s11, s25
	s_cselect_b32 s28, s19, s24
	s_cselect_b32 s27, s9, s56
	s_cselect_b32 s26, s50, s51
	v_lshl_add_u64 v[176:177], s[22:23], 0, v[132:133]
	s_add_i32 m0, s21, 0xc000
	ds_read_b128 v[162:165], v148
	ds_read_b128 v[166:169], v148 offset:1024
	ds_read_b128 v[170:173], v148 offset:2048
	ds_read_b128 v[180:183], v148 offset:3072
	ds_read_b128 v[184:187], v148 offset:4096
	ds_read_b128 v[188:191], v148 offset:5120
	ds_read_b128 v[192:195], v148 offset:6144
	ds_read_b128 v[196:199], v148 offset:7168
	global_load_lds_dwordx4 v[176:177], off
	v_lshl_add_u64 v[176:177], s[22:23], 0, v[134:135]
	s_add_i32 m0, s21, 0xe000
	s_nop 0
	global_load_lds_dwordx4 v[176:177], off
	s_waitcnt lgkmcnt(8)
	s_barrier
	s_waitcnt lgkmcnt(0)
	s_setprio 1
	s_waitcnt lgkmcnt(0)
	v_mfma_f32_16x16x32_bf16 v[124:127], v[140:143], v[162:165], v[124:127]
	v_mfma_f32_16x16x32_bf16 v[120:123], v[154:157], v[162:165], v[120:123]
	v_mfma_f32_16x16x32_bf16 v[108:111], v[140:143], v[170:173], v[108:111]
	v_mfma_f32_16x16x32_bf16 v[104:107], v[154:157], v[170:173], v[104:107]
	v_mfma_f32_16x16x32_bf16 v[92:95], v[140:143], v[184:187], v[92:95]
	v_mfma_f32_16x16x32_bf16 v[88:91], v[154:157], v[184:187], v[88:91]
	v_mfma_f32_16x16x32_bf16 v[76:79], v[140:143], v[192:195], v[76:79]
	v_mfma_f32_16x16x32_bf16 v[72:75], v[154:157], v[192:195], v[72:75]
	v_mfma_f32_16x16x32_bf16 v[124:127], v[150:153], v[166:169], v[124:127]
	v_mfma_f32_16x16x32_bf16 v[120:123], v[158:161], v[166:169], v[120:123]
	v_mfma_f32_16x16x32_bf16 v[108:111], v[150:153], v[180:183], v[108:111]
	v_mfma_f32_16x16x32_bf16 v[104:107], v[158:161], v[180:183], v[104:107]
	v_mfma_f32_16x16x32_bf16 v[92:95], v[150:153], v[188:191], v[92:95]
	v_mfma_f32_16x16x32_bf16 v[88:91], v[158:161], v[188:191], v[88:91]
	v_mfma_f32_16x16x32_bf16 v[76:79], v[150:153], v[196:199], v[76:79]
	v_mfma_f32_16x16x32_bf16 v[72:75], v[158:161], v[196:199], v[72:75]
	s_setprio 0
	s_barrier
	s_add_i32 s22, s48, s3
	v_lshl_add_u64 v[176:177], s[26:27], 0, v[128:129]
	s_mov_b32 m0, s22
	ds_read_b128 v[200:203], v149
	ds_read_b128 v[204:207], v149 offset:1024
	ds_read_b128 v[208:211], v149 offset:2048
	ds_read_b128 v[212:215], v149 offset:3072
	global_load_lds_dwordx4 v[176:177], off
	v_lshl_add_u64 v[216:217], s[26:27], 0, v[130:131]
	s_add_i32 m0, s22, 0x2000
	s_nop 0
	global_load_lds_dwordx4 v[216:217], off
	s_barrier
	s_waitcnt lgkmcnt(0)
	s_setprio 1
	s_waitcnt lgkmcnt(0)
	v_mfma_f32_16x16x32_bf16 v[116:119], v[200:203], v[162:165], v[116:119]
	v_mfma_f32_16x16x32_bf16 v[112:115], v[208:211], v[162:165], v[112:115]
	v_mfma_f32_16x16x32_bf16 v[100:103], v[200:203], v[170:173], v[100:103]
	v_mfma_f32_16x16x32_bf16 v[96:99], v[208:211], v[170:173], v[96:99]
	v_mfma_f32_16x16x32_bf16 v[84:87], v[200:203], v[184:187], v[84:87]
	v_mfma_f32_16x16x32_bf16 v[80:83], v[208:211], v[184:187], v[80:83]
	v_mfma_f32_16x16x32_bf16 v[68:71], v[200:203], v[192:195], v[68:71]
	v_mfma_f32_16x16x32_bf16 v[64:67], v[208:211], v[192:195], v[64:67]
	v_mfma_f32_16x16x32_bf16 v[116:119], v[204:207], v[166:169], v[116:119]
	v_mfma_f32_16x16x32_bf16 v[112:115], v[212:215], v[166:169], v[112:115]
	v_mfma_f32_16x16x32_bf16 v[100:103], v[204:207], v[180:183], v[100:103]
	v_mfma_f32_16x16x32_bf16 v[96:99], v[212:215], v[180:183], v[96:99]
	v_mfma_f32_16x16x32_bf16 v[84:87], v[204:207], v[188:191], v[84:87]
	v_mfma_f32_16x16x32_bf16 v[80:83], v[212:215], v[188:191], v[80:83]
	v_mfma_f32_16x16x32_bf16 v[68:71], v[204:207], v[196:199], v[68:71]
	v_mfma_f32_16x16x32_bf16 v[64:67], v[212:215], v[196:199], v[64:67]
	s_setprio 0
	s_mov_b32 m0, s21
	v_lshl_add_u64 v[218:219], s[28:29], 0, v[128:129]
	s_barrier
	ds_read_b128 v[162:165], v148 offset:16384
	ds_read_b128 v[166:169], v148 offset:17408
	ds_read_b128 v[170:173], v148 offset:18432
	ds_read_b128 v[180:183], v148 offset:19456
	ds_read_b128 v[184:187], v148 offset:20480
	ds_read_b128 v[188:191], v148 offset:21504
	ds_read_b128 v[192:195], v148 offset:22528
	ds_read_b128 v[196:199], v148 offset:23552
	global_load_lds_dwordx4 v[218:219], off
	v_lshl_add_u64 v[220:221], s[28:29], 0, v[130:131]
	s_mov_b32 m0, s33
	s_nop 0
	global_load_lds_dwordx4 v[220:221], off
	s_barrier
	s_waitcnt lgkmcnt(0)
	s_setprio 1
	s_waitcnt lgkmcnt(0)
	v_mfma_f32_16x16x32_bf16 v[60:63], v[140:143], v[162:165], v[60:63]
	v_mfma_f32_16x16x32_bf16 v[56:59], v[154:157], v[162:165], v[56:59]
	v_mfma_f32_16x16x32_bf16 v[44:47], v[140:143], v[170:173], v[44:47]
	v_mfma_f32_16x16x32_bf16 v[40:43], v[154:157], v[170:173], v[40:43]
	v_mfma_f32_16x16x32_bf16 v[28:31], v[140:143], v[184:187], v[28:31]
	v_mfma_f32_16x16x32_bf16 v[24:27], v[154:157], v[184:187], v[24:27]
	v_mfma_f32_16x16x32_bf16 v[12:15], v[140:143], v[192:195], v[12:15]
	v_mfma_f32_16x16x32_bf16 v[8:11], v[154:157], v[192:195], v[8:11]
	v_mfma_f32_16x16x32_bf16 v[60:63], v[150:153], v[166:169], v[60:63]
	v_mfma_f32_16x16x32_bf16 v[56:59], v[158:161], v[166:169], v[56:59]
	v_mfma_f32_16x16x32_bf16 v[44:47], v[150:153], v[180:183], v[44:47]
	v_mfma_f32_16x16x32_bf16 v[40:43], v[158:161], v[180:183], v[40:43]
	v_mfma_f32_16x16x32_bf16 v[28:31], v[150:153], v[188:191], v[28:31]
	v_mfma_f32_16x16x32_bf16 v[24:27], v[158:161], v[188:191], v[24:27]
	v_mfma_f32_16x16x32_bf16 v[12:15], v[150:153], v[196:199], v[12:15]
	v_mfma_f32_16x16x32_bf16 v[8:11], v[158:161], v[196:199], v[8:11]
	s_setprio 0
	s_barrier
; #define PG8_STAGE(bufoff, gbase, voff) do { _Pragma("unroll") for (int _i = 0; _i < 2; ++_i) \
;         __builtin_amdgcn_global_load_lds((const unsigned*)((const char*)(gbase) + (voff)[_i]), (LAS unsigned*)(lds + (bufoff) + ldsw + _i * 8192), 16, 0, 0); } while (0)
; #define PG8_LDA(dst, b, h) do { _Pragma("unroll") for (int m = 0; m < 4; ++m) _Pragma("unroll") for (int k = 0; k < 2; ++k) dst[m][k] = *(const LAS bf16x8*)(lds + PG8_SA(b, h) + aoff + m * 2048 + k * 1024); } while (0)
; #define PG8_LDB(dst, b, h) do { _Pragma("unroll") for (int n = 0; n < 2; ++n) _Pragma("unroll") for (int k = 0; k < 2; ++k) dst[n][k] = *(const LAS bf16x8*)(lds + PG8_SB(b, h) + boff + n * 2048 + k * 1024); } while (0)
; #define PG8_MMA(ai, bj, At, Bt) do { __builtin_amdgcn_s_setprio(1); _Pragma("unroll") for (int m = 0; m < 4; ++m) _Pragma("unroll") for (int n = 0; n < 2; ++n) _Pragma("unroll") for (int k = 0; k < 2; ++k) \
;         acc[ai][bj][m][n] = __builtin_amdgcn_mfma_f32_16x16x32_bf16(Bt[n][k], At[m][k], acc[ai][bj][m][n], 0, 0, 0); __builtin_amdgcn_s_setprio(0); } while (0)
; #define PG8_WAIT_V(n) asm volatile("s_waitcnt vmcnt(" #n ")" ::: "memory")
; #define PG8_WAIT_L(n) asm volatile("s_waitcnt lgkmcnt(" #n ")" ::: "memory")
; #define PG8_BAR __builtin_amdgcn_s_barrier()
; #define PG8_SCHED __builtin_amdgcn_sched_barrier(0)
; template <class Epi>
; __device__ __forceinline__ void gemm_phase(LAS unsigned char* lds, const Gemm g, const StaticOrder& S, const Epi& E) {
;     ...
;             PG8_STAGE(PG8_SB(0, 1), b2 + hstep, voffB);
;             PG8_WAIT_V(6); PG8_BAR; PG8_MMA(1, 1, At, B1); PG8_BAR;
;             PG8_LDB(B0, 1, 0); PG8_SCHED; PG8_LDA(At, 1, 0); PG8_STAGE(PG8_SA(0, 1), a2 + hstep, voffA);
;             PG8_WAIT_L(8); PG8_BAR; PG8_WAIT_L(0); PG8_MMA(0, 0, At, B0); PG8_BAR; PG8_SCHED;
;             PG8_LDB(B1, 1, 1); PG8_STAGE(PG8_SB(1, 0), b3, voffB);
;             PG8_BAR; PG8_WAIT_L(0); PG8_MMA(0, 1, At, B1); PG8_BAR;
;             PG8_LDA(At, 1, 1); PG8_STAGE(PG8_SA(1, 0), a3, voffA);
;             PG8_BAR; PG8_WAIT_L(0); PG8_MMA(1, 0, At, B0); PG8_BAR; PG8_SCHED;
	s_add_u32 s22, s26, 0x100000
	s_addc_u32 s23, s27, 0
	s_add_i32 s58, s49, s3
	v_lshl_add_u64 v[140:141], s[22:23], 0, v[128:129]
	s_mov_b32 m0, s58
	s_nop 0
	global_load_lds_dwordx4 v[140:141], off
	v_lshl_add_u64 v[140:141], s[22:23], 0, v[130:131]
	s_add_i32 m0, s58, 0x2000
	s_nop 0
	global_load_lds_dwordx4 v[140:141], off
	s_waitcnt vmcnt(6)
	s_barrier
	s_setprio 1
	v_mfma_f32_16x16x32_bf16 v[52:55], v[200:203], v[162:165], v[52:55]
	v_mfma_f32_16x16x32_bf16 v[48:51], v[208:211], v[162:165], v[48:51]
	v_mfma_f32_16x16x32_bf16 v[36:39], v[200:203], v[170:173], v[36:39]
	v_mfma_f32_16x16x32_bf16 v[32:35], v[208:211], v[170:173], v[32:35]
	v_mfma_f32_16x16x32_bf16 v[20:23], v[200:203], v[184:187], v[20:23]
	v_mfma_f32_16x16x32_bf16 v[16:19], v[208:211], v[184:187], v[16:19]
	v_mfma_f32_16x16x32_bf16 v[4:7], v[200:203], v[192:195], v[4:7]
	v_mfma_f32_16x16x32_bf16 v[0:3], v[208:211], v[192:195], v[0:3]
	v_mfma_f32_16x16x32_bf16 v[52:55], v[204:207], v[166:169], v[52:55]
	v_mfma_f32_16x16x32_bf16 v[48:51], v[212:215], v[166:169], v[48:51]
	v_mfma_f32_16x16x32_bf16 v[36:39], v[204:207], v[180:183], v[36:39]
	v_mfma_f32_16x16x32_bf16 v[32:35], v[212:215], v[180:183], v[32:35]
	v_mfma_f32_16x16x32_bf16 v[20:23], v[204:207], v[188:191], v[20:23]
	v_mfma_f32_16x16x32_bf16 v[16:19], v[212:215], v[188:191], v[16:19]
	v_mfma_f32_16x16x32_bf16 v[4:7], v[204:207], v[196:199], v[4:7]
	v_mfma_f32_16x16x32_bf16 v[0:3], v[212:215], v[196:199], v[0:3]
	s_setprio 0
	s_add_i32 s58, 0, 0x18000
	v_add_u32_e32 v158, s58, v145
	s_barrier
	ds_read_b128 v[140:143], v158
	ds_read_b128 v[150:153], v158 offset:1024
	ds_read_b128 v[154:157], v158 offset:2048
	ds_read_b128 v[158:161], v158 offset:3072
	s_add_u32 s22, s28, 0x100000
	s_addc_u32 s23, s29, 0
	s_mov_b32 m0, s36
	v_lshl_add_u64 v[200:201], s[22:23], 0, v[128:129]
	ds_read_b128 v[162:165], v148 offset:32768
	ds_read_b128 v[166:169], v148 offset:33792
	ds_read_b128 v[170:173], v148 offset:34816
	ds_read_b128 v[180:183], v148 offset:35840
	ds_read_b128 v[184:187], v148 offset:36864
	ds_read_b128 v[188:191], v148 offset:37888
	ds_read_b128 v[192:195], v148 offset:38912
	ds_read_b128 v[196:199], v148 offset:39936
	global_load_lds_dwordx4 v[200:201], off
	v_lshl_add_u64 v[200:201], s[22:23], 0, v[130:131]
	s_mov_b32 m0, s37
	s_nop 0
	global_load_lds_dwordx4 v[200:201], off
	s_waitcnt lgkmcnt(8)
	s_barrier
	s_waitcnt lgkmcnt(0)
	s_setprio 1
	s_waitcnt lgkmcnt(0)
	v_mfma_f32_16x16x32_bf16 v[124:127], v[140:143], v[162:165], v[124:127]
	v_mfma_f32_16x16x32_bf16 v[120:123], v[154:157], v[162:165], v[120:123]
	v_mfma_f32_16x16x32_bf16 v[108:111], v[140:143], v[170:173], v[108:111]
	v_mfma_f32_16x16x32_bf16 v[104:107], v[154:157], v[170:173], v[104:107]
	v_mfma_f32_16x16x32_bf16 v[92:95], v[140:143], v[184:187], v[92:95]
	v_mfma_f32_16x16x32_bf16 v[88:91], v[154:157], v[184:187], v[88:91]
	v_mfma_f32_16x16x32_bf16 v[76:79], v[140:143], v[192:195], v[76:79]
	v_mfma_f32_16x16x32_bf16 v[72:75], v[154:157], v[192:195], v[72:75]
	v_mfma_f32_16x16x32_bf16 v[124:127], v[150:153], v[166:169], v[124:127]
	v_mfma_f32_16x16x32_bf16 v[120:123], v[158:161], v[166:169], v[120:123]
	v_mfma_f32_16x16x32_bf16 v[108:111], v[150:153], v[180:183], v[108:111]
	v_mfma_f32_16x16x32_bf16 v[104:107], v[158:161], v[180:183], v[104:107]
	v_mfma_f32_16x16x32_bf16 v[92:95], v[150:153], v[188:191], v[92:95]
	v_mfma_f32_16x16x32_bf16 v[88:91], v[158:161], v[188:191], v[88:91]
	v_mfma_f32_16x16x32_bf16 v[76:79], v[150:153], v[196:199], v[76:79]
	v_mfma_f32_16x16x32_bf16 v[72:75], v[158:161], v[196:199], v[72:75]
	s_setprio 0
	s_barrier
	s_add_i32 s28, 0, 0x1c000
	s_add_i32 s22, s58, s3
	v_add_u32_e32 v174, s28, v145
	v_lshl_add_u64 v[176:177], v[176:177], 0, s[0:1]
	s_mov_b32 m0, s22
	ds_read_b128 v[200:203], v174
	ds_read_b128 v[204:207], v174 offset:1024
	ds_read_b128 v[208:211], v174 offset:2048
	ds_read_b128 v[212:215], v174 offset:3072
	global_load_lds_dwordx4 v[176:177], off
	v_lshl_add_u64 v[176:177], v[216:217], 0, s[0:1]
	s_add_i32 m0, s22, 0x2000
	s_nop 0
	global_load_lds_dwordx4 v[176:177], off
	s_barrier
	s_waitcnt lgkmcnt(0)
	s_setprio 1
	s_waitcnt lgkmcnt(0)
	v_mfma_f32_16x16x32_bf16 v[116:119], v[200:203], v[162:165], v[116:119]
	v_mfma_f32_16x16x32_bf16 v[112:115], v[208:211], v[162:165], v[112:115]
	v_mfma_f32_16x16x32_bf16 v[100:103], v[200:203], v[170:173], v[100:103]
	v_mfma_f32_16x16x32_bf16 v[96:99], v[208:211], v[170:173], v[96:99]
	v_mfma_f32_16x16x32_bf16 v[84:87], v[200:203], v[184:187], v[84:87]
	v_mfma_f32_16x16x32_bf16 v[80:83], v[208:211], v[184:187], v[80:83]
	v_mfma_f32_16x16x32_bf16 v[68:71], v[200:203], v[192:195], v[68:71]
	v_mfma_f32_16x16x32_bf16 v[64:67], v[208:211], v[192:195], v[64:67]
	v_mfma_f32_16x16x32_bf16 v[116:119], v[204:207], v[166:169], v[116:119]
	v_mfma_f32_16x16x32_bf16 v[112:115], v[212:215], v[166:169], v[112:115]
	v_mfma_f32_16x16x32_bf16 v[100:103], v[204:207], v[180:183], v[100:103]
	v_mfma_f32_16x16x32_bf16 v[96:99], v[212:215], v[180:183], v[96:99]
	v_mfma_f32_16x16x32_bf16 v[84:87], v[204:207], v[188:191], v[84:87]
	v_mfma_f32_16x16x32_bf16 v[80:83], v[212:215], v[188:191], v[80:83]
	v_mfma_f32_16x16x32_bf16 v[68:71], v[204:207], v[196:199], v[68:71]
	v_mfma_f32_16x16x32_bf16 v[64:67], v[212:215], v[196:199], v[64:67]
	s_setprio 0
	s_mov_b32 m0, s39
	v_lshl_add_u64 v[176:177], v[218:219], 0, s[0:1]
	s_barrier
	ds_read_b128 v[162:165], v148 offset:49152
	ds_read_b128 v[166:169], v148 offset:50176
	ds_read_b128 v[170:173], v148 offset:51200
	ds_read_b128 v[180:183], v148 offset:52224
	ds_read_b128 v[184:187], v148 offset:53248
	ds_read_b128 v[188:191], v148 offset:54272
	ds_read_b128 v[192:195], v148 offset:55296
	ds_read_b128 v[196:199], v148 offset:56320
	global_load_lds_dwordx4 v[176:177], off
	v_lshl_add_u64 v[176:177], v[220:221], 0, s[0:1]
	s_mov_b32 m0, s42
	s_nop 0
	global_load_lds_dwordx4 v[176:177], off
	s_barrier
; DI float sum_x16_x32(float x) { return sum_x32(sum_x16(x)); }
; #define PG8_BAR __builtin_amdgcn_s_barrier()
; template <class Epi>
; __device__ __forceinline__ void gemm_phase(LAS unsigned char* lds, const Gemm g, const StaticOrder& S, const Epi& E) {
;     ...
;             PG8_WAIT_V(6); PG8_BAR; PG8_MMA(1, 1, At, B1); PG8_BAR;
;             PG8_LDB(B0, 1, 0); PG8_SCHED; PG8_LDA(At, 1, 0); PG8_STAGE(PG8_SA(0, 1), a2 + hstep, voffA);
;             PG8_WAIT_L(8); PG8_BAR; PG8_WAIT_L(0); PG8_MMA(0, 0, At, B0); PG8_BAR; PG8_SCHED;
;             PG8_LDB(B1, 1, 1); PG8_STAGE(PG8_SB(1, 0), b3, voffB);
;             PG8_BAR; PG8_WAIT_L(0); PG8_MMA(0, 1, At, B1); PG8_BAR;
;             PG8_LDA(At, 1, 1); PG8_STAGE(PG8_SA(1, 0), a3, voffA);
;             PG8_BAR; PG8_WAIT_L(0); PG8_MMA(1, 0, At, B0); PG8_BAR; PG8_SCHED;
;             PG8_STAGE(PG8_SB(1, 1), b3 + hstep, voffB);
;             PG8_WAIT_V(6); PG8_BAR; PG8_MMA(1, 1, At, B1); PG8_BAR;
;     DI void operator()(const f32x4 (&acc)[2][2][4][2], const Unit& u, int wr, int wc, int fr, int fq) const {
;         const int row0 = u.pm * 256 + wr * 64 + fr, col0 = u.pn * 256 + wc * 32 + 4 * fq;
; #pragma unroll
;         for (int ai = 0; ai < 2; ++ai)
; #pragma unroll
;             for (int m = 0; m < 4; ++m) {
;                 const int r = row0 + ai * 128 + m * 16;
;                 const float* rp;
;                 if (MODE == 0) rp = x + (size_t)r * 1024;
;                 else rp = h + (size_t)r * 1024;
;                 float sq = 0.f;
; #pragma unroll
;                 for (int bj = 0; bj < 2; ++bj)
; #pragma unroll
;                     for (int n = 0; n < 2; ++n) {
;                         const int c = col0 + bj * 128 + n * 16;
;                         f32x4 rv = rp ? *(const f32x4*)(rp + c) : (f32x4){0.f, 0.f, 0.f, 0.f};
;                         f32x4 v = acc[ai][bj][m][n] + rv;
;                         *(f32x4*)(h + (size_t)r * 1024 + c) = v;
;                         if (WRITE_HB) {
;                             u32x2 w; w.x = pk2(v[0], v[1]); w.y = pk2(v[2], v[3]);
;                             *(u32x2*)(hb + (size_t)r * 1024 + c) = w;
;                         }
;                         sq += v[0] * v[0] + v[1] * v[1] + v[2] * v[2] + v[3] * v[3];
;                     }
;                 sq = sum_x16_x32(sq);
;                 if (fq == 0) atomicAdd(ss + r, sq);
;             }
	s_waitcnt lgkmcnt(0)
	s_setprio 1
	s_waitcnt lgkmcnt(0)
	v_mfma_f32_16x16x32_bf16 v[60:63], v[140:143], v[162:165], v[60:63]
	v_mfma_f32_16x16x32_bf16 v[56:59], v[154:157], v[162:165], v[56:59]
	v_mfma_f32_16x16x32_bf16 v[44:47], v[140:143], v[170:173], v[44:47]
	v_mfma_f32_16x16x32_bf16 v[40:43], v[154:157], v[170:173], v[40:43]
	v_mfma_f32_16x16x32_bf16 v[28:31], v[140:143], v[184:187], v[28:31]
	v_mfma_f32_16x16x32_bf16 v[24:27], v[154:157], v[184:187], v[24:27]
	v_mfma_f32_16x16x32_bf16 v[12:15], v[140:143], v[192:195], v[12:15]
	v_mfma_f32_16x16x32_bf16 v[8:11], v[154:157], v[192:195], v[8:11]
	v_mfma_f32_16x16x32_bf16 v[60:63], v[150:153], v[166:169], v[60:63]
	v_mfma_f32_16x16x32_bf16 v[56:59], v[158:161], v[166:169], v[56:59]
	v_mfma_f32_16x16x32_bf16 v[44:47], v[150:153], v[180:183], v[44:47]
	v_mfma_f32_16x16x32_bf16 v[40:43], v[158:161], v[180:183], v[40:43]
	v_mfma_f32_16x16x32_bf16 v[28:31], v[150:153], v[188:191], v[28:31]
	v_mfma_f32_16x16x32_bf16 v[24:27], v[158:161], v[188:191], v[24:27]
	v_mfma_f32_16x16x32_bf16 v[12:15], v[150:153], v[196:199], v[12:15]
	v_mfma_f32_16x16x32_bf16 v[8:11], v[158:161], v[196:199], v[8:11]
	s_setprio 0
	s_barrier
	s_add_u32 s22, s26, 0x100080
	s_addc_u32 s23, s27, 0
	s_add_i32 s26, s28, s3
	v_lshl_add_u64 v[140:141], s[22:23], 0, v[128:129]
	s_mov_b32 m0, s26
	s_nop 0
	global_load_lds_dwordx4 v[140:141], off
	v_lshl_add_u64 v[140:141], s[22:23], 0, v[130:131]
	s_add_i32 m0, s26, 0x2000
	s_nop 0
	global_load_lds_dwordx4 v[140:141], off
	s_waitcnt vmcnt(6)
	s_barrier
	s_setprio 1
	v_mfma_f32_16x16x32_bf16 v[52:55], v[200:203], v[162:165], v[52:55]
	v_mfma_f32_16x16x32_bf16 v[48:51], v[208:211], v[162:165], v[48:51]
	v_mfma_f32_16x16x32_bf16 v[36:39], v[200:203], v[170:173], v[36:39]
	v_mfma_f32_16x16x32_bf16 v[32:35], v[208:211], v[170:173], v[32:35]
	v_mfma_f32_16x16x32_bf16 v[20:23], v[200:203], v[184:187], v[20:23]
	v_mfma_f32_16x16x32_bf16 v[16:19], v[208:211], v[184:187], v[16:19]
	v_mfma_f32_16x16x32_bf16 v[4:7], v[200:203], v[192:195], v[4:7]
	v_mfma_f32_16x16x32_bf16 v[0:3], v[208:211], v[192:195], v[0:3]
	v_mfma_f32_16x16x32_bf16 v[52:55], v[204:207], v[166:169], v[52:55]
	v_mfma_f32_16x16x32_bf16 v[48:51], v[212:215], v[166:169], v[48:51]
	v_mfma_f32_16x16x32_bf16 v[36:39], v[204:207], v[180:183], v[36:39]
	v_mfma_f32_16x16x32_bf16 v[32:35], v[212:215], v[180:183], v[32:35]
	v_mfma_f32_16x16x32_bf16 v[20:23], v[204:207], v[188:191], v[20:23]
	v_mfma_f32_16x16x32_bf16 v[16:19], v[212:215], v[188:191], v[16:19]
	v_mfma_f32_16x16x32_bf16 v[4:7], v[204:207], v[196:199], v[4:7]
	v_mfma_f32_16x16x32_bf16 v[0:3], v[212:215], v[196:199], v[0:3]
	s_setprio 0
	s_add_i32 s57, s57, 2
	s_add_u32 s51, s51, 0x100
	s_addc_u32 s56, s56, 0
	s_cmp_gt_u32 s57, 61
	s_mov_b64 s[22:23], s[24:25]
	s_barrier
	s_cbranch_scc0 .LBB0_1008
	v_lshl_add_u32 v142, s18, 8, v144
	v_ashrrev_i32_e32 v143, 31, v142
	v_lshl_or_b32 v140, s20, 8, v146
	v_lshlrev_b64 v[150:151], 12, v[142:143]
	v_lshl_add_u64 v[150:151], s[66:67], 0, v[150:151]
	v_ashrrev_i32_e32 v141, 31, v140
	v_lshl_add_u64 v[154:155], v[140:141], 2, v[150:151]
	s_mov_b64 s[98:99], 0x10000
	s_mov_b64 s[100:101], 0x80000
	v_mov_b64_e32 v[196:197], v[154:155]
	v_lshl_add_u64 v[200:201], v[154:155], 0, s[100:101]
	v_lshl_add_u64 v[198:199], v[154:155], 0, s[98:99]
	global_load_dwordx4 v[180:183], v[154:155], off
	global_load_dwordx4 v[184:187], v[154:155], off offset:64
	global_load_dwordx4 v[188:191], v[154:155], off offset:512
	global_load_dwordx4 v[192:195], v[154:155], off offset:576
	global_load_dwordx4 v[212:215], v[198:199], off
	global_load_dwordx4 v[216:219], v[198:199], off offset:64
	global_load_dwordx4 v[220:223], v[198:199], off offset:512
	global_load_dwordx4 v[224:227], v[198:199], off offset:576
	v_lshlrev_b64 v[156:157], 11, v[142:143]
	v_lshl_add_u64 v[156:157], s[68:69], 0, v[156:157]
	v_lshl_add_u64 v[156:157], v[140:141], 1, v[156:157]
	s_waitcnt vmcnt(7)
	v_pk_add_f32 v[126:127], v[126:127], v[182:183]
	v_pk_add_f32 v[124:125], v[124:125], v[180:181]
	v_cvt_pk_bf16_f32 v151, v126, v127
	v_cvt_pk_bf16_f32 v150, v124, v125
	global_store_dwordx4 v[154:155], v[124:127], off
	global_store_dwordx2 v[156:157], v[150:151], off
	s_nop 0
	v_mul_f32_e32 v125, v125, v125
	v_fmac_f32_e32 v125, v124, v124
	v_fmac_f32_e32 v125, v126, v126
	v_fmac_f32_e32 v125, v127, v127
	s_waitcnt vmcnt(8)
	v_pk_add_f32 v[122:123], v[122:123], v[186:187]
	v_pk_add_f32 v[120:121], v[120:121], v[184:185]
	v_cvt_pk_bf16_f32 v151, v122, v123
	v_cvt_pk_bf16_f32 v150, v120, v121
	global_store_dwordx4 v[154:155], v[120:123], off offset:64
	global_store_dwordx2 v[156:157], v[150:151], off offset:32
	s_nop 0
	v_mul_f32_e32 v121, v121, v121
	v_fmac_f32_e32 v121, v120, v120
	v_fmac_f32_e32 v121, v122, v122
	v_fmac_f32_e32 v121, v123, v123
	v_add_f32_e32 v120, v125, v121
	s_waitcnt vmcnt(9)
	v_pk_add_f32 v[118:119], v[118:119], v[190:191]
	v_pk_add_f32 v[116:117], v[116:117], v[188:189]
	v_cvt_pk_bf16_f32 v151, v118, v119
	v_cvt_pk_bf16_f32 v150, v116, v117
	global_store_dwordx4 v[154:155], v[116:119], off offset:512
	global_store_dwordx2 v[156:157], v[150:151], off offset:256
	s_nop 0
	v_mul_f32_e32 v117, v117, v117
	v_fmac_f32_e32 v117, v116, v116
	v_fmac_f32_e32 v117, v118, v118
	v_fmac_f32_e32 v117, v119, v119
	v_add_f32_e32 v118, v120, v117
	s_waitcnt vmcnt(10)
	v_pk_add_f32 v[114:115], v[114:115], v[194:195]
	v_pk_add_f32 v[112:113], v[112:113], v[192:193]
	global_store_dwordx4 v[154:155], v[112:115], off offset:576
	v_cvt_pk_bf16_f32 v116, v112, v113
	v_cvt_pk_bf16_f32 v117, v114, v115
	v_mul_f32_e32 v113, v113, v113
	v_fmac_f32_e32 v113, v112, v112
	v_fmac_f32_e32 v113, v114, v114
	v_fmac_f32_e32 v113, v115, v115
	v_add_f32_e32 v112, v118, v113
	v_mov_b32_e32 v113, v112
	s_nop 1
	v_permlane16_swap_b32_e32 v112, v113
	v_add_f32_e32 v112, v112, v113
	v_mov_b32_e32 v113, v112
	s_nop 1
	v_permlane32_swap_b32_e32 v112, v113
	global_store_dwordx2 v[156:157], v[116:117], off offset:288
	s_and_saveexec_b64 s[18:19], s[4:5]
	s_cbranch_execz .LBB0_1011
	v_lshl_add_u64 v[114:115], v[142:143], 2, s[44:45]
	v_add_f32_e32 v112, v112, v113
	global_atomic_add_f32 v[114:115], v112, off
; DI unsigned pk2(float a, float b) { f32x2 v = {a, b}; hbf2 r = __builtin_convertvector(v, hbf2); return __builtin_bit_cast(unsigned, r); }
; DI float sum_x16_x32(float x) { return sum_x32(sum_x16(x)); }
;     DI void operator()(const f32x4 (&acc)[2][2][4][2], const Unit& u, int wr, int wc, int fr, int fq) const {
;     ...
; #pragma unroll
;         for (int ai = 0; ai < 2; ++ai)
; #pragma unroll
;             for (int m = 0; m < 4; ++m) {
;                 const int r = row0 + ai * 128 + m * 16;
;                 const float* rp;
;                 if (MODE == 0) rp = x + (size_t)r * 1024;
;                 else rp = h + (size_t)r * 1024;
;                 float sq = 0.f;
; #pragma unroll
;                 for (int bj = 0; bj < 2; ++bj)
; #pragma unroll
;                     for (int n = 0; n < 2; ++n) {
;                         const int c = col0 + bj * 128 + n * 16;
;                         f32x4 rv = rp ? *(const f32x4*)(rp + c) : (f32x4){0.f, 0.f, 0.f, 0.f};
;                         f32x4 v = acc[ai][bj][m][n] + rv;
;                         *(f32x4*)(h + (size_t)r * 1024 + c) = v;
;                         if (WRITE_HB) {
;                             u32x2 w; w.x = pk2(v[0], v[1]); w.y = pk2(v[2], v[3]);
;                             *(u32x2*)(hb + (size_t)r * 1024 + c) = w;
;                         }
;                         sq += v[0] * v[0] + v[1] * v[1] + v[2] * v[2] + v[3] * v[3];
;                     }
;                 sq = sum_x16_x32(sq);
;                 if (fq == 0) atomicAdd(ss + r, sq);
;             }
.LBB0_1011:
	s_or_b64 exec, exec, s[18:19]
	v_or_b32_e32 v112, 16, v142
	v_ashrrev_i32_e32 v113, 31, v112
	v_lshlrev_b64 v[114:115], 12, v[112:113]
	v_lshl_add_u64 v[114:115], s[66:67], 0, v[114:115]
	v_lshl_add_u64 v[118:119], v[140:141], 2, v[114:115]
	v_lshl_add_u64 v[198:199], v[198:199], 0, s[98:99]
	global_load_dwordx4 v[180:183], v[198:199], off
	global_load_dwordx4 v[184:187], v[198:199], off offset:64
	global_load_dwordx4 v[188:191], v[198:199], off offset:512
	global_load_dwordx4 v[192:195], v[198:199], off offset:576
	v_lshlrev_b64 v[120:121], 11, v[112:113]
	v_lshl_add_u64 v[120:121], s[68:69], 0, v[120:121]
	v_lshl_add_u64 v[120:121], v[140:141], 1, v[120:121]
	s_waitcnt vmcnt(15)
	v_pk_add_f32 v[110:111], v[110:111], v[214:215]
	v_pk_add_f32 v[108:109], v[108:109], v[212:213]
	v_cvt_pk_bf16_f32 v115, v110, v111
	v_cvt_pk_bf16_f32 v114, v108, v109
	global_store_dwordx4 v[118:119], v[108:111], off
	global_store_dwordx2 v[120:121], v[114:115], off
	s_nop 0
	v_mul_f32_e32 v109, v109, v109
	v_fmac_f32_e32 v109, v108, v108
	v_fmac_f32_e32 v109, v110, v110
	v_fmac_f32_e32 v109, v111, v111
	s_waitcnt vmcnt(16)
	v_pk_add_f32 v[106:107], v[106:107], v[218:219]
	v_pk_add_f32 v[104:105], v[104:105], v[216:217]
	v_cvt_pk_bf16_f32 v115, v106, v107
	v_cvt_pk_bf16_f32 v114, v104, v105
	global_store_dwordx4 v[118:119], v[104:107], off offset:64
	global_store_dwordx2 v[120:121], v[114:115], off offset:32
	s_nop 0
	v_mul_f32_e32 v105, v105, v105
	v_fmac_f32_e32 v105, v104, v104
	v_fmac_f32_e32 v105, v106, v106
	v_fmac_f32_e32 v105, v107, v107
	v_add_f32_e32 v104, v109, v105
	s_waitcnt vmcnt(17)
	v_pk_add_f32 v[102:103], v[102:103], v[222:223]
	v_pk_add_f32 v[100:101], v[100:101], v[220:221]
	v_cvt_pk_bf16_f32 v115, v102, v103
	v_cvt_pk_bf16_f32 v114, v100, v101
	global_store_dwordx4 v[118:119], v[100:103], off offset:512
	global_store_dwordx2 v[120:121], v[114:115], off offset:256
	s_nop 0
	v_mul_f32_e32 v101, v101, v101
	v_fmac_f32_e32 v101, v100, v100
	v_fmac_f32_e32 v101, v102, v102
	v_fmac_f32_e32 v101, v103, v103
	v_add_f32_e32 v102, v104, v101
	s_waitcnt vmcnt(18)
	v_pk_add_f32 v[98:99], v[98:99], v[226:227]
	v_pk_add_f32 v[96:97], v[96:97], v[224:225]
	global_store_dwordx4 v[118:119], v[96:99], off offset:576
	v_cvt_pk_bf16_f32 v100, v96, v97
	v_cvt_pk_bf16_f32 v101, v98, v99
	v_mul_f32_e32 v97, v97, v97
	v_fmac_f32_e32 v97, v96, v96
	v_fmac_f32_e32 v97, v98, v98
	v_fmac_f32_e32 v97, v99, v99
	v_add_f32_e32 v96, v102, v97
	v_mov_b32_e32 v97, v96
	s_nop 1
	v_permlane16_swap_b32_e32 v96, v97
	v_add_f32_e32 v96, v96, v97
	v_mov_b32_e32 v97, v96
	s_nop 1
	v_permlane32_swap_b32_e32 v96, v97
	global_store_dwordx2 v[120:121], v[100:101], off offset:288
	s_and_saveexec_b64 s[18:19], s[4:5]
	s_cbranch_execz .LBB0_1013
	v_lshl_add_u64 v[98:99], v[112:113], 2, s[44:45]
	v_add_f32_e32 v96, v96, v97
	global_atomic_add_f32 v[98:99], v96, off
.LBB0_1013:
	s_or_b64 exec, exec, s[18:19]
	v_or_b32_e32 v96, 32, v142
	v_ashrrev_i32_e32 v97, 31, v96
	v_lshlrev_b64 v[98:99], 12, v[96:97]
	v_lshl_add_u64 v[98:99], s[66:67], 0, v[98:99]
	v_lshl_add_u64 v[102:103], v[140:141], 2, v[98:99]
	v_lshl_add_u64 v[198:199], v[198:199], 0, s[98:99]
	global_load_dwordx4 v[212:215], v[198:199], off
	global_load_dwordx4 v[216:219], v[198:199], off offset:64
	global_load_dwordx4 v[220:223], v[198:199], off offset:512
	global_load_dwordx4 v[224:227], v[198:199], off offset:576
	v_lshlrev_b64 v[104:105], 11, v[96:97]
	v_lshl_add_u64 v[104:105], s[68:69], 0, v[104:105]
	v_lshl_add_u64 v[104:105], v[140:141], 1, v[104:105]
	s_waitcnt vmcnt(15)
	v_pk_add_f32 v[94:95], v[94:95], v[182:183]
	v_pk_add_f32 v[92:93], v[92:93], v[180:181]
	v_cvt_pk_bf16_f32 v99, v94, v95
	v_cvt_pk_bf16_f32 v98, v92, v93
	global_store_dwordx4 v[102:103], v[92:95], off
	global_store_dwordx2 v[104:105], v[98:99], off
	s_nop 0
	v_mul_f32_e32 v93, v93, v93
	v_fmac_f32_e32 v93, v92, v92
	v_fmac_f32_e32 v93, v94, v94
	v_fmac_f32_e32 v93, v95, v95
	s_waitcnt vmcnt(16)
	v_pk_add_f32 v[90:91], v[90:91], v[186:187]
	v_pk_add_f32 v[88:89], v[88:89], v[184:185]
	v_cvt_pk_bf16_f32 v99, v90, v91
	v_cvt_pk_bf16_f32 v98, v88, v89
	global_store_dwordx4 v[102:103], v[88:91], off offset:64
	global_store_dwordx2 v[104:105], v[98:99], off offset:32
	s_nop 0
	v_mul_f32_e32 v89, v89, v89
	v_fmac_f32_e32 v89, v88, v88
	v_fmac_f32_e32 v89, v90, v90
	v_fmac_f32_e32 v89, v91, v91
	v_add_f32_e32 v88, v93, v89
	s_waitcnt vmcnt(17)
	v_pk_add_f32 v[86:87], v[86:87], v[190:191]
	v_pk_add_f32 v[84:85], v[84:85], v[188:189]
	v_cvt_pk_bf16_f32 v99, v86, v87
	v_cvt_pk_bf16_f32 v98, v84, v85
	global_store_dwordx4 v[102:103], v[84:87], off offset:512
	global_store_dwordx2 v[104:105], v[98:99], off offset:256
	s_nop 0
	v_mul_f32_e32 v85, v85, v85
	v_fmac_f32_e32 v85, v84, v84
	v_fmac_f32_e32 v85, v86, v86
	v_fmac_f32_e32 v85, v87, v87
	v_add_f32_e32 v86, v88, v85
	s_waitcnt vmcnt(18)
	v_pk_add_f32 v[82:83], v[82:83], v[194:195]
	v_pk_add_f32 v[80:81], v[80:81], v[192:193]
	global_store_dwordx4 v[102:103], v[80:83], off offset:576
	v_cvt_pk_bf16_f32 v84, v80, v81
	v_cvt_pk_bf16_f32 v85, v82, v83
	v_mul_f32_e32 v81, v81, v81
	v_fmac_f32_e32 v81, v80, v80
	v_fmac_f32_e32 v81, v82, v82
	v_fmac_f32_e32 v81, v83, v83
	v_add_f32_e32 v80, v86, v81
	v_mov_b32_e32 v81, v80
	s_nop 1
	v_permlane16_swap_b32_e32 v80, v81
	v_add_f32_e32 v80, v80, v81
	v_mov_b32_e32 v81, v80
	s_nop 1
	v_permlane32_swap_b32_e32 v80, v81
	global_store_dwordx2 v[104:105], v[84:85], off offset:288
	s_and_saveexec_b64 s[18:19], s[4:5]
	s_cbranch_execz .LBB0_1015
	v_lshl_add_u64 v[82:83], v[96:97], 2, s[44:45]
	v_add_f32_e32 v80, v80, v81
	global_atomic_add_f32 v[82:83], v80, off
; DI unsigned pk2(float a, float b) { f32x2 v = {a, b}; hbf2 r = __builtin_convertvector(v, hbf2); return __builtin_bit_cast(unsigned, r); }
; DI float sum_x16_x32(float x) { return sum_x32(sum_x16(x)); }
;     DI void operator()(const f32x4 (&acc)[2][2][4][2], const Unit& u, int wr, int wc, int fr, int fq) const {
;     ...
; #pragma unroll
;         for (int ai = 0; ai < 2; ++ai)
; #pragma unroll
;             for (int m = 0; m < 4; ++m) {
;                 const int r = row0 + ai * 128 + m * 16;
;                 const float* rp;
;                 if (MODE == 0) rp = x + (size_t)r * 1024;
;                 else rp = h + (size_t)r * 1024;
;                 float sq = 0.f;
; #pragma unroll
;                 for (int bj = 0; bj < 2; ++bj)
; #pragma unroll
;                     for (int n = 0; n < 2; ++n) {
;                         const int c = col0 + bj * 128 + n * 16;
;                         f32x4 rv = rp ? *(const f32x4*)(rp + c) : (f32x4){0.f, 0.f, 0.f, 0.f};
;                         f32x4 v = acc[ai][bj][m][n] + rv;
;                         *(f32x4*)(h + (size_t)r * 1024 + c) = v;
;                         if (WRITE_HB) {
;                             u32x2 w; w.x = pk2(v[0], v[1]); w.y = pk2(v[2], v[3]);
;                             *(u32x2*)(hb + (size_t)r * 1024 + c) = w;
;                         }
;                         sq += v[0] * v[0] + v[1] * v[1] + v[2] * v[2] + v[3] * v[3];
;                     }
;                 sq = sum_x16_x32(sq);
;                 if (fq == 0) atomicAdd(ss + r, sq);
;             }
.LBB0_1015:
	s_or_b64 exec, exec, s[18:19]
	v_or_b32_e32 v80, 48, v142
	v_ashrrev_i32_e32 v81, 31, v80
	v_lshlrev_b64 v[82:83], 12, v[80:81]
	v_lshl_add_u64 v[82:83], s[66:67], 0, v[82:83]
	v_lshl_add_u64 v[86:87], v[140:141], 2, v[82:83]
	v_mov_b64_e32 v[198:199], v[200:201]
	global_load_dwordx4 v[180:183], v[198:199], off
	global_load_dwordx4 v[184:187], v[198:199], off offset:64
	global_load_dwordx4 v[188:191], v[198:199], off offset:512
	global_load_dwordx4 v[192:195], v[198:199], off offset:576
	v_lshlrev_b64 v[88:89], 11, v[80:81]
	v_lshl_add_u64 v[88:89], s[68:69], 0, v[88:89]
	v_lshl_add_u64 v[88:89], v[140:141], 1, v[88:89]
	s_waitcnt vmcnt(15)
	v_pk_add_f32 v[78:79], v[78:79], v[214:215]
	v_pk_add_f32 v[76:77], v[76:77], v[212:213]
	v_cvt_pk_bf16_f32 v83, v78, v79
	v_cvt_pk_bf16_f32 v82, v76, v77
	global_store_dwordx4 v[86:87], v[76:79], off
	global_store_dwordx2 v[88:89], v[82:83], off
	s_nop 0
	v_mul_f32_e32 v77, v77, v77
	v_fmac_f32_e32 v77, v76, v76
	v_fmac_f32_e32 v77, v78, v78
	v_fmac_f32_e32 v77, v79, v79
	s_waitcnt vmcnt(16)
	v_pk_add_f32 v[74:75], v[74:75], v[218:219]
	v_pk_add_f32 v[72:73], v[72:73], v[216:217]
	v_cvt_pk_bf16_f32 v83, v74, v75
	v_cvt_pk_bf16_f32 v82, v72, v73
	global_store_dwordx4 v[86:87], v[72:75], off offset:64
	global_store_dwordx2 v[88:89], v[82:83], off offset:32
	s_nop 0
	v_mul_f32_e32 v73, v73, v73
	v_fmac_f32_e32 v73, v72, v72
	v_fmac_f32_e32 v73, v74, v74
	v_fmac_f32_e32 v73, v75, v75
	v_add_f32_e32 v72, v77, v73
	s_waitcnt vmcnt(17)
	v_pk_add_f32 v[70:71], v[70:71], v[222:223]
	v_pk_add_f32 v[68:69], v[68:69], v[220:221]
	v_cvt_pk_bf16_f32 v83, v70, v71
	v_cvt_pk_bf16_f32 v82, v68, v69
	global_store_dwordx4 v[86:87], v[68:71], off offset:512
	global_store_dwordx2 v[88:89], v[82:83], off offset:256
	s_nop 0
	v_mul_f32_e32 v69, v69, v69
	v_fmac_f32_e32 v69, v68, v68
	v_fmac_f32_e32 v69, v70, v70
	v_fmac_f32_e32 v69, v71, v71
	v_add_f32_e32 v70, v72, v69
	s_waitcnt vmcnt(18)
	v_pk_add_f32 v[66:67], v[66:67], v[226:227]
	v_pk_add_f32 v[64:65], v[64:65], v[224:225]
	global_store_dwordx4 v[86:87], v[64:67], off offset:576
	v_cvt_pk_bf16_f32 v68, v64, v65
	v_cvt_pk_bf16_f32 v69, v66, v67
	v_mul_f32_e32 v65, v65, v65
	v_fmac_f32_e32 v65, v64, v64
	v_fmac_f32_e32 v65, v66, v66
	v_fmac_f32_e32 v65, v67, v67
	v_add_f32_e32 v64, v70, v65
	v_mov_b32_e32 v65, v64
	s_nop 1
	v_permlane16_swap_b32_e32 v64, v65
	v_add_f32_e32 v64, v64, v65
	v_mov_b32_e32 v65, v64
	s_nop 1
	v_permlane32_swap_b32_e32 v64, v65
	global_store_dwordx2 v[88:89], v[68:69], off offset:288
	s_and_saveexec_b64 s[18:19], s[4:5]
	s_cbranch_execz .LBB0_1017
	v_lshl_add_u64 v[66:67], v[80:81], 2, s[44:45]
	v_add_f32_e32 v64, v64, v65
	global_atomic_add_f32 v[66:67], v64, off
.LBB0_1017:
	s_or_b64 exec, exec, s[18:19]
	v_add_u32_e32 v64, 0x80, v142
	v_ashrrev_i32_e32 v65, 31, v64
	v_lshlrev_b64 v[66:67], 12, v[64:65]
	v_lshl_add_u64 v[66:67], s[66:67], 0, v[66:67]
	v_lshl_add_u64 v[70:71], v[140:141], 2, v[66:67]
	v_lshl_add_u64 v[198:199], v[198:199], 0, s[98:99]
	global_load_dwordx4 v[212:215], v[198:199], off
	global_load_dwordx4 v[216:219], v[198:199], off offset:64
	global_load_dwordx4 v[220:223], v[198:199], off offset:512
	global_load_dwordx4 v[224:227], v[198:199], off offset:576
	v_lshlrev_b64 v[72:73], 11, v[64:65]
	v_lshl_add_u64 v[72:73], s[68:69], 0, v[72:73]
	v_lshl_add_u64 v[72:73], v[140:141], 1, v[72:73]
	s_waitcnt vmcnt(15)
	v_pk_add_f32 v[62:63], v[62:63], v[182:183]
	v_pk_add_f32 v[60:61], v[60:61], v[180:181]
	v_cvt_pk_bf16_f32 v67, v62, v63
	v_cvt_pk_bf16_f32 v66, v60, v61
	global_store_dwordx4 v[70:71], v[60:63], off
	global_store_dwordx2 v[72:73], v[66:67], off
	s_nop 0
	v_mul_f32_e32 v61, v61, v61
	v_fmac_f32_e32 v61, v60, v60
	v_fmac_f32_e32 v61, v62, v62
	v_fmac_f32_e32 v61, v63, v63
	s_waitcnt vmcnt(16)
	v_pk_add_f32 v[58:59], v[58:59], v[186:187]
	v_pk_add_f32 v[56:57], v[56:57], v[184:185]
	v_cvt_pk_bf16_f32 v67, v58, v59
	v_cvt_pk_bf16_f32 v66, v56, v57
	global_store_dwordx4 v[70:71], v[56:59], off offset:64
	global_store_dwordx2 v[72:73], v[66:67], off offset:32
	s_nop 0
	v_mul_f32_e32 v57, v57, v57
	v_fmac_f32_e32 v57, v56, v56
	v_fmac_f32_e32 v57, v58, v58
	v_fmac_f32_e32 v57, v59, v59
	v_add_f32_e32 v56, v61, v57
	s_waitcnt vmcnt(17)
	v_pk_add_f32 v[54:55], v[54:55], v[190:191]
	v_pk_add_f32 v[52:53], v[52:53], v[188:189]
	v_cvt_pk_bf16_f32 v67, v54, v55
	v_cvt_pk_bf16_f32 v66, v52, v53
	global_store_dwordx4 v[70:71], v[52:55], off offset:512
	global_store_dwordx2 v[72:73], v[66:67], off offset:256
	s_nop 0
	v_mul_f32_e32 v53, v53, v53
	v_fmac_f32_e32 v53, v52, v52
	v_fmac_f32_e32 v53, v54, v54
	v_fmac_f32_e32 v53, v55, v55
	v_add_f32_e32 v54, v56, v53
	s_waitcnt vmcnt(18)
	v_pk_add_f32 v[50:51], v[50:51], v[194:195]
	v_pk_add_f32 v[48:49], v[48:49], v[192:193]
	global_store_dwordx4 v[70:71], v[48:51], off offset:576
	v_cvt_pk_bf16_f32 v52, v48, v49
	v_cvt_pk_bf16_f32 v53, v50, v51
	v_mul_f32_e32 v49, v49, v49
	v_fmac_f32_e32 v49, v48, v48
	v_fmac_f32_e32 v49, v50, v50
	v_fmac_f32_e32 v49, v51, v51
	v_add_f32_e32 v48, v54, v49
	v_mov_b32_e32 v49, v48
	s_nop 1
	v_permlane16_swap_b32_e32 v48, v49
	v_add_f32_e32 v48, v48, v49
	v_mov_b32_e32 v49, v48
	s_nop 1
	v_permlane32_swap_b32_e32 v48, v49
	global_store_dwordx2 v[72:73], v[52:53], off offset:288
	s_and_saveexec_b64 s[18:19], s[4:5]
	s_cbranch_execz .LBB0_1019
	v_lshl_add_u64 v[50:51], v[64:65], 2, s[44:45]
	v_add_f32_e32 v48, v48, v49
	global_atomic_add_f32 v[50:51], v48, off
; DI unsigned pk2(float a, float b) { f32x2 v = {a, b}; hbf2 r = __builtin_convertvector(v, hbf2); return __builtin_bit_cast(unsigned, r); }
; DI float sum_x16_x32(float x) { return sum_x32(sum_x16(x)); }
;     DI void operator()(const f32x4 (&acc)[2][2][4][2], const Unit& u, int wr, int wc, int fr, int fq) const {
;     ...
; #pragma unroll
;         for (int ai = 0; ai < 2; ++ai)
; #pragma unroll
;             for (int m = 0; m < 4; ++m) {
;                 const int r = row0 + ai * 128 + m * 16;
;                 const float* rp;
;                 if (MODE == 0) rp = x + (size_t)r * 1024;
;                 else rp = h + (size_t)r * 1024;
;                 float sq = 0.f;
; #pragma unroll
;                 for (int bj = 0; bj < 2; ++bj)
; #pragma unroll
;                     for (int n = 0; n < 2; ++n) {
;                         const int c = col0 + bj * 128 + n * 16;
;                         f32x4 rv = rp ? *(const f32x4*)(rp + c) : (f32x4){0.f, 0.f, 0.f, 0.f};
;                         f32x4 v = acc[ai][bj][m][n] + rv;
;                         *(f32x4*)(h + (size_t)r * 1024 + c) = v;
;                         if (WRITE_HB) {
;                             u32x2 w; w.x = pk2(v[0], v[1]); w.y = pk2(v[2], v[3]);
;                             *(u32x2*)(hb + (size_t)r * 1024 + c) = w;
;                         }
;                         sq += v[0] * v[0] + v[1] * v[1] + v[2] * v[2] + v[3] * v[3];
;                     }
;                 sq = sum_x16_x32(sq);
;                 if (fq == 0) atomicAdd(ss + r, sq);
;             }
.LBB0_1019:
	s_or_b64 exec, exec, s[18:19]
	v_add_u32_e32 v48, 0x90, v142
	v_ashrrev_i32_e32 v49, 31, v48
	v_lshlrev_b64 v[50:51], 12, v[48:49]
	v_lshl_add_u64 v[50:51], s[66:67], 0, v[50:51]
	v_lshl_add_u64 v[54:55], v[140:141], 2, v[50:51]
	v_lshl_add_u64 v[198:199], v[198:199], 0, s[98:99]
	global_load_dwordx4 v[180:183], v[198:199], off
	global_load_dwordx4 v[184:187], v[198:199], off offset:64
	global_load_dwordx4 v[188:191], v[198:199], off offset:512
	global_load_dwordx4 v[192:195], v[198:199], off offset:576
	v_lshlrev_b64 v[56:57], 11, v[48:49]
	v_lshl_add_u64 v[56:57], s[68:69], 0, v[56:57]
	v_lshl_add_u64 v[56:57], v[140:141], 1, v[56:57]
	s_waitcnt vmcnt(15)
	v_pk_add_f32 v[46:47], v[46:47], v[214:215]
	v_pk_add_f32 v[44:45], v[44:45], v[212:213]
	v_cvt_pk_bf16_f32 v51, v46, v47
	v_cvt_pk_bf16_f32 v50, v44, v45
	global_store_dwordx4 v[54:55], v[44:47], off
	global_store_dwordx2 v[56:57], v[50:51], off
	s_nop 0
	v_mul_f32_e32 v45, v45, v45
	v_fmac_f32_e32 v45, v44, v44
	v_fmac_f32_e32 v45, v46, v46
	v_fmac_f32_e32 v45, v47, v47
	s_waitcnt vmcnt(16)
	v_pk_add_f32 v[42:43], v[42:43], v[218:219]
	v_pk_add_f32 v[40:41], v[40:41], v[216:217]
	v_cvt_pk_bf16_f32 v51, v42, v43
	v_cvt_pk_bf16_f32 v50, v40, v41
	global_store_dwordx4 v[54:55], v[40:43], off offset:64
	global_store_dwordx2 v[56:57], v[50:51], off offset:32
	s_nop 0
	v_mul_f32_e32 v41, v41, v41
	v_fmac_f32_e32 v41, v40, v40
	v_fmac_f32_e32 v41, v42, v42
	v_fmac_f32_e32 v41, v43, v43
	v_add_f32_e32 v40, v45, v41
	s_waitcnt vmcnt(17)
	v_pk_add_f32 v[38:39], v[38:39], v[222:223]
	v_pk_add_f32 v[36:37], v[36:37], v[220:221]
	v_cvt_pk_bf16_f32 v51, v38, v39
	v_cvt_pk_bf16_f32 v50, v36, v37
	global_store_dwordx4 v[54:55], v[36:39], off offset:512
	global_store_dwordx2 v[56:57], v[50:51], off offset:256
	s_nop 0
	v_mul_f32_e32 v37, v37, v37
	v_fmac_f32_e32 v37, v36, v36
	v_fmac_f32_e32 v37, v38, v38
	v_fmac_f32_e32 v37, v39, v39
	v_add_f32_e32 v38, v40, v37
	s_waitcnt vmcnt(18)
	v_pk_add_f32 v[34:35], v[34:35], v[226:227]
	v_pk_add_f32 v[32:33], v[32:33], v[224:225]
	global_store_dwordx4 v[54:55], v[32:35], off offset:576
	v_cvt_pk_bf16_f32 v36, v32, v33
	v_cvt_pk_bf16_f32 v37, v34, v35
	v_mul_f32_e32 v33, v33, v33
	v_fmac_f32_e32 v33, v32, v32
	v_fmac_f32_e32 v33, v34, v34
	v_fmac_f32_e32 v33, v35, v35
	v_add_f32_e32 v32, v38, v33
	v_mov_b32_e32 v33, v32
	s_nop 1
	v_permlane16_swap_b32_e32 v32, v33
	v_add_f32_e32 v32, v32, v33
	v_mov_b32_e32 v33, v32
	s_nop 1
	v_permlane32_swap_b32_e32 v32, v33
	global_store_dwordx2 v[56:57], v[36:37], off offset:288
	s_and_saveexec_b64 s[18:19], s[4:5]
	s_cbranch_execz .LBB0_1021
	v_lshl_add_u64 v[34:35], v[48:49], 2, s[44:45]
	v_add_f32_e32 v32, v32, v33
	global_atomic_add_f32 v[34:35], v32, off
; DI unsigned pk2(float a, float b) { f32x2 v = {a, b}; hbf2 r = __builtin_convertvector(v, hbf2); return __builtin_bit_cast(unsigned, r); }
; DI float sum_x16_x32(float x) { return sum_x32(sum_x16(x)); }
;     DI void operator()(const f32x4 (&acc)[2][2][4][2], const Unit& u, int wr, int wc, int fr, int fq) const {
;     ...
; #pragma unroll
;         for (int ai = 0; ai < 2; ++ai)
; #pragma unroll
;             for (int m = 0; m < 4; ++m) {
;                 const int r = row0 + ai * 128 + m * 16;
;                 const float* rp;
;                 if (MODE == 0) rp = x + (size_t)r * 1024;
;                 else rp = h + (size_t)r * 1024;
;                 float sq = 0.f;
; #pragma unroll
;                 for (int bj = 0; bj < 2; ++bj)
; #pragma unroll
;                     for (int n = 0; n < 2; ++n) {
;                         const int c = col0 + bj * 128 + n * 16;
;                         f32x4 rv = rp ? *(const f32x4*)(rp + c) : (f32x4){0.f, 0.f, 0.f, 0.f};
;                         f32x4 v = acc[ai][bj][m][n] + rv;
;                         *(f32x4*)(h + (size_t)r * 1024 + c) = v;
;                         if (WRITE_HB) {
;                             u32x2 w; w.x = pk2(v[0], v[1]); w.y = pk2(v[2], v[3]);
;                             *(u32x2*)(hb + (size_t)r * 1024 + c) = w;
;                         }
;                         sq += v[0] * v[0] + v[1] * v[1] + v[2] * v[2] + v[3] * v[3];
;                     }
;                 sq = sum_x16_x32(sq);
;                 if (fq == 0) atomicAdd(ss + r, sq);
;             }
.LBB0_1021:
	s_or_b64 exec, exec, s[18:19]
	v_add_u32_e32 v32, 0xa0, v142
	v_ashrrev_i32_e32 v33, 31, v32
	v_lshlrev_b64 v[34:35], 12, v[32:33]
	v_lshl_add_u64 v[34:35], s[66:67], 0, v[34:35]
	v_lshl_add_u64 v[38:39], v[140:141], 2, v[34:35]
	v_lshl_add_u64 v[198:199], v[198:199], 0, s[98:99]
	global_load_dwordx4 v[212:215], v[198:199], off
	global_load_dwordx4 v[216:219], v[198:199], off offset:64
	global_load_dwordx4 v[220:223], v[198:199], off offset:512
	global_load_dwordx4 v[224:227], v[198:199], off offset:576
	v_lshlrev_b64 v[40:41], 11, v[32:33]
	v_lshl_add_u64 v[40:41], s[68:69], 0, v[40:41]
	v_lshl_add_u64 v[40:41], v[140:141], 1, v[40:41]
	s_waitcnt vmcnt(15)
	v_pk_add_f32 v[30:31], v[30:31], v[182:183]
	v_pk_add_f32 v[28:29], v[28:29], v[180:181]
	v_cvt_pk_bf16_f32 v35, v30, v31
	v_cvt_pk_bf16_f32 v34, v28, v29
	global_store_dwordx4 v[38:39], v[28:31], off
	global_store_dwordx2 v[40:41], v[34:35], off
	s_nop 0
	v_mul_f32_e32 v29, v29, v29
	v_fmac_f32_e32 v29, v28, v28
	v_fmac_f32_e32 v29, v30, v30
	v_fmac_f32_e32 v29, v31, v31
	s_waitcnt vmcnt(16)
	v_pk_add_f32 v[26:27], v[26:27], v[186:187]
	v_pk_add_f32 v[24:25], v[24:25], v[184:185]
	v_cvt_pk_bf16_f32 v35, v26, v27
	v_cvt_pk_bf16_f32 v34, v24, v25
	global_store_dwordx4 v[38:39], v[24:27], off offset:64
	global_store_dwordx2 v[40:41], v[34:35], off offset:32
	s_nop 0
	v_mul_f32_e32 v25, v25, v25
	v_fmac_f32_e32 v25, v24, v24
	v_fmac_f32_e32 v25, v26, v26
	v_fmac_f32_e32 v25, v27, v27
	v_add_f32_e32 v24, v29, v25
	s_waitcnt vmcnt(17)
	v_pk_add_f32 v[22:23], v[22:23], v[190:191]
	v_pk_add_f32 v[20:21], v[20:21], v[188:189]
	v_cvt_pk_bf16_f32 v35, v22, v23
	v_cvt_pk_bf16_f32 v34, v20, v21
	global_store_dwordx4 v[38:39], v[20:23], off offset:512
	global_store_dwordx2 v[40:41], v[34:35], off offset:256
	s_nop 0
	v_mul_f32_e32 v21, v21, v21
	v_fmac_f32_e32 v21, v20, v20
	v_fmac_f32_e32 v21, v22, v22
	v_fmac_f32_e32 v21, v23, v23
	v_add_f32_e32 v22, v24, v21
	s_waitcnt vmcnt(18)
	v_pk_add_f32 v[18:19], v[18:19], v[194:195]
	v_pk_add_f32 v[16:17], v[16:17], v[192:193]
	global_store_dwordx4 v[38:39], v[16:19], off offset:576
	v_cvt_pk_bf16_f32 v20, v16, v17
	v_cvt_pk_bf16_f32 v21, v18, v19
	v_mul_f32_e32 v17, v17, v17
	v_fmac_f32_e32 v17, v16, v16
	v_fmac_f32_e32 v17, v18, v18
	v_fmac_f32_e32 v17, v19, v19
	v_add_f32_e32 v16, v22, v17
	v_mov_b32_e32 v17, v16
	s_nop 1
	v_permlane16_swap_b32_e32 v16, v17
	v_add_f32_e32 v16, v16, v17
	v_mov_b32_e32 v17, v16
	s_nop 1
	v_permlane32_swap_b32_e32 v16, v17
	global_store_dwordx2 v[40:41], v[20:21], off offset:288
	s_and_saveexec_b64 s[18:19], s[4:5]
	s_cbranch_execz .LBB0_1023
	v_lshl_add_u64 v[18:19], v[32:33], 2, s[44:45]
	v_add_f32_e32 v16, v16, v17
	global_atomic_add_f32 v[18:19], v16, off
.LBB0_1023:
	s_or_b64 exec, exec, s[18:19]
	v_add_u32_e32 v16, 0xb0, v142
	v_ashrrev_i32_e32 v17, 31, v16
	v_lshlrev_b64 v[18:19], 12, v[16:17]
	v_lshl_add_u64 v[18:19], s[66:67], 0, v[18:19]
	v_lshl_add_u64 v[22:23], v[140:141], 2, v[18:19]
	s_nop 0
	v_lshlrev_b64 v[24:25], 11, v[16:17]
	v_lshl_add_u64 v[24:25], s[68:69], 0, v[24:25]
	v_lshl_add_u64 v[24:25], v[140:141], 1, v[24:25]
	s_waitcnt vmcnt(11)
	v_pk_add_f32 v[14:15], v[14:15], v[214:215]
	v_pk_add_f32 v[12:13], v[12:13], v[212:213]
	v_cvt_pk_bf16_f32 v19, v14, v15
	v_cvt_pk_bf16_f32 v18, v12, v13
	global_store_dwordx4 v[22:23], v[12:15], off
	global_store_dwordx2 v[24:25], v[18:19], off
	s_nop 0
	v_mul_f32_e32 v13, v13, v13
	v_fmac_f32_e32 v13, v12, v12
	v_fmac_f32_e32 v13, v14, v14
	v_fmac_f32_e32 v13, v15, v15
	s_waitcnt vmcnt(12)
	v_pk_add_f32 v[10:11], v[10:11], v[218:219]
	v_pk_add_f32 v[8:9], v[8:9], v[216:217]
	v_cvt_pk_bf16_f32 v19, v10, v11
	v_cvt_pk_bf16_f32 v18, v8, v9
	global_store_dwordx4 v[22:23], v[8:11], off offset:64
	global_store_dwordx2 v[24:25], v[18:19], off offset:32
	s_nop 0
	v_mul_f32_e32 v9, v9, v9
	v_fmac_f32_e32 v9, v8, v8
	v_fmac_f32_e32 v9, v10, v10
	v_fmac_f32_e32 v9, v11, v11
	v_add_f32_e32 v8, v13, v9
	s_waitcnt vmcnt(13)
	v_pk_add_f32 v[6:7], v[6:7], v[222:223]
	v_pk_add_f32 v[4:5], v[4:5], v[220:221]
	v_cvt_pk_bf16_f32 v19, v6, v7
	v_cvt_pk_bf16_f32 v18, v4, v5
	global_store_dwordx4 v[22:23], v[4:7], off offset:512
	global_store_dwordx2 v[24:25], v[18:19], off offset:256
	s_nop 0
	v_mul_f32_e32 v5, v5, v5
	v_fmac_f32_e32 v5, v4, v4
	v_fmac_f32_e32 v5, v6, v6
	v_fmac_f32_e32 v5, v7, v7
	v_add_f32_e32 v6, v8, v5
	s_waitcnt vmcnt(14)
	v_pk_add_f32 v[2:3], v[2:3], v[226:227]
	v_pk_add_f32 v[0:1], v[0:1], v[224:225]
	global_store_dwordx4 v[22:23], v[0:3], off offset:576
	v_cvt_pk_bf16_f32 v4, v0, v1
	v_cvt_pk_bf16_f32 v5, v2, v3
	v_mul_f32_e32 v1, v1, v1
	v_fmac_f32_e32 v1, v0, v0
	v_fmac_f32_e32 v1, v2, v2
	v_fmac_f32_e32 v1, v3, v3
	v_add_f32_e32 v0, v6, v1
	v_mov_b32_e32 v1, v0
	s_nop 1
	v_permlane16_swap_b32_e32 v0, v1
	v_add_f32_e32 v0, v0, v1
	v_mov_b32_e32 v1, v0
	s_nop 1
	v_permlane32_swap_b32_e32 v0, v1
	global_store_dwordx2 v[24:25], v[4:5], off offset:288
	s_and_saveexec_b64 s[18:19], s[4:5]
	s_cbranch_execz .LBB0_1000
	v_lshl_add_u64 v[2:3], v[16:17], 2, s[44:45]
	v_add_f32_e32 v0, v0, v1
	global_atomic_add_f32 v[2:3], v0, off
	s_branch .LBB0_1000

; #define PG8_STAGE(bufoff, gbase, voff) do { _Pragma("unroll") for (int _i = 0; _i < 2; ++_i) \
;         __builtin_amdgcn_global_load_lds((const unsigned*)((const char*)(gbase) + (voff)[_i]), (LAS unsigned*)(lds + (bufoff) + ldsw + _i * 8192), 16, 0, 0); } while (0)
; #define PG8_LDA(dst, b, h) do { _Pragma("unroll") for (int m = 0; m < 4; ++m) _Pragma("unroll") for (int k = 0; k < 2; ++k) dst[m][k] = *(const LAS bf16x8*)(lds + PG8_SA(b, h) + aoff + m * 2048 + k * 1024); } while (0)
; #define PG8_LDB(dst, b, h) do { _Pragma("unroll") for (int n = 0; n < 2; ++n) _Pragma("unroll") for (int k = 0; k < 2; ++k) dst[n][k] = *(const LAS bf16x8*)(lds + PG8_SB(b, h) + boff + n * 2048 + k * 1024); } while (0)
; #define PG8_MMA(ai, bj, At, Bt) do { __builtin_amdgcn_s_setprio(1); _Pragma("unroll") for (int m = 0; m < 4; ++m) _Pragma("unroll") for (int n = 0; n < 2; ++n) _Pragma("unroll") for (int k = 0; k < 2; ++k) \
;         acc[ai][bj][m][n] = __builtin_amdgcn_mfma_f32_16x16x32_bf16(Bt[n][k], At[m][k], acc[ai][bj][m][n], 0, 0, 0); __builtin_amdgcn_s_setprio(0); } while (0)
; #define PG8_WAIT_L(n) asm volatile("s_waitcnt lgkmcnt(" #n ")" ::: "memory")
; #define PG8_BAR __builtin_amdgcn_s_barrier()
; #define PG8_SCHED __builtin_amdgcn_sched_barrier(0)
; template <class Epi>
; __device__ __forceinline__ void gemm_phase(LAS unsigned char* lds, const Gemm g, const StaticOrder& S, const Epi& E) {
;     ...
;         for (int t = 0; t < nt; t += 2) {
;             const bool last = (t == nt - 2);
;             const char* a1 = cA + (size_t)(t + 1) * kstep;
;             const char* a2 = last ? nA : cA + (size_t)(t + 2) * kstep; const char* b2 = last ? nB : cB + (size_t)(t + 2) * kstep;
;             const char* a3 = a2 + kstep; const char* b3 = b2 + kstep;
;             PG8_LDB(B0, 0, 0); PG8_SCHED; PG8_LDA(At, 0, 0); PG8_STAGE(PG8_SA(1, 1), a1 + hstep, voffA);
;             PG8_WAIT_L(8); PG8_BAR; PG8_WAIT_L(0); PG8_MMA(0, 0, At, B0); PG8_BAR; PG8_SCHED;
;             PG8_LDB(B1, 0, 1); PG8_STAGE(PG8_SB(0, 0), b2, voffB);
;             PG8_BAR; PG8_WAIT_L(0); PG8_MMA(0, 1, At, B1); PG8_BAR;
;             PG8_LDA(At, 0, 1); PG8_STAGE(PG8_SA(0, 0), a2, voffA);
;             PG8_BAR; PG8_WAIT_L(0); PG8_MMA(1, 0, At, B0); PG8_BAR; PG8_SCHED;
.LBB0_1377:
	ds_read_b128 v[140:143], v147
	ds_read_b128 v[150:153], v147 offset:1024
	ds_read_b128 v[154:157], v147 offset:2048
	ds_read_b128 v[158:161], v147 offset:3072
	s_add_u32 s30, s28, 0x100
	s_addc_u32 s31, s29, 0
	s_cmp_eq_u32 s59, 12
	s_cselect_b32 s39, s19, s31
	s_cselect_b32 s38, s25, s30
	s_cselect_b32 s37, s15, s58
	s_cselect_b32 s36, s56, s57
	v_lshl_add_u64 v[196:197], s[28:29], 0, v[132:133]
	s_add_i32 m0, s27, 0xc000
	ds_read_b128 v[162:165], v148
	ds_read_b128 v[166:169], v148 offset:1024
	ds_read_b128 v[170:173], v148 offset:2048
	ds_read_b128 v[174:177], v148 offset:3072
	ds_read_b128 v[180:183], v148 offset:4096
	ds_read_b128 v[184:187], v148 offset:5120
	ds_read_b128 v[188:191], v148 offset:6144
	ds_read_b128 v[192:195], v148 offset:7168
	global_load_lds_dwordx4 v[196:197], off
	v_lshl_add_u64 v[196:197], s[28:29], 0, v[134:135]
	s_add_i32 m0, s27, 0xe000
	s_nop 0
	global_load_lds_dwordx4 v[196:197], off
	s_waitcnt lgkmcnt(8)
	s_barrier
	s_waitcnt lgkmcnt(0)
	s_setprio 1
	s_waitcnt lgkmcnt(0)
	v_mfma_f32_16x16x32_bf16 v[124:127], v[140:143], v[162:165], v[124:127]
	v_mfma_f32_16x16x32_bf16 v[120:123], v[154:157], v[162:165], v[120:123]
	v_mfma_f32_16x16x32_bf16 v[108:111], v[140:143], v[170:173], v[108:111]
	v_mfma_f32_16x16x32_bf16 v[104:107], v[154:157], v[170:173], v[104:107]
	v_mfma_f32_16x16x32_bf16 v[92:95], v[140:143], v[180:183], v[92:95]
	v_mfma_f32_16x16x32_bf16 v[88:91], v[154:157], v[180:183], v[88:91]
	v_mfma_f32_16x16x32_bf16 v[76:79], v[140:143], v[188:191], v[76:79]
	v_mfma_f32_16x16x32_bf16 v[72:75], v[154:157], v[188:191], v[72:75]
	v_mfma_f32_16x16x32_bf16 v[124:127], v[150:153], v[166:169], v[124:127]
	v_mfma_f32_16x16x32_bf16 v[120:123], v[158:161], v[166:169], v[120:123]
	v_mfma_f32_16x16x32_bf16 v[108:111], v[150:153], v[174:177], v[108:111]
	v_mfma_f32_16x16x32_bf16 v[104:107], v[158:161], v[174:177], v[104:107]
	v_mfma_f32_16x16x32_bf16 v[92:95], v[150:153], v[184:187], v[92:95]
	v_mfma_f32_16x16x32_bf16 v[88:91], v[158:161], v[184:187], v[88:91]
	v_mfma_f32_16x16x32_bf16 v[76:79], v[150:153], v[192:195], v[76:79]
	v_mfma_f32_16x16x32_bf16 v[72:75], v[158:161], v[192:195], v[72:75]
	s_setprio 0
	s_barrier
	s_add_i32 s28, s50, s40
	v_lshl_add_u64 v[212:213], s[36:37], 0, v[128:129]
	s_mov_b32 m0, s28
	ds_read_b128 v[196:199], v149
	ds_read_b128 v[200:203], v149 offset:1024
	ds_read_b128 v[204:207], v149 offset:2048
	ds_read_b128 v[208:211], v149 offset:3072
	global_load_lds_dwordx4 v[212:213], off
	v_lshl_add_u64 v[214:215], s[36:37], 0, v[130:131]
	s_add_i32 m0, s28, 0x2000
	s_nop 0
	global_load_lds_dwordx4 v[214:215], off
	s_barrier
	s_waitcnt lgkmcnt(0)
	s_setprio 1
	s_waitcnt lgkmcnt(0)
	v_mfma_f32_16x16x32_bf16 v[116:119], v[196:199], v[162:165], v[116:119]
	v_mfma_f32_16x16x32_bf16 v[112:115], v[204:207], v[162:165], v[112:115]
	v_mfma_f32_16x16x32_bf16 v[100:103], v[196:199], v[170:173], v[100:103]
	v_mfma_f32_16x16x32_bf16 v[96:99], v[204:207], v[170:173], v[96:99]
	v_mfma_f32_16x16x32_bf16 v[84:87], v[196:199], v[180:183], v[84:87]
	v_mfma_f32_16x16x32_bf16 v[80:83], v[204:207], v[180:183], v[80:83]
	v_mfma_f32_16x16x32_bf16 v[68:71], v[196:199], v[188:191], v[68:71]
	v_mfma_f32_16x16x32_bf16 v[64:67], v[204:207], v[188:191], v[64:67]
	v_mfma_f32_16x16x32_bf16 v[116:119], v[200:203], v[166:169], v[116:119]
	v_mfma_f32_16x16x32_bf16 v[112:115], v[208:211], v[166:169], v[112:115]
	v_mfma_f32_16x16x32_bf16 v[100:103], v[200:203], v[174:177], v[100:103]
	v_mfma_f32_16x16x32_bf16 v[96:99], v[208:211], v[174:177], v[96:99]
	v_mfma_f32_16x16x32_bf16 v[84:87], v[200:203], v[184:187], v[84:87]
	v_mfma_f32_16x16x32_bf16 v[80:83], v[208:211], v[184:187], v[80:83]
	v_mfma_f32_16x16x32_bf16 v[68:71], v[200:203], v[192:195], v[68:71]
	v_mfma_f32_16x16x32_bf16 v[64:67], v[208:211], v[192:195], v[64:67]
	s_setprio 0
	s_mov_b32 m0, s27
	v_lshl_add_u64 v[216:217], s[38:39], 0, v[128:129]
	s_barrier
	ds_read_b128 v[162:165], v148 offset:16384
	ds_read_b128 v[166:169], v148 offset:17408
	ds_read_b128 v[170:173], v148 offset:18432
	ds_read_b128 v[174:177], v148 offset:19456
	ds_read_b128 v[180:183], v148 offset:20480
	ds_read_b128 v[184:187], v148 offset:21504
	ds_read_b128 v[188:191], v148 offset:22528
	ds_read_b128 v[192:195], v148 offset:23552
	global_load_lds_dwordx4 v[216:217], off
	v_lshl_add_u64 v[218:219], s[38:39], 0, v[130:131]
	s_mov_b32 m0, s41
	s_nop 0
	global_load_lds_dwordx4 v[218:219], off
	s_barrier
	s_waitcnt lgkmcnt(0)
	s_setprio 1
	s_waitcnt lgkmcnt(0)
	v_mfma_f32_16x16x32_bf16 v[60:63], v[140:143], v[162:165], v[60:63]
	v_mfma_f32_16x16x32_bf16 v[56:59], v[154:157], v[162:165], v[56:59]
	v_mfma_f32_16x16x32_bf16 v[44:47], v[140:143], v[170:173], v[44:47]
	v_mfma_f32_16x16x32_bf16 v[40:43], v[154:157], v[170:173], v[40:43]
	v_mfma_f32_16x16x32_bf16 v[28:31], v[140:143], v[180:183], v[28:31]
	v_mfma_f32_16x16x32_bf16 v[24:27], v[154:157], v[180:183], v[24:27]
	v_mfma_f32_16x16x32_bf16 v[12:15], v[140:143], v[188:191], v[12:15]
	v_mfma_f32_16x16x32_bf16 v[8:11], v[154:157], v[188:191], v[8:11]
	v_mfma_f32_16x16x32_bf16 v[60:63], v[150:153], v[166:169], v[60:63]
	v_mfma_f32_16x16x32_bf16 v[56:59], v[158:161], v[166:169], v[56:59]
	v_mfma_f32_16x16x32_bf16 v[44:47], v[150:153], v[174:177], v[44:47]
	v_mfma_f32_16x16x32_bf16 v[40:43], v[158:161], v[174:177], v[40:43]
	v_mfma_f32_16x16x32_bf16 v[28:31], v[150:153], v[184:187], v[28:31]
	v_mfma_f32_16x16x32_bf16 v[24:27], v[158:161], v[184:187], v[24:27]
	v_mfma_f32_16x16x32_bf16 v[12:15], v[150:153], v[192:195], v[12:15]
	v_mfma_f32_16x16x32_bf16 v[8:11], v[158:161], v[192:195], v[8:11]
	s_setprio 0
	s_barrier
; #define PG8_STAGE(bufoff, gbase, voff) do { _Pragma("unroll") for (int _i = 0; _i < 2; ++_i) \
;         __builtin_amdgcn_global_load_lds((const unsigned*)((const char*)(gbase) + (voff)[_i]), (LAS unsigned*)(lds + (bufoff) + ldsw + _i * 8192), 16, 0, 0); } while (0)
; #define PG8_LDA(dst, b, h) do { _Pragma("unroll") for (int m = 0; m < 4; ++m) _Pragma("unroll") for (int k = 0; k < 2; ++k) dst[m][k] = *(const LAS bf16x8*)(lds + PG8_SA(b, h) + aoff + m * 2048 + k * 1024); } while (0)
; #define PG8_LDB(dst, b, h) do { _Pragma("unroll") for (int n = 0; n < 2; ++n) _Pragma("unroll") for (int k = 0; k < 2; ++k) dst[n][k] = *(const LAS bf16x8*)(lds + PG8_SB(b, h) + boff + n * 2048 + k * 1024); } while (0)
; #define PG8_MMA(ai, bj, At, Bt) do { __builtin_amdgcn_s_setprio(1); _Pragma("unroll") for (int m = 0; m < 4; ++m) _Pragma("unroll") for (int n = 0; n < 2; ++n) _Pragma("unroll") for (int k = 0; k < 2; ++k) \
;         acc[ai][bj][m][n] = __builtin_amdgcn_mfma_f32_16x16x32_bf16(Bt[n][k], At[m][k], acc[ai][bj][m][n], 0, 0, 0); __builtin_amdgcn_s_setprio(0); } while (0)
; #define PG8_WAIT_V(n) asm volatile("s_waitcnt vmcnt(" #n ")" ::: "memory")
; #define PG8_WAIT_L(n) asm volatile("s_waitcnt lgkmcnt(" #n ")" ::: "memory")
; #define PG8_BAR __builtin_amdgcn_s_barrier()
; #define PG8_SCHED __builtin_amdgcn_sched_barrier(0)
; template <class Epi>
; __device__ __forceinline__ void gemm_phase(LAS unsigned char* lds, const Gemm g, const StaticOrder& S, const Epi& E) {
;     ...
;             PG8_STAGE(PG8_SB(0, 1), b2 + hstep, voffB);
;             PG8_WAIT_V(6); PG8_BAR; PG8_MMA(1, 1, At, B1); PG8_BAR;
;             PG8_LDB(B0, 1, 0); PG8_SCHED; PG8_LDA(At, 1, 0); PG8_STAGE(PG8_SA(0, 1), a2 + hstep, voffA);
;             PG8_WAIT_L(8); PG8_BAR; PG8_WAIT_L(0); PG8_MMA(0, 0, At, B0); PG8_BAR; PG8_SCHED;
;             PG8_LDB(B1, 1, 1); PG8_STAGE(PG8_SB(1, 0), b3, voffB);
;             PG8_BAR; PG8_WAIT_L(0); PG8_MMA(0, 1, At, B1); PG8_BAR;
;             PG8_LDA(At, 1, 1); PG8_STAGE(PG8_SA(1, 0), a3, voffA);
;             PG8_BAR; PG8_WAIT_L(0); PG8_MMA(1, 0, At, B0); PG8_BAR; PG8_SCHED;
	s_add_u32 s28, s36, 0x40000
	s_addc_u32 s29, s37, 0
	s_add_i32 s60, s51, s40
	v_lshl_add_u64 v[140:141], s[28:29], 0, v[128:129]
	s_mov_b32 m0, s60
	s_nop 0
	global_load_lds_dwordx4 v[140:141], off
	v_lshl_add_u64 v[140:141], s[28:29], 0, v[130:131]
	s_add_i32 m0, s60, 0x2000
	s_nop 0
	global_load_lds_dwordx4 v[140:141], off
	s_waitcnt vmcnt(6)
	s_barrier
	s_setprio 1
	v_mfma_f32_16x16x32_bf16 v[52:55], v[196:199], v[162:165], v[52:55]
	v_mfma_f32_16x16x32_bf16 v[48:51], v[204:207], v[162:165], v[48:51]
	v_mfma_f32_16x16x32_bf16 v[36:39], v[196:199], v[170:173], v[36:39]
	v_mfma_f32_16x16x32_bf16 v[32:35], v[204:207], v[170:173], v[32:35]
	v_mfma_f32_16x16x32_bf16 v[20:23], v[196:199], v[180:183], v[20:23]
	v_mfma_f32_16x16x32_bf16 v[16:19], v[204:207], v[180:183], v[16:19]
	v_mfma_f32_16x16x32_bf16 v[4:7], v[196:199], v[188:191], v[4:7]
	v_mfma_f32_16x16x32_bf16 v[0:3], v[204:207], v[188:191], v[0:3]
	v_mfma_f32_16x16x32_bf16 v[52:55], v[200:203], v[166:169], v[52:55]
	v_mfma_f32_16x16x32_bf16 v[48:51], v[208:211], v[166:169], v[48:51]
	v_mfma_f32_16x16x32_bf16 v[36:39], v[200:203], v[174:177], v[36:39]
	v_mfma_f32_16x16x32_bf16 v[32:35], v[208:211], v[174:177], v[32:35]
	v_mfma_f32_16x16x32_bf16 v[20:23], v[200:203], v[184:187], v[20:23]
	v_mfma_f32_16x16x32_bf16 v[16:19], v[208:211], v[184:187], v[16:19]
	v_mfma_f32_16x16x32_bf16 v[4:7], v[200:203], v[192:195], v[4:7]
	v_mfma_f32_16x16x32_bf16 v[0:3], v[208:211], v[192:195], v[0:3]
	s_setprio 0
	s_add_i32 s60, 0, 0x18000
	v_add_u32_e32 v158, s60, v145
	s_barrier
	ds_read_b128 v[140:143], v158
	ds_read_b128 v[150:153], v158 offset:1024
	ds_read_b128 v[154:157], v158 offset:2048
	ds_read_b128 v[158:161], v158 offset:3072
	s_add_u32 s28, s38, 0x40000
	s_addc_u32 s29, s39, 0
	s_mov_b32 m0, s42
	v_lshl_add_u64 v[196:197], s[28:29], 0, v[128:129]
	ds_read_b128 v[162:165], v148 offset:32768
	ds_read_b128 v[166:169], v148 offset:33792
	ds_read_b128 v[170:173], v148 offset:34816
	ds_read_b128 v[174:177], v148 offset:35840
	ds_read_b128 v[180:183], v148 offset:36864
	ds_read_b128 v[184:187], v148 offset:37888
	ds_read_b128 v[188:191], v148 offset:38912
	ds_read_b128 v[192:195], v148 offset:39936
	global_load_lds_dwordx4 v[196:197], off
	v_lshl_add_u64 v[196:197], s[28:29], 0, v[130:131]
	s_mov_b32 m0, s43
	s_nop 0
	global_load_lds_dwordx4 v[196:197], off
	s_waitcnt lgkmcnt(8)
	s_barrier
	s_waitcnt lgkmcnt(0)
	s_setprio 1
	s_waitcnt lgkmcnt(0)
	v_mfma_f32_16x16x32_bf16 v[124:127], v[140:143], v[162:165], v[124:127]
	v_mfma_f32_16x16x32_bf16 v[120:123], v[154:157], v[162:165], v[120:123]
	v_mfma_f32_16x16x32_bf16 v[108:111], v[140:143], v[170:173], v[108:111]
	v_mfma_f32_16x16x32_bf16 v[104:107], v[154:157], v[170:173], v[104:107]
	v_mfma_f32_16x16x32_bf16 v[92:95], v[140:143], v[180:183], v[92:95]
	v_mfma_f32_16x16x32_bf16 v[88:91], v[154:157], v[180:183], v[88:91]
	v_mfma_f32_16x16x32_bf16 v[76:79], v[140:143], v[188:191], v[76:79]
	v_mfma_f32_16x16x32_bf16 v[72:75], v[154:157], v[188:191], v[72:75]
	v_mfma_f32_16x16x32_bf16 v[124:127], v[150:153], v[166:169], v[124:127]
	v_mfma_f32_16x16x32_bf16 v[120:123], v[158:161], v[166:169], v[120:123]
	v_mfma_f32_16x16x32_bf16 v[108:111], v[150:153], v[174:177], v[108:111]
	v_mfma_f32_16x16x32_bf16 v[104:107], v[158:161], v[174:177], v[104:107]
	v_mfma_f32_16x16x32_bf16 v[92:95], v[150:153], v[184:187], v[92:95]
	v_mfma_f32_16x16x32_bf16 v[88:91], v[158:161], v[184:187], v[88:91]
	v_mfma_f32_16x16x32_bf16 v[76:79], v[150:153], v[192:195], v[76:79]
	v_mfma_f32_16x16x32_bf16 v[72:75], v[158:161], v[192:195], v[72:75]
	s_setprio 0
	s_barrier
	s_add_i32 s38, 0, 0x1c000
	s_add_i32 s28, s60, s40
	v_add_u32_e32 v179, s38, v145
	v_lshl_add_u64 v[212:213], v[212:213], 0, s[12:13]
	s_mov_b32 m0, s28
	ds_read_b128 v[196:199], v179
	ds_read_b128 v[200:203], v179 offset:1024
	ds_read_b128 v[204:207], v179 offset:2048
	ds_read_b128 v[208:211], v179 offset:3072
	global_load_lds_dwordx4 v[212:213], off
	v_lshl_add_u64 v[212:213], v[214:215], 0, s[12:13]
	s_add_i32 m0, s28, 0x2000
	s_nop 0
	global_load_lds_dwordx4 v[212:213], off
	s_barrier
	s_waitcnt lgkmcnt(0)
	s_setprio 1
	s_waitcnt lgkmcnt(0)
	v_mfma_f32_16x16x32_bf16 v[116:119], v[196:199], v[162:165], v[116:119]
	v_mfma_f32_16x16x32_bf16 v[112:115], v[204:207], v[162:165], v[112:115]
	v_mfma_f32_16x16x32_bf16 v[100:103], v[196:199], v[170:173], v[100:103]
	v_mfma_f32_16x16x32_bf16 v[96:99], v[204:207], v[170:173], v[96:99]
	v_mfma_f32_16x16x32_bf16 v[84:87], v[196:199], v[180:183], v[84:87]
	v_mfma_f32_16x16x32_bf16 v[80:83], v[204:207], v[180:183], v[80:83]
	v_mfma_f32_16x16x32_bf16 v[68:71], v[196:199], v[188:191], v[68:71]
	v_mfma_f32_16x16x32_bf16 v[64:67], v[204:207], v[188:191], v[64:67]
	v_mfma_f32_16x16x32_bf16 v[116:119], v[200:203], v[166:169], v[116:119]
	v_mfma_f32_16x16x32_bf16 v[112:115], v[208:211], v[166:169], v[112:115]
	v_mfma_f32_16x16x32_bf16 v[100:103], v[200:203], v[174:177], v[100:103]
	v_mfma_f32_16x16x32_bf16 v[96:99], v[208:211], v[174:177], v[96:99]
	v_mfma_f32_16x16x32_bf16 v[84:87], v[200:203], v[184:187], v[84:87]
	v_mfma_f32_16x16x32_bf16 v[80:83], v[208:211], v[184:187], v[80:83]
	v_mfma_f32_16x16x32_bf16 v[68:71], v[200:203], v[192:195], v[68:71]
	v_mfma_f32_16x16x32_bf16 v[64:67], v[208:211], v[192:195], v[64:67]
	s_setprio 0
	s_mov_b32 m0, s45
	v_lshl_add_u64 v[212:213], v[216:217], 0, s[12:13]
	s_barrier
	ds_read_b128 v[162:165], v148 offset:49152
	ds_read_b128 v[166:169], v148 offset:50176
	ds_read_b128 v[170:173], v148 offset:51200
	ds_read_b128 v[174:177], v148 offset:52224
	ds_read_b128 v[180:183], v148 offset:53248
	ds_read_b128 v[184:187], v148 offset:54272
	ds_read_b128 v[188:191], v148 offset:55296
	ds_read_b128 v[192:195], v148 offset:56320
	global_load_lds_dwordx4 v[212:213], off
	v_lshl_add_u64 v[212:213], v[218:219], 0, s[12:13]
	s_mov_b32 m0, s46
	s_nop 0
	global_load_lds_dwordx4 v[212:213], off
	s_barrier
; DI float sum_x16_x32(float x) { return sum_x32(sum_x16(x)); }
; #define PG8_BAR __builtin_amdgcn_s_barrier()
; template <class Epi>
; __device__ __forceinline__ void gemm_phase(LAS unsigned char* lds, const Gemm g, const StaticOrder& S, const Epi& E) {
;     ...
;             PG8_WAIT_V(6); PG8_BAR; PG8_MMA(1, 1, At, B1); PG8_BAR;
;             PG8_LDB(B0, 1, 0); PG8_SCHED; PG8_LDA(At, 1, 0); PG8_STAGE(PG8_SA(0, 1), a2 + hstep, voffA);
;             PG8_WAIT_L(8); PG8_BAR; PG8_WAIT_L(0); PG8_MMA(0, 0, At, B0); PG8_BAR; PG8_SCHED;
;             PG8_LDB(B1, 1, 1); PG8_STAGE(PG8_SB(1, 0), b3, voffB);
;             PG8_BAR; PG8_WAIT_L(0); PG8_MMA(0, 1, At, B1); PG8_BAR;
;             PG8_LDA(At, 1, 1); PG8_STAGE(PG8_SA(1, 0), a3, voffA);
;             PG8_BAR; PG8_WAIT_L(0); PG8_MMA(1, 0, At, B0); PG8_BAR; PG8_SCHED;
;             PG8_STAGE(PG8_SB(1, 1), b3 + hstep, voffB);
;             PG8_WAIT_V(6); PG8_BAR; PG8_MMA(1, 1, At, B1); PG8_BAR;
;     DI void operator()(const f32x4 (&acc)[2][2][4][2], const Unit& u, int wr, int wc, int fr, int fq) const {
;         const int row0 = u.pm * 256 + wr * 64 + fr, col0 = u.pn * 256 + wc * 32 + 4 * fq;
; #pragma unroll
;         for (int ai = 0; ai < 2; ++ai)
; #pragma unroll
;             for (int m = 0; m < 4; ++m) {
;                 const int r = row0 + ai * 128 + m * 16;
;                 const float* rp;
;                 if (MODE == 0) rp = x + (size_t)r * 1024;
;                 else rp = h + (size_t)r * 1024;
;                 float sq = 0.f;
; #pragma unroll
;                 for (int bj = 0; bj < 2; ++bj)
; #pragma unroll
;                     for (int n = 0; n < 2; ++n) {
;                         const int c = col0 + bj * 128 + n * 16;
;                         f32x4 rv = rp ? *(const f32x4*)(rp + c) : (f32x4){0.f, 0.f, 0.f, 0.f};
;                         f32x4 v = acc[ai][bj][m][n] + rv;
;                         *(f32x4*)(h + (size_t)r * 1024 + c) = v;
;                         if (WRITE_HB) {
;                             u32x2 w; w.x = pk2(v[0], v[1]); w.y = pk2(v[2], v[3]);
;                             *(u32x2*)(hb + (size_t)r * 1024 + c) = w;
;                         }
;                         sq += v[0] * v[0] + v[1] * v[1] + v[2] * v[2] + v[3] * v[3];
;                     }
;                 sq = sum_x16_x32(sq);
;                 if (fq == 0) atomicAdd(ss + r, sq);
;             }
	s_waitcnt lgkmcnt(0)
	s_setprio 1
	s_waitcnt lgkmcnt(0)
	v_mfma_f32_16x16x32_bf16 v[60:63], v[140:143], v[162:165], v[60:63]
	v_mfma_f32_16x16x32_bf16 v[56:59], v[154:157], v[162:165], v[56:59]
	v_mfma_f32_16x16x32_bf16 v[44:47], v[140:143], v[170:173], v[44:47]
	v_mfma_f32_16x16x32_bf16 v[40:43], v[154:157], v[170:173], v[40:43]
	v_mfma_f32_16x16x32_bf16 v[28:31], v[140:143], v[180:183], v[28:31]
	v_mfma_f32_16x16x32_bf16 v[24:27], v[154:157], v[180:183], v[24:27]
	v_mfma_f32_16x16x32_bf16 v[12:15], v[140:143], v[188:191], v[12:15]
	v_mfma_f32_16x16x32_bf16 v[8:11], v[154:157], v[188:191], v[8:11]
	v_mfma_f32_16x16x32_bf16 v[60:63], v[150:153], v[166:169], v[60:63]
	v_mfma_f32_16x16x32_bf16 v[56:59], v[158:161], v[166:169], v[56:59]
	v_mfma_f32_16x16x32_bf16 v[44:47], v[150:153], v[174:177], v[44:47]
	v_mfma_f32_16x16x32_bf16 v[40:43], v[158:161], v[174:177], v[40:43]
	v_mfma_f32_16x16x32_bf16 v[28:31], v[150:153], v[184:187], v[28:31]
	v_mfma_f32_16x16x32_bf16 v[24:27], v[158:161], v[184:187], v[24:27]
	v_mfma_f32_16x16x32_bf16 v[12:15], v[150:153], v[192:195], v[12:15]
	v_mfma_f32_16x16x32_bf16 v[8:11], v[158:161], v[192:195], v[8:11]
	s_setprio 0
	s_barrier
	s_add_u32 s28, s36, 0x40080
	s_addc_u32 s29, s37, 0
	s_add_i32 s36, s38, s40
	v_lshl_add_u64 v[140:141], s[28:29], 0, v[128:129]
	s_mov_b32 m0, s36
	s_nop 0
	global_load_lds_dwordx4 v[140:141], off
	v_lshl_add_u64 v[140:141], s[28:29], 0, v[130:131]
	s_add_i32 m0, s36, 0x2000
	s_nop 0
	global_load_lds_dwordx4 v[140:141], off
	s_waitcnt vmcnt(6)
	s_barrier
	s_setprio 1
	v_mfma_f32_16x16x32_bf16 v[52:55], v[196:199], v[162:165], v[52:55]
	v_mfma_f32_16x16x32_bf16 v[48:51], v[204:207], v[162:165], v[48:51]
	v_mfma_f32_16x16x32_bf16 v[36:39], v[196:199], v[170:173], v[36:39]
	v_mfma_f32_16x16x32_bf16 v[32:35], v[204:207], v[170:173], v[32:35]
	v_mfma_f32_16x16x32_bf16 v[20:23], v[196:199], v[180:183], v[20:23]
	v_mfma_f32_16x16x32_bf16 v[16:19], v[204:207], v[180:183], v[16:19]
	v_mfma_f32_16x16x32_bf16 v[4:7], v[196:199], v[188:191], v[4:7]
	v_mfma_f32_16x16x32_bf16 v[0:3], v[204:207], v[188:191], v[0:3]
	v_mfma_f32_16x16x32_bf16 v[52:55], v[200:203], v[166:169], v[52:55]
	v_mfma_f32_16x16x32_bf16 v[48:51], v[208:211], v[166:169], v[48:51]
	v_mfma_f32_16x16x32_bf16 v[36:39], v[200:203], v[174:177], v[36:39]
	v_mfma_f32_16x16x32_bf16 v[32:35], v[208:211], v[174:177], v[32:35]
	v_mfma_f32_16x16x32_bf16 v[20:23], v[200:203], v[184:187], v[20:23]
	v_mfma_f32_16x16x32_bf16 v[16:19], v[208:211], v[184:187], v[16:19]
	v_mfma_f32_16x16x32_bf16 v[4:7], v[200:203], v[192:195], v[4:7]
	v_mfma_f32_16x16x32_bf16 v[0:3], v[208:211], v[192:195], v[0:3]
	s_setprio 0
	s_add_i32 s59, s59, 2
	s_add_u32 s57, s57, 0x100
	s_addc_u32 s58, s58, 0
	s_cmp_gt_u32 s59, 13
	s_mov_b64 s[28:29], s[30:31]
	s_barrier
	s_cbranch_scc0 .LBB0_1377
	v_lshl_add_u32 v142, s24, 8, v144
	v_ashrrev_i32_e32 v143, 31, v142
	v_lshl_or_b32 v140, s26, 8, v146
	v_lshlrev_b64 v[150:151], 12, v[142:143]
	v_lshl_add_u64 v[150:151], s[66:67], 0, v[150:151]
	v_ashrrev_i32_e32 v141, 31, v140
	v_lshl_add_u64 v[154:155], v[140:141], 2, v[150:151]
	s_mov_b64 s[98:99], 0x10000
	s_mov_b64 s[100:101], 0x80000
	v_mov_b64_e32 v[196:197], v[154:155]
	v_lshl_add_u64 v[200:201], v[154:155], 0, s[100:101]
	v_lshl_add_u64 v[198:199], v[154:155], 0, s[98:99]
	global_load_dwordx4 v[180:183], v[154:155], off
	global_load_dwordx4 v[184:187], v[154:155], off offset:64
	global_load_dwordx4 v[188:191], v[154:155], off offset:512
	global_load_dwordx4 v[192:195], v[154:155], off offset:576
	global_load_dwordx4 v[212:215], v[198:199], off
	global_load_dwordx4 v[216:219], v[198:199], off offset:64
	global_load_dwordx4 v[220:223], v[198:199], off offset:512
	global_load_dwordx4 v[224:227], v[198:199], off offset:576
	v_lshlrev_b64 v[156:157], 11, v[142:143]
	v_lshl_add_u64 v[156:157], s[68:69], 0, v[156:157]
	v_lshl_add_u64 v[156:157], v[140:141], 1, v[156:157]
	s_waitcnt vmcnt(7)
	v_pk_add_f32 v[126:127], v[126:127], v[182:183]
	v_pk_add_f32 v[124:125], v[124:125], v[180:181]
	v_cvt_pk_bf16_f32 v151, v126, v127
	v_cvt_pk_bf16_f32 v150, v124, v125
	global_store_dwordx4 v[154:155], v[124:127], off
	global_store_dwordx2 v[156:157], v[150:151], off
	s_nop 0
	v_mul_f32_e32 v125, v125, v125
	v_fmac_f32_e32 v125, v124, v124
	v_fmac_f32_e32 v125, v126, v126
	v_fmac_f32_e32 v125, v127, v127
	s_waitcnt vmcnt(8)
	v_pk_add_f32 v[122:123], v[122:123], v[186:187]
	v_pk_add_f32 v[120:121], v[120:121], v[184:185]
	v_cvt_pk_bf16_f32 v151, v122, v123
	v_cvt_pk_bf16_f32 v150, v120, v121
	global_store_dwordx4 v[154:155], v[120:123], off offset:64
	global_store_dwordx2 v[156:157], v[150:151], off offset:32
	s_nop 0
	v_mul_f32_e32 v121, v121, v121
	v_fmac_f32_e32 v121, v120, v120
	v_fmac_f32_e32 v121, v122, v122
	v_fmac_f32_e32 v121, v123, v123
	v_add_f32_e32 v120, v125, v121
	s_waitcnt vmcnt(9)
	v_pk_add_f32 v[118:119], v[118:119], v[190:191]
	v_pk_add_f32 v[116:117], v[116:117], v[188:189]
	v_cvt_pk_bf16_f32 v151, v118, v119
	v_cvt_pk_bf16_f32 v150, v116, v117
	global_store_dwordx4 v[154:155], v[116:119], off offset:512
	global_store_dwordx2 v[156:157], v[150:151], off offset:256
	s_nop 0
	v_mul_f32_e32 v117, v117, v117
	v_fmac_f32_e32 v117, v116, v116
	v_fmac_f32_e32 v117, v118, v118
	v_fmac_f32_e32 v117, v119, v119
	v_add_f32_e32 v118, v120, v117
	s_waitcnt vmcnt(10)
	v_pk_add_f32 v[114:115], v[114:115], v[194:195]
	v_pk_add_f32 v[112:113], v[112:113], v[192:193]
	global_store_dwordx4 v[154:155], v[112:115], off offset:576
	v_cvt_pk_bf16_f32 v116, v112, v113
	v_cvt_pk_bf16_f32 v117, v114, v115
	v_mul_f32_e32 v113, v113, v113
	v_fmac_f32_e32 v113, v112, v112
	v_fmac_f32_e32 v113, v114, v114
	v_fmac_f32_e32 v113, v115, v115
	v_add_f32_e32 v112, v118, v113
	v_mov_b32_e32 v113, v112
	s_nop 1
	v_permlane16_swap_b32_e32 v112, v113
	v_add_f32_e32 v112, v112, v113
	v_mov_b32_e32 v113, v112
	s_nop 1
	v_permlane32_swap_b32_e32 v112, v113
	global_store_dwordx2 v[156:157], v[116:117], off offset:288
	s_and_saveexec_b64 s[24:25], s[6:7]
	s_cbranch_execz .LBB0_1380
	v_lshl_add_u64 v[114:115], v[142:143], 2, s[10:11]
	v_add_f32_e32 v112, v112, v113
	global_atomic_add_f32 v[114:115], v112, off
; DI unsigned pk2(float a, float b) { f32x2 v = {a, b}; hbf2 r = __builtin_convertvector(v, hbf2); return __builtin_bit_cast(unsigned, r); }
; DI float sum_x16_x32(float x) { return sum_x32(sum_x16(x)); }
;     DI void operator()(const f32x4 (&acc)[2][2][4][2], const Unit& u, int wr, int wc, int fr, int fq) const {
;     ...
; #pragma unroll
;         for (int ai = 0; ai < 2; ++ai)
; #pragma unroll
;             for (int m = 0; m < 4; ++m) {
;                 const int r = row0 + ai * 128 + m * 16;
;                 const float* rp;
;                 if (MODE == 0) rp = x + (size_t)r * 1024;
;                 else rp = h + (size_t)r * 1024;
;                 float sq = 0.f;
; #pragma unroll
;                 for (int bj = 0; bj < 2; ++bj)
; #pragma unroll
;                     for (int n = 0; n < 2; ++n) {
;                         const int c = col0 + bj * 128 + n * 16;
;                         f32x4 rv = rp ? *(const f32x4*)(rp + c) : (f32x4){0.f, 0.f, 0.f, 0.f};
;                         f32x4 v = acc[ai][bj][m][n] + rv;
;                         *(f32x4*)(h + (size_t)r * 1024 + c) = v;
;                         if (WRITE_HB) {
;                             u32x2 w; w.x = pk2(v[0], v[1]); w.y = pk2(v[2], v[3]);
;                             *(u32x2*)(hb + (size_t)r * 1024 + c) = w;
;                         }
;                         sq += v[0] * v[0] + v[1] * v[1] + v[2] * v[2] + v[3] * v[3];
;                     }
;                 sq = sum_x16_x32(sq);
;                 if (fq == 0) atomicAdd(ss + r, sq);
;             }
.LBB0_1380:
	s_or_b64 exec, exec, s[24:25]
	v_or_b32_e32 v112, 16, v142
	v_ashrrev_i32_e32 v113, 31, v112
	v_lshlrev_b64 v[114:115], 12, v[112:113]
	v_lshl_add_u64 v[114:115], s[66:67], 0, v[114:115]
	v_lshl_add_u64 v[118:119], v[140:141], 2, v[114:115]
	v_lshl_add_u64 v[198:199], v[198:199], 0, s[98:99]
	global_load_dwordx4 v[180:183], v[198:199], off
	global_load_dwordx4 v[184:187], v[198:199], off offset:64
	global_load_dwordx4 v[188:191], v[198:199], off offset:512
	global_load_dwordx4 v[192:195], v[198:199], off offset:576
	v_lshlrev_b64 v[120:121], 11, v[112:113]
	v_lshl_add_u64 v[120:121], s[68:69], 0, v[120:121]
	v_lshl_add_u64 v[120:121], v[140:141], 1, v[120:121]
	s_waitcnt vmcnt(15)
	v_pk_add_f32 v[110:111], v[110:111], v[214:215]
	v_pk_add_f32 v[108:109], v[108:109], v[212:213]
	v_cvt_pk_bf16_f32 v115, v110, v111
	v_cvt_pk_bf16_f32 v114, v108, v109
	global_store_dwordx4 v[118:119], v[108:111], off
	global_store_dwordx2 v[120:121], v[114:115], off
	s_nop 0
	v_mul_f32_e32 v109, v109, v109
	v_fmac_f32_e32 v109, v108, v108
	v_fmac_f32_e32 v109, v110, v110
	v_fmac_f32_e32 v109, v111, v111
	s_waitcnt vmcnt(16)
	v_pk_add_f32 v[106:107], v[106:107], v[218:219]
	v_pk_add_f32 v[104:105], v[104:105], v[216:217]
	v_cvt_pk_bf16_f32 v115, v106, v107
	v_cvt_pk_bf16_f32 v114, v104, v105
	global_store_dwordx4 v[118:119], v[104:107], off offset:64
	global_store_dwordx2 v[120:121], v[114:115], off offset:32
	s_nop 0
	v_mul_f32_e32 v105, v105, v105
	v_fmac_f32_e32 v105, v104, v104
	v_fmac_f32_e32 v105, v106, v106
	v_fmac_f32_e32 v105, v107, v107
	v_add_f32_e32 v104, v109, v105
	s_waitcnt vmcnt(17)
	v_pk_add_f32 v[102:103], v[102:103], v[222:223]
	v_pk_add_f32 v[100:101], v[100:101], v[220:221]
	v_cvt_pk_bf16_f32 v115, v102, v103
	v_cvt_pk_bf16_f32 v114, v100, v101
	global_store_dwordx4 v[118:119], v[100:103], off offset:512
	global_store_dwordx2 v[120:121], v[114:115], off offset:256
	s_nop 0
	v_mul_f32_e32 v101, v101, v101
	v_fmac_f32_e32 v101, v100, v100
	v_fmac_f32_e32 v101, v102, v102
	v_fmac_f32_e32 v101, v103, v103
	v_add_f32_e32 v102, v104, v101
	s_waitcnt vmcnt(18)
	v_pk_add_f32 v[98:99], v[98:99], v[226:227]
	v_pk_add_f32 v[96:97], v[96:97], v[224:225]
	global_store_dwordx4 v[118:119], v[96:99], off offset:576
	v_cvt_pk_bf16_f32 v100, v96, v97
	v_cvt_pk_bf16_f32 v101, v98, v99
	v_mul_f32_e32 v97, v97, v97
	v_fmac_f32_e32 v97, v96, v96
	v_fmac_f32_e32 v97, v98, v98
	v_fmac_f32_e32 v97, v99, v99
	v_add_f32_e32 v96, v102, v97
	v_mov_b32_e32 v97, v96
	s_nop 1
	v_permlane16_swap_b32_e32 v96, v97
	v_add_f32_e32 v96, v96, v97
	v_mov_b32_e32 v97, v96
	s_nop 1
	v_permlane32_swap_b32_e32 v96, v97
	global_store_dwordx2 v[120:121], v[100:101], off offset:288
	s_and_saveexec_b64 s[24:25], s[6:7]
	s_cbranch_execz .LBB0_1382
	v_lshl_add_u64 v[98:99], v[112:113], 2, s[10:11]
	v_add_f32_e32 v96, v96, v97
	global_atomic_add_f32 v[98:99], v96, off
.LBB0_1382:
	s_or_b64 exec, exec, s[24:25]
	v_or_b32_e32 v96, 32, v142
	v_ashrrev_i32_e32 v97, 31, v96
	v_lshlrev_b64 v[98:99], 12, v[96:97]
	v_lshl_add_u64 v[98:99], s[66:67], 0, v[98:99]
	v_lshl_add_u64 v[102:103], v[140:141], 2, v[98:99]
	v_lshl_add_u64 v[198:199], v[198:199], 0, s[98:99]
	global_load_dwordx4 v[212:215], v[198:199], off
	global_load_dwordx4 v[216:219], v[198:199], off offset:64
	global_load_dwordx4 v[220:223], v[198:199], off offset:512
	global_load_dwordx4 v[224:227], v[198:199], off offset:576
	v_lshlrev_b64 v[104:105], 11, v[96:97]
	v_lshl_add_u64 v[104:105], s[68:69], 0, v[104:105]
	v_lshl_add_u64 v[104:105], v[140:141], 1, v[104:105]
	s_waitcnt vmcnt(15)
	v_pk_add_f32 v[94:95], v[94:95], v[182:183]
	v_pk_add_f32 v[92:93], v[92:93], v[180:181]
	v_cvt_pk_bf16_f32 v99, v94, v95
	v_cvt_pk_bf16_f32 v98, v92, v93
	global_store_dwordx4 v[102:103], v[92:95], off
	global_store_dwordx2 v[104:105], v[98:99], off
	s_nop 0
	v_mul_f32_e32 v93, v93, v93
	v_fmac_f32_e32 v93, v92, v92
	v_fmac_f32_e32 v93, v94, v94
	v_fmac_f32_e32 v93, v95, v95
	s_waitcnt vmcnt(16)
	v_pk_add_f32 v[90:91], v[90:91], v[186:187]
	v_pk_add_f32 v[88:89], v[88:89], v[184:185]
	v_cvt_pk_bf16_f32 v99, v90, v91
	v_cvt_pk_bf16_f32 v98, v88, v89
	global_store_dwordx4 v[102:103], v[88:91], off offset:64
	global_store_dwordx2 v[104:105], v[98:99], off offset:32
	s_nop 0
	v_mul_f32_e32 v89, v89, v89
	v_fmac_f32_e32 v89, v88, v88
	v_fmac_f32_e32 v89, v90, v90
	v_fmac_f32_e32 v89, v91, v91
	v_add_f32_e32 v88, v93, v89
	s_waitcnt vmcnt(17)
	v_pk_add_f32 v[86:87], v[86:87], v[190:191]
	v_pk_add_f32 v[84:85], v[84:85], v[188:189]
	v_cvt_pk_bf16_f32 v99, v86, v87
	v_cvt_pk_bf16_f32 v98, v84, v85
	global_store_dwordx4 v[102:103], v[84:87], off offset:512
	global_store_dwordx2 v[104:105], v[98:99], off offset:256
	s_nop 0
	v_mul_f32_e32 v85, v85, v85
	v_fmac_f32_e32 v85, v84, v84
	v_fmac_f32_e32 v85, v86, v86
	v_fmac_f32_e32 v85, v87, v87
	v_add_f32_e32 v86, v88, v85
	s_waitcnt vmcnt(18)
	v_pk_add_f32 v[82:83], v[82:83], v[194:195]
	v_pk_add_f32 v[80:81], v[80:81], v[192:193]
	global_store_dwordx4 v[102:103], v[80:83], off offset:576
	v_cvt_pk_bf16_f32 v84, v80, v81
	v_cvt_pk_bf16_f32 v85, v82, v83
	v_mul_f32_e32 v81, v81, v81
	v_fmac_f32_e32 v81, v80, v80
	v_fmac_f32_e32 v81, v82, v82
	v_fmac_f32_e32 v81, v83, v83
	v_add_f32_e32 v80, v86, v81
	v_mov_b32_e32 v81, v80
	s_nop 1
	v_permlane16_swap_b32_e32 v80, v81
	v_add_f32_e32 v80, v80, v81
	v_mov_b32_e32 v81, v80
	s_nop 1
	v_permlane32_swap_b32_e32 v80, v81
	global_store_dwordx2 v[104:105], v[84:85], off offset:288
	s_and_saveexec_b64 s[24:25], s[6:7]
	s_cbranch_execz .LBB0_1384
	v_lshl_add_u64 v[82:83], v[96:97], 2, s[10:11]
	v_add_f32_e32 v80, v80, v81
	global_atomic_add_f32 v[82:83], v80, off
; DI unsigned pk2(float a, float b) { f32x2 v = {a, b}; hbf2 r = __builtin_convertvector(v, hbf2); return __builtin_bit_cast(unsigned, r); }
; DI float sum_x16_x32(float x) { return sum_x32(sum_x16(x)); }
;     DI void operator()(const f32x4 (&acc)[2][2][4][2], const Unit& u, int wr, int wc, int fr, int fq) const {
;     ...
; #pragma unroll
;         for (int ai = 0; ai < 2; ++ai)
; #pragma unroll
;             for (int m = 0; m < 4; ++m) {
;                 const int r = row0 + ai * 128 + m * 16;
;                 const float* rp;
;                 if (MODE == 0) rp = x + (size_t)r * 1024;
;                 else rp = h + (size_t)r * 1024;
;                 float sq = 0.f;
; #pragma unroll
;                 for (int bj = 0; bj < 2; ++bj)
; #pragma unroll
;                     for (int n = 0; n < 2; ++n) {
;                         const int c = col0 + bj * 128 + n * 16;
;                         f32x4 rv = rp ? *(const f32x4*)(rp + c) : (f32x4){0.f, 0.f, 0.f, 0.f};
;                         f32x4 v = acc[ai][bj][m][n] + rv;
;                         *(f32x4*)(h + (size_t)r * 1024 + c) = v;
;                         if (WRITE_HB) {
;                             u32x2 w; w.x = pk2(v[0], v[1]); w.y = pk2(v[2], v[3]);
;                             *(u32x2*)(hb + (size_t)r * 1024 + c) = w;
;                         }
;                         sq += v[0] * v[0] + v[1] * v[1] + v[2] * v[2] + v[3] * v[3];
;                     }
;                 sq = sum_x16_x32(sq);
;                 if (fq == 0) atomicAdd(ss + r, sq);
;             }
.LBB0_1384:
	s_or_b64 exec, exec, s[24:25]
	v_or_b32_e32 v80, 48, v142
	v_ashrrev_i32_e32 v81, 31, v80
	v_lshlrev_b64 v[82:83], 12, v[80:81]
	v_lshl_add_u64 v[82:83], s[66:67], 0, v[82:83]
	v_lshl_add_u64 v[86:87], v[140:141], 2, v[82:83]
	v_mov_b64_e32 v[198:199], v[200:201]
	global_load_dwordx4 v[180:183], v[198:199], off
	global_load_dwordx4 v[184:187], v[198:199], off offset:64
	global_load_dwordx4 v[188:191], v[198:199], off offset:512
	global_load_dwordx4 v[192:195], v[198:199], off offset:576
	v_lshlrev_b64 v[88:89], 11, v[80:81]
	v_lshl_add_u64 v[88:89], s[68:69], 0, v[88:89]
	v_lshl_add_u64 v[88:89], v[140:141], 1, v[88:89]
	s_waitcnt vmcnt(15)
	v_pk_add_f32 v[78:79], v[78:79], v[214:215]
	v_pk_add_f32 v[76:77], v[76:77], v[212:213]
	v_cvt_pk_bf16_f32 v83, v78, v79
	v_cvt_pk_bf16_f32 v82, v76, v77
	global_store_dwordx4 v[86:87], v[76:79], off
	global_store_dwordx2 v[88:89], v[82:83], off
	s_nop 0
	v_mul_f32_e32 v77, v77, v77
	v_fmac_f32_e32 v77, v76, v76
	v_fmac_f32_e32 v77, v78, v78
	v_fmac_f32_e32 v77, v79, v79
	s_waitcnt vmcnt(16)
	v_pk_add_f32 v[74:75], v[74:75], v[218:219]
	v_pk_add_f32 v[72:73], v[72:73], v[216:217]
	v_cvt_pk_bf16_f32 v83, v74, v75
	v_cvt_pk_bf16_f32 v82, v72, v73
	global_store_dwordx4 v[86:87], v[72:75], off offset:64
	global_store_dwordx2 v[88:89], v[82:83], off offset:32
	s_nop 0
	v_mul_f32_e32 v73, v73, v73
	v_fmac_f32_e32 v73, v72, v72
	v_fmac_f32_e32 v73, v74, v74
	v_fmac_f32_e32 v73, v75, v75
	v_add_f32_e32 v72, v77, v73
	s_waitcnt vmcnt(17)
	v_pk_add_f32 v[70:71], v[70:71], v[222:223]
	v_pk_add_f32 v[68:69], v[68:69], v[220:221]
	v_cvt_pk_bf16_f32 v83, v70, v71
	v_cvt_pk_bf16_f32 v82, v68, v69
	global_store_dwordx4 v[86:87], v[68:71], off offset:512
	global_store_dwordx2 v[88:89], v[82:83], off offset:256
	s_nop 0
	v_mul_f32_e32 v69, v69, v69
	v_fmac_f32_e32 v69, v68, v68
	v_fmac_f32_e32 v69, v70, v70
	v_fmac_f32_e32 v69, v71, v71
	v_add_f32_e32 v70, v72, v69
	s_waitcnt vmcnt(18)
	v_pk_add_f32 v[66:67], v[66:67], v[226:227]
	v_pk_add_f32 v[64:65], v[64:65], v[224:225]
	global_store_dwordx4 v[86:87], v[64:67], off offset:576
	v_cvt_pk_bf16_f32 v68, v64, v65
	v_cvt_pk_bf16_f32 v69, v66, v67
	v_mul_f32_e32 v65, v65, v65
	v_fmac_f32_e32 v65, v64, v64
	v_fmac_f32_e32 v65, v66, v66
	v_fmac_f32_e32 v65, v67, v67
	v_add_f32_e32 v64, v70, v65
	v_mov_b32_e32 v65, v64
	s_nop 1
	v_permlane16_swap_b32_e32 v64, v65
	v_add_f32_e32 v64, v64, v65
	v_mov_b32_e32 v65, v64
	s_nop 1
	v_permlane32_swap_b32_e32 v64, v65
	global_store_dwordx2 v[88:89], v[68:69], off offset:288
	s_and_saveexec_b64 s[24:25], s[6:7]
	s_cbranch_execz .LBB0_1386
	v_lshl_add_u64 v[66:67], v[80:81], 2, s[10:11]
	v_add_f32_e32 v64, v64, v65
	global_atomic_add_f32 v[66:67], v64, off
.LBB0_1386:
	s_or_b64 exec, exec, s[24:25]
	v_add_u32_e32 v64, 0x80, v142
	v_ashrrev_i32_e32 v65, 31, v64
	v_lshlrev_b64 v[66:67], 12, v[64:65]
	v_lshl_add_u64 v[66:67], s[66:67], 0, v[66:67]
	v_lshl_add_u64 v[70:71], v[140:141], 2, v[66:67]
	v_lshl_add_u64 v[198:199], v[198:199], 0, s[98:99]
	global_load_dwordx4 v[212:215], v[198:199], off
	global_load_dwordx4 v[216:219], v[198:199], off offset:64
	global_load_dwordx4 v[220:223], v[198:199], off offset:512
	global_load_dwordx4 v[224:227], v[198:199], off offset:576
	v_lshlrev_b64 v[72:73], 11, v[64:65]
	v_lshl_add_u64 v[72:73], s[68:69], 0, v[72:73]
	v_lshl_add_u64 v[72:73], v[140:141], 1, v[72:73]
	s_waitcnt vmcnt(15)
	v_pk_add_f32 v[62:63], v[62:63], v[182:183]
	v_pk_add_f32 v[60:61], v[60:61], v[180:181]
	v_cvt_pk_bf16_f32 v67, v62, v63
	v_cvt_pk_bf16_f32 v66, v60, v61
	global_store_dwordx4 v[70:71], v[60:63], off
	global_store_dwordx2 v[72:73], v[66:67], off
	s_nop 0
	v_mul_f32_e32 v61, v61, v61
	v_fmac_f32_e32 v61, v60, v60
	v_fmac_f32_e32 v61, v62, v62
	v_fmac_f32_e32 v61, v63, v63
	s_waitcnt vmcnt(16)
	v_pk_add_f32 v[58:59], v[58:59], v[186:187]
	v_pk_add_f32 v[56:57], v[56:57], v[184:185]
	v_cvt_pk_bf16_f32 v67, v58, v59
	v_cvt_pk_bf16_f32 v66, v56, v57
	global_store_dwordx4 v[70:71], v[56:59], off offset:64
	global_store_dwordx2 v[72:73], v[66:67], off offset:32
	s_nop 0
	v_mul_f32_e32 v57, v57, v57
	v_fmac_f32_e32 v57, v56, v56
	v_fmac_f32_e32 v57, v58, v58
	v_fmac_f32_e32 v57, v59, v59
	v_add_f32_e32 v56, v61, v57
	s_waitcnt vmcnt(17)
	v_pk_add_f32 v[54:55], v[54:55], v[190:191]
	v_pk_add_f32 v[52:53], v[52:53], v[188:189]
	v_cvt_pk_bf16_f32 v67, v54, v55
	v_cvt_pk_bf16_f32 v66, v52, v53
	global_store_dwordx4 v[70:71], v[52:55], off offset:512
	global_store_dwordx2 v[72:73], v[66:67], off offset:256
	s_nop 0
	v_mul_f32_e32 v53, v53, v53
	v_fmac_f32_e32 v53, v52, v52
	v_fmac_f32_e32 v53, v54, v54
	v_fmac_f32_e32 v53, v55, v55
	v_add_f32_e32 v54, v56, v53
	s_waitcnt vmcnt(18)
	v_pk_add_f32 v[50:51], v[50:51], v[194:195]
	v_pk_add_f32 v[48:49], v[48:49], v[192:193]
	global_store_dwordx4 v[70:71], v[48:51], off offset:576
	v_cvt_pk_bf16_f32 v52, v48, v49
	v_cvt_pk_bf16_f32 v53, v50, v51
	v_mul_f32_e32 v49, v49, v49
	v_fmac_f32_e32 v49, v48, v48
	v_fmac_f32_e32 v49, v50, v50
	v_fmac_f32_e32 v49, v51, v51
	v_add_f32_e32 v48, v54, v49
	v_mov_b32_e32 v49, v48
	s_nop 1
	v_permlane16_swap_b32_e32 v48, v49
	v_add_f32_e32 v48, v48, v49
	v_mov_b32_e32 v49, v48
	s_nop 1
	v_permlane32_swap_b32_e32 v48, v49
	global_store_dwordx2 v[72:73], v[52:53], off offset:288
	s_and_saveexec_b64 s[24:25], s[6:7]
	s_cbranch_execz .LBB0_1388
	v_lshl_add_u64 v[50:51], v[64:65], 2, s[10:11]
	v_add_f32_e32 v48, v48, v49
	global_atomic_add_f32 v[50:51], v48, off
; DI unsigned pk2(float a, float b) { f32x2 v = {a, b}; hbf2 r = __builtin_convertvector(v, hbf2); return __builtin_bit_cast(unsigned, r); }
; DI float sum_x16_x32(float x) { return sum_x32(sum_x16(x)); }
;     DI void operator()(const f32x4 (&acc)[2][2][4][2], const Unit& u, int wr, int wc, int fr, int fq) const {
;     ...
; #pragma unroll
;         for (int ai = 0; ai < 2; ++ai)
; #pragma unroll
;             for (int m = 0; m < 4; ++m) {
;                 const int r = row0 + ai * 128 + m * 16;
;                 const float* rp;
;                 if (MODE == 0) rp = x + (size_t)r * 1024;
;                 else rp = h + (size_t)r * 1024;
;                 float sq = 0.f;
; #pragma unroll
;                 for (int bj = 0; bj < 2; ++bj)
; #pragma unroll
;                     for (int n = 0; n < 2; ++n) {
;                         const int c = col0 + bj * 128 + n * 16;
;                         f32x4 rv = rp ? *(const f32x4*)(rp + c) : (f32x4){0.f, 0.f, 0.f, 0.f};
;                         f32x4 v = acc[ai][bj][m][n] + rv;
;                         *(f32x4*)(h + (size_t)r * 1024 + c) = v;
;                         if (WRITE_HB) {
;                             u32x2 w; w.x = pk2(v[0], v[1]); w.y = pk2(v[2], v[3]);
;                             *(u32x2*)(hb + (size_t)r * 1024 + c) = w;
;                         }
;                         sq += v[0] * v[0] + v[1] * v[1] + v[2] * v[2] + v[3] * v[3];
;                     }
;                 sq = sum_x16_x32(sq);
;                 if (fq == 0) atomicAdd(ss + r, sq);
;             }
.LBB0_1388:
	s_or_b64 exec, exec, s[24:25]
	v_add_u32_e32 v48, 0x90, v142
	v_ashrrev_i32_e32 v49, 31, v48
	v_lshlrev_b64 v[50:51], 12, v[48:49]
	v_lshl_add_u64 v[50:51], s[66:67], 0, v[50:51]
	v_lshl_add_u64 v[54:55], v[140:141], 2, v[50:51]
	v_lshl_add_u64 v[198:199], v[198:199], 0, s[98:99]
	global_load_dwordx4 v[180:183], v[198:199], off
	global_load_dwordx4 v[184:187], v[198:199], off offset:64
	global_load_dwordx4 v[188:191], v[198:199], off offset:512
	global_load_dwordx4 v[192:195], v[198:199], off offset:576
	v_lshlrev_b64 v[56:57], 11, v[48:49]
	v_lshl_add_u64 v[56:57], s[68:69], 0, v[56:57]
	v_lshl_add_u64 v[56:57], v[140:141], 1, v[56:57]
	s_waitcnt vmcnt(15)
	v_pk_add_f32 v[46:47], v[46:47], v[214:215]
	v_pk_add_f32 v[44:45], v[44:45], v[212:213]
	v_cvt_pk_bf16_f32 v51, v46, v47
	v_cvt_pk_bf16_f32 v50, v44, v45
	global_store_dwordx4 v[54:55], v[44:47], off
	global_store_dwordx2 v[56:57], v[50:51], off
	s_nop 0
	v_mul_f32_e32 v45, v45, v45
	v_fmac_f32_e32 v45, v44, v44
	v_fmac_f32_e32 v45, v46, v46
	v_fmac_f32_e32 v45, v47, v47
	s_waitcnt vmcnt(16)
	v_pk_add_f32 v[42:43], v[42:43], v[218:219]
	v_pk_add_f32 v[40:41], v[40:41], v[216:217]
	v_cvt_pk_bf16_f32 v51, v42, v43
	v_cvt_pk_bf16_f32 v50, v40, v41
	global_store_dwordx4 v[54:55], v[40:43], off offset:64
	global_store_dwordx2 v[56:57], v[50:51], off offset:32
	s_nop 0
	v_mul_f32_e32 v41, v41, v41
	v_fmac_f32_e32 v41, v40, v40
	v_fmac_f32_e32 v41, v42, v42
	v_fmac_f32_e32 v41, v43, v43
	v_add_f32_e32 v40, v45, v41
	s_waitcnt vmcnt(17)
	v_pk_add_f32 v[38:39], v[38:39], v[222:223]
	v_pk_add_f32 v[36:37], v[36:37], v[220:221]
	v_cvt_pk_bf16_f32 v51, v38, v39
	v_cvt_pk_bf16_f32 v50, v36, v37
	global_store_dwordx4 v[54:55], v[36:39], off offset:512
	global_store_dwordx2 v[56:57], v[50:51], off offset:256
	s_nop 0
	v_mul_f32_e32 v37, v37, v37
	v_fmac_f32_e32 v37, v36, v36
	v_fmac_f32_e32 v37, v38, v38
	v_fmac_f32_e32 v37, v39, v39
	v_add_f32_e32 v38, v40, v37
	s_waitcnt vmcnt(18)
	v_pk_add_f32 v[34:35], v[34:35], v[226:227]
	v_pk_add_f32 v[32:33], v[32:33], v[224:225]
	global_store_dwordx4 v[54:55], v[32:35], off offset:576
	v_cvt_pk_bf16_f32 v36, v32, v33
	v_cvt_pk_bf16_f32 v37, v34, v35
	v_mul_f32_e32 v33, v33, v33
	v_fmac_f32_e32 v33, v32, v32
	v_fmac_f32_e32 v33, v34, v34
	v_fmac_f32_e32 v33, v35, v35
	v_add_f32_e32 v32, v38, v33
	v_mov_b32_e32 v33, v32
	s_nop 1
	v_permlane16_swap_b32_e32 v32, v33
	v_add_f32_e32 v32, v32, v33
	v_mov_b32_e32 v33, v32
	s_nop 1
	v_permlane32_swap_b32_e32 v32, v33
	global_store_dwordx2 v[56:57], v[36:37], off offset:288
	s_and_saveexec_b64 s[24:25], s[6:7]
	s_cbranch_execz .LBB0_1390
	v_lshl_add_u64 v[34:35], v[48:49], 2, s[10:11]
	v_add_f32_e32 v32, v32, v33
	global_atomic_add_f32 v[34:35], v32, off
; DI unsigned pk2(float a, float b) { f32x2 v = {a, b}; hbf2 r = __builtin_convertvector(v, hbf2); return __builtin_bit_cast(unsigned, r); }
; DI float sum_x16_x32(float x) { return sum_x32(sum_x16(x)); }
;     DI void operator()(const f32x4 (&acc)[2][2][4][2], const Unit& u, int wr, int wc, int fr, int fq) const {
;     ...
; #pragma unroll
;         for (int ai = 0; ai < 2; ++ai)
; #pragma unroll
;             for (int m = 0; m < 4; ++m) {
;                 const int r = row0 + ai * 128 + m * 16;
;                 const float* rp;
;                 if (MODE == 0) rp = x + (size_t)r * 1024;
;                 else rp = h + (size_t)r * 1024;
;                 float sq = 0.f;
; #pragma unroll
;                 for (int bj = 0; bj < 2; ++bj)
; #pragma unroll
;                     for (int n = 0; n < 2; ++n) {
;                         const int c = col0 + bj * 128 + n * 16;
;                         f32x4 rv = rp ? *(const f32x4*)(rp + c) : (f32x4){0.f, 0.f, 0.f, 0.f};
;                         f32x4 v = acc[ai][bj][m][n] + rv;
;                         *(f32x4*)(h + (size_t)r * 1024 + c) = v;
;                         if (WRITE_HB) {
;                             u32x2 w; w.x = pk2(v[0], v[1]); w.y = pk2(v[2], v[3]);
;                             *(u32x2*)(hb + (size_t)r * 1024 + c) = w;
;                         }
;                         sq += v[0] * v[0] + v[1] * v[1] + v[2] * v[2] + v[3] * v[3];
;                     }
;                 sq = sum_x16_x32(sq);
;                 if (fq == 0) atomicAdd(ss + r, sq);
;             }
.LBB0_1390:
	s_or_b64 exec, exec, s[24:25]
	v_add_u32_e32 v32, 0xa0, v142
	v_ashrrev_i32_e32 v33, 31, v32
	v_lshlrev_b64 v[34:35], 12, v[32:33]
	v_lshl_add_u64 v[34:35], s[66:67], 0, v[34:35]
	v_lshl_add_u64 v[38:39], v[140:141], 2, v[34:35]
	v_lshl_add_u64 v[198:199], v[198:199], 0, s[98:99]
	global_load_dwordx4 v[212:215], v[198:199], off
	global_load_dwordx4 v[216:219], v[198:199], off offset:64
	global_load_dwordx4 v[220:223], v[198:199], off offset:512
	global_load_dwordx4 v[224:227], v[198:199], off offset:576
	v_lshlrev_b64 v[40:41], 11, v[32:33]
	v_lshl_add_u64 v[40:41], s[68:69], 0, v[40:41]
	v_lshl_add_u64 v[40:41], v[140:141], 1, v[40:41]
	s_waitcnt vmcnt(15)
	v_pk_add_f32 v[30:31], v[30:31], v[182:183]
	v_pk_add_f32 v[28:29], v[28:29], v[180:181]
	v_cvt_pk_bf16_f32 v35, v30, v31
	v_cvt_pk_bf16_f32 v34, v28, v29
	global_store_dwordx4 v[38:39], v[28:31], off
	global_store_dwordx2 v[40:41], v[34:35], off
	s_nop 0
	v_mul_f32_e32 v29, v29, v29
	v_fmac_f32_e32 v29, v28, v28
	v_fmac_f32_e32 v29, v30, v30
	v_fmac_f32_e32 v29, v31, v31
	s_waitcnt vmcnt(16)
	v_pk_add_f32 v[26:27], v[26:27], v[186:187]
	v_pk_add_f32 v[24:25], v[24:25], v[184:185]
	v_cvt_pk_bf16_f32 v35, v26, v27
	v_cvt_pk_bf16_f32 v34, v24, v25
	global_store_dwordx4 v[38:39], v[24:27], off offset:64
	global_store_dwordx2 v[40:41], v[34:35], off offset:32
	s_nop 0
	v_mul_f32_e32 v25, v25, v25
	v_fmac_f32_e32 v25, v24, v24
	v_fmac_f32_e32 v25, v26, v26
	v_fmac_f32_e32 v25, v27, v27
	v_add_f32_e32 v24, v29, v25
	s_waitcnt vmcnt(17)
	v_pk_add_f32 v[22:23], v[22:23], v[190:191]
	v_pk_add_f32 v[20:21], v[20:21], v[188:189]
	v_cvt_pk_bf16_f32 v35, v22, v23
	v_cvt_pk_bf16_f32 v34, v20, v21
	global_store_dwordx4 v[38:39], v[20:23], off offset:512
	global_store_dwordx2 v[40:41], v[34:35], off offset:256
	s_nop 0
	v_mul_f32_e32 v21, v21, v21
	v_fmac_f32_e32 v21, v20, v20
	v_fmac_f32_e32 v21, v22, v22
	v_fmac_f32_e32 v21, v23, v23
	v_add_f32_e32 v22, v24, v21
	s_waitcnt vmcnt(18)
	v_pk_add_f32 v[18:19], v[18:19], v[194:195]
	v_pk_add_f32 v[16:17], v[16:17], v[192:193]
	global_store_dwordx4 v[38:39], v[16:19], off offset:576
	v_cvt_pk_bf16_f32 v20, v16, v17
	v_cvt_pk_bf16_f32 v21, v18, v19
	v_mul_f32_e32 v17, v17, v17
	v_fmac_f32_e32 v17, v16, v16
	v_fmac_f32_e32 v17, v18, v18
	v_fmac_f32_e32 v17, v19, v19
	v_add_f32_e32 v16, v22, v17
	v_mov_b32_e32 v17, v16
	s_nop 1
	v_permlane16_swap_b32_e32 v16, v17
	v_add_f32_e32 v16, v16, v17
	v_mov_b32_e32 v17, v16
	s_nop 1
	v_permlane32_swap_b32_e32 v16, v17
	global_store_dwordx2 v[40:41], v[20:21], off offset:288
	s_and_saveexec_b64 s[24:25], s[6:7]
	s_cbranch_execz .LBB0_1392
	v_lshl_add_u64 v[18:19], v[32:33], 2, s[10:11]
	v_add_f32_e32 v16, v16, v17
	global_atomic_add_f32 v[18:19], v16, off
.LBB0_1392:
	s_or_b64 exec, exec, s[24:25]
	v_add_u32_e32 v16, 0xb0, v142
	v_ashrrev_i32_e32 v17, 31, v16
	v_lshlrev_b64 v[18:19], 12, v[16:17]
	v_lshl_add_u64 v[18:19], s[66:67], 0, v[18:19]
	v_lshl_add_u64 v[22:23], v[140:141], 2, v[18:19]
	s_nop 0
	v_lshlrev_b64 v[24:25], 11, v[16:17]
	v_lshl_add_u64 v[24:25], s[68:69], 0, v[24:25]
	v_lshl_add_u64 v[24:25], v[140:141], 1, v[24:25]
	s_waitcnt vmcnt(11)
	v_pk_add_f32 v[14:15], v[14:15], v[214:215]
	v_pk_add_f32 v[12:13], v[12:13], v[212:213]
	v_cvt_pk_bf16_f32 v19, v14, v15
	v_cvt_pk_bf16_f32 v18, v12, v13
	global_store_dwordx4 v[22:23], v[12:15], off
	global_store_dwordx2 v[24:25], v[18:19], off
	s_nop 0
	v_mul_f32_e32 v13, v13, v13
	v_fmac_f32_e32 v13, v12, v12
	v_fmac_f32_e32 v13, v14, v14
	v_fmac_f32_e32 v13, v15, v15
	s_waitcnt vmcnt(12)
	v_pk_add_f32 v[10:11], v[10:11], v[218:219]
	v_pk_add_f32 v[8:9], v[8:9], v[216:217]
	v_cvt_pk_bf16_f32 v19, v10, v11
	v_cvt_pk_bf16_f32 v18, v8, v9
	global_store_dwordx4 v[22:23], v[8:11], off offset:64
	global_store_dwordx2 v[24:25], v[18:19], off offset:32
	s_nop 0
	v_mul_f32_e32 v9, v9, v9
	v_fmac_f32_e32 v9, v8, v8
	v_fmac_f32_e32 v9, v10, v10
	v_fmac_f32_e32 v9, v11, v11
	v_add_f32_e32 v8, v13, v9
	s_waitcnt vmcnt(13)
	v_pk_add_f32 v[6:7], v[6:7], v[222:223]
	v_pk_add_f32 v[4:5], v[4:5], v[220:221]
	v_cvt_pk_bf16_f32 v19, v6, v7
	v_cvt_pk_bf16_f32 v18, v4, v5
	global_store_dwordx4 v[22:23], v[4:7], off offset:512
	global_store_dwordx2 v[24:25], v[18:19], off offset:256
	s_nop 0
	v_mul_f32_e32 v5, v5, v5
	v_fmac_f32_e32 v5, v4, v4
	v_fmac_f32_e32 v5, v6, v6
	v_fmac_f32_e32 v5, v7, v7
	v_add_f32_e32 v6, v8, v5
	s_waitcnt vmcnt(14)
	v_pk_add_f32 v[2:3], v[2:3], v[226:227]
	v_pk_add_f32 v[0:1], v[0:1], v[224:225]
	global_store_dwordx4 v[22:23], v[0:3], off offset:576
	v_cvt_pk_bf16_f32 v4, v0, v1
	v_cvt_pk_bf16_f32 v5, v2, v3
	v_mul_f32_e32 v1, v1, v1
	v_fmac_f32_e32 v1, v0, v0
	v_fmac_f32_e32 v1, v2, v2
	v_fmac_f32_e32 v1, v3, v3
	v_add_f32_e32 v0, v6, v1
	v_mov_b32_e32 v1, v0
	s_nop 1
	v_permlane16_swap_b32_e32 v0, v1
	v_add_f32_e32 v0, v0, v1
	v_mov_b32_e32 v1, v0
	s_nop 1
	v_permlane32_swap_b32_e32 v0, v1
	global_store_dwordx2 v[24:25], v[4:5], off offset:288
	s_and_saveexec_b64 s[24:25], s[6:7]
	s_cbranch_execz .LBB0_1369
	v_lshl_add_u64 v[2:3], v[16:17], 2, s[10:11]
	v_add_f32_e32 v0, v0, v1
	global_atomic_add_f32 v[2:3], v0, off
	s_branch .LBB0_1369
